# rowwise P3/P9/P12 loops hand-rewritten: 4-row batches with all loads in flight, gains preloaded, v_cvt_pk_bf16
# speedup vs baseline: 1.0173x; 1.0173x over previous
.LBB0_286:
	s_cmp_lt_i32 s90, 4
	s_cselect_b64 s[0:1], -1, 0
	s_cmp_gt_i32 s91, 3
	s_cselect_b64 s[2:3], -1, 0
	s_and_b64 s[0:1], s[0:1], s[2:3]
	s_andn2_b64 vcc, exec, s[0:1]
	s_cbranch_vccnz .LBB0_382
	s_lshl_b32 s0, s82, 3
	s_add_i32 s0, s0, s83
	s_cmpk_gt_i32 s0, 0x41ff
	v_mbcnt_lo_u32_b32 v82, -1, 0
	v_mbcnt_hi_u32_b32 v82, -1, v82
	s_cbranch_scc1 .LBB0_327
	s_waitcnt lgkmcnt(0)
	s_mov_b32 s4, s0
	v_mbcnt_lo_u32_b32 v1, -1, 0
	v_mbcnt_hi_u32_b32 v1, -1, v1
	v_lshlrev_b32_e32 v19, 4, v1
	v_lshlrev_b32_e32 v1, 3, v1
	s_add_u32 s14, s66, 0x1000
	s_addc_u32 s15, s67, 0
	global_load_dwordx4 v[2:5], v19, s[14:15] offset:0
	global_load_dwordx4 v[6:9], v19, s[14:15] offset:1024
	global_load_dwordx4 v[10:13], v19, s[14:15] offset:2048
	global_load_dwordx4 v[14:17], v19, s[14:15] offset:3072
	s_add_u32 s14, s66, 0x2000
	s_addc_u32 s15, s67, 0
	global_load_dwordx4 v[20:23], v19, s[14:15] offset:0
	global_load_dwordx4 v[24:27], v19, s[14:15] offset:1024
	global_load_dwordx4 v[28:31], v19, s[14:15] offset:2048
	global_load_dwordx4 v[32:35], v19, s[14:15] offset:3072
	s_mov_b32 s34, 0xffff0000
	s_mov_b32 s35, 0xf800000
	v_mov_b32_e32 v69, 0x358637bd
	v_mov_b32_e32 v80, 0x260
	s_lshl_b32 s23, s33, 3
	s_lshl_b32 s20, s33, 14
	s_lshl_b32 s21, s33, 15
	s_mul_i32 s22, s23, 3
	s_sub_i32 s22, 0x4000, s22
	s_mov_b32 s5, s4
	s_lshl_b32 s36, s4, 11
	s_lshl_b32 s37, s4, 12
	s_add_u32 s6, s26, 0xae00000
	s_addc_u32 s7, s27, 0
	s_add_u32 s6, s6, s36
	s_addc_u32 s7, s7, 0
	s_add_u32 s8, s52, s37
	s_addc_u32 s9, s53, 0
	s_add_u32 s10, s26, 0xf000000
	s_addc_u32 s11, s27, 0
	s_add_u32 s10, s10, s36
	s_addc_u32 s11, s11, 0
	s_add_u32 s12, s26, 0x3000000
	s_addc_u32 s13, s27, 0
	s_add_u32 s12, s12, s36
	s_addc_u32 s13, s13, 0
.Lrw3_batch:
	s_cmp_lt_i32 s5, s22
	s_cbranch_scc0 .Lrw3_single
	global_load_dwordx2 v[84:85], v1, s[6:7] offset:0
	global_load_dwordx2 v[86:87], v1, s[6:7] offset:512
	global_load_dwordx2 v[88:89], v1, s[6:7] offset:1024
	global_load_dwordx2 v[90:91], v1, s[6:7] offset:1536
	global_load_dwordx4 v[92:95], v19, s[8:9] offset:0 nt
	global_load_dwordx4 v[96:99], v19, s[8:9] offset:1024 nt
	global_load_dwordx4 v[100:103], v19, s[8:9] offset:2048 nt
	global_load_dwordx4 v[104:107], v19, s[8:9] offset:3072 nt
	s_add_u32 s6, s6, s20
	s_addc_u32 s7, s7, 0
	s_add_u32 s8, s8, s21
	s_addc_u32 s9, s9, 0
	global_load_dwordx2 v[108:109], v1, s[6:7] offset:0
	global_load_dwordx2 v[110:111], v1, s[6:7] offset:512
	global_load_dwordx2 v[112:113], v1, s[6:7] offset:1024
	global_load_dwordx2 v[114:115], v1, s[6:7] offset:1536
	global_load_dwordx4 v[116:119], v19, s[8:9] offset:0 nt
	global_load_dwordx4 v[120:123], v19, s[8:9] offset:1024 nt
	global_load_dwordx4 v[124:127], v19, s[8:9] offset:2048 nt
	global_load_dwordx4 v[128:131], v19, s[8:9] offset:3072 nt
	s_add_u32 s6, s6, s20
	s_addc_u32 s7, s7, 0
	s_add_u32 s8, s8, s21
	s_addc_u32 s9, s9, 0
	global_load_dwordx2 v[132:133], v1, s[6:7] offset:0
	global_load_dwordx2 v[134:135], v1, s[6:7] offset:512
	global_load_dwordx2 v[136:137], v1, s[6:7] offset:1024
	global_load_dwordx2 v[138:139], v1, s[6:7] offset:1536
	global_load_dwordx4 v[140:143], v19, s[8:9] offset:0 nt
	global_load_dwordx4 v[144:147], v19, s[8:9] offset:1024 nt
	global_load_dwordx4 v[148:151], v19, s[8:9] offset:2048 nt
	global_load_dwordx4 v[152:155], v19, s[8:9] offset:3072 nt
	s_add_u32 s6, s6, s20
	s_addc_u32 s7, s7, 0
	s_add_u32 s8, s8, s21
	s_addc_u32 s9, s9, 0
	global_load_dwordx2 v[156:157], v1, s[6:7] offset:0
	global_load_dwordx2 v[158:159], v1, s[6:7] offset:512
	global_load_dwordx2 v[160:161], v1, s[6:7] offset:1024
	global_load_dwordx2 v[162:163], v1, s[6:7] offset:1536
	global_load_dwordx4 v[164:167], v19, s[8:9] offset:0 nt
	global_load_dwordx4 v[168:171], v19, s[8:9] offset:1024 nt
	global_load_dwordx4 v[172:175], v19, s[8:9] offset:2048 nt
	global_load_dwordx4 v[176:179], v19, s[8:9] offset:3072 nt
	s_add_u32 s6, s6, s20
	s_addc_u32 s7, s7, 0
	s_add_u32 s8, s8, s21
	s_addc_u32 s9, s9, 0
	s_waitcnt vmcnt(24)
	v_lshlrev_b32_e32 v36, 16, v84
	v_and_b32_e32 v37, s34, v84
	v_lshlrev_b32_e32 v38, 16, v85
	v_and_b32_e32 v39, s34, v85
	v_lshlrev_b32_e32 v40, 16, v86
	v_and_b32_e32 v41, s34, v86
	v_lshlrev_b32_e32 v42, 16, v87
	v_and_b32_e32 v43, s34, v87
	v_lshlrev_b32_e32 v44, 16, v88
	v_and_b32_e32 v45, s34, v88
	v_lshlrev_b32_e32 v46, 16, v89
	v_and_b32_e32 v47, s34, v89
	v_lshlrev_b32_e32 v48, 16, v90
	v_and_b32_e32 v49, s34, v90
	v_lshlrev_b32_e32 v50, 16, v91
	v_and_b32_e32 v51, s34, v91
	v_pk_mul_f32 v[70:71], v[36:37], v[36:37]
	v_pk_mul_f32 v[72:73], v[38:39], v[38:39]
	v_pk_fma_f32 v[70:71], v[40:41], v[40:41], v[70:71]
	v_pk_fma_f32 v[72:73], v[42:43], v[42:43], v[72:73]
	v_pk_fma_f32 v[70:71], v[44:45], v[44:45], v[70:71]
	v_pk_fma_f32 v[72:73], v[46:47], v[46:47], v[72:73]
	v_pk_fma_f32 v[70:71], v[48:49], v[48:49], v[70:71]
	v_pk_fma_f32 v[72:73], v[50:51], v[50:51], v[72:73]
	v_pk_add_f32 v[70:71], v[70:71], v[72:73]
	s_nop 0
	v_add_f32_e32 v70, v70, v71
	s_nop 1
	v_add_f32_dpp v70, v70, v70 quad_perm:[1,0,3,2] row_mask:0xf bank_mask:0xf bound_ctrl:1
	s_nop 1
	v_add_f32_dpp v70, v70, v70 quad_perm:[2,3,0,1] row_mask:0xf bank_mask:0xf bound_ctrl:1
	s_nop 1
	v_add_f32_dpp v70, v70, v70 row_half_mirror row_mask:0xf bank_mask:0xf bound_ctrl:1
	s_nop 1
	v_add_f32_dpp v70, v70, v70 row_mirror row_mask:0xf bank_mask:0xf bound_ctrl:1
	v_mov_b32_e32 v71, v70
	s_nop 1
	v_permlane16_swap_b32_e32 v70, v71
	v_add_f32_e32 v70, v70, v71
	v_mov_b32_e32 v71, v70
	s_nop 1
	v_permlane32_swap_b32_e32 v70, v71
	v_add_f32_e32 v70, v70, v71
	v_fmamk_f32 v70, v70, 0x3a800000, v69
	v_mul_f32_e32 v71, 0x4f800000, v70
	v_cmp_gt_f32_e32 vcc, s35, v70
	s_nop 1
	v_cndmask_b32_e32 v70, v70, v71, vcc
	v_sqrt_f32_e32 v71, v70
	s_nop 1
	v_add_u32_e32 v72, -1, v71
	v_add_u32_e32 v73, 1, v71
	v_fma_f32 v74, -v72, v71, v70
	v_fma_f32 v75, -v73, v71, v70
	v_cmp_ge_f32_e64 s[0:1], 0, v74
	s_nop 1
	v_cndmask_b32_e64 v71, v71, v72, s[0:1]
	v_cmp_lt_f32_e64 s[0:1], 0, v75
	s_nop 1
	v_cndmask_b32_e64 v71, v71, v73, s[0:1]
	v_mul_f32_e32 v72, 0x37800000, v71
	s_nop 0
	v_cndmask_b32_e32 v71, v71, v72, vcc
	v_cmp_class_f32_e32 vcc, v70, v80
	s_nop 1
	v_cndmask_b32_e32 v70, v71, v70, vcc
	v_div_scale_f32 v71, s[0:1], v70, v70, 0.5
	v_rcp_f32_e32 v72, v71
	v_div_scale_f32 v73, vcc, 0.5, v70, 0.5
	v_fma_f32 v74, -v71, v72, 1.0
	v_fmac_f32_e32 v72, v74, v72
	v_mul_f32_e32 v74, v73, v72
	v_fma_f32 v75, -v71, v74, v73
	v_fmac_f32_e32 v74, v75, v72
	v_fma_f32 v71, -v71, v74, v73
	v_div_fmas_f32 v71, v71, v72, v74
	v_div_fixup_f32 v76, v71, v70, 0.5
	v_pk_mul_f32 v[36:37], v[36:37], v[76:77] op_sel_hi:[1,0]
	v_pk_mul_f32 v[38:39], v[38:39], v[76:77] op_sel_hi:[1,0]
	v_pk_mul_f32 v[40:41], v[40:41], v[76:77] op_sel_hi:[1,0]
	v_pk_mul_f32 v[42:43], v[42:43], v[76:77] op_sel_hi:[1,0]
	v_pk_mul_f32 v[44:45], v[44:45], v[76:77] op_sel_hi:[1,0]
	v_pk_mul_f32 v[46:47], v[46:47], v[76:77] op_sel_hi:[1,0]
	v_pk_mul_f32 v[48:49], v[48:49], v[76:77] op_sel_hi:[1,0]
	v_pk_mul_f32 v[50:51], v[50:51], v[76:77] op_sel_hi:[1,0]
	v_pk_fma_f32 v[52:53], v[36:37], v[2:3], v[92:93]
	v_pk_fma_f32 v[54:55], v[38:39], v[4:5], v[94:95]
	v_pk_fma_f32 v[56:57], v[40:41], v[6:7], v[96:97]
	v_pk_fma_f32 v[58:59], v[42:43], v[8:9], v[98:99]
	v_pk_fma_f32 v[60:61], v[44:45], v[10:11], v[100:101]
	v_pk_fma_f32 v[62:63], v[46:47], v[12:13], v[102:103]
	v_pk_fma_f32 v[64:65], v[48:49], v[14:15], v[104:105]
	v_pk_fma_f32 v[66:67], v[50:51], v[16:17], v[106:107]
	v_cvt_pk_bf16_f32 v180, v52, v53
	v_cvt_pk_bf16_f32 v181, v54, v55
	v_cvt_pk_bf16_f32 v182, v56, v57
	v_cvt_pk_bf16_f32 v183, v58, v59
	v_cvt_pk_bf16_f32 v184, v60, v61
	v_cvt_pk_bf16_f32 v185, v62, v63
	v_cvt_pk_bf16_f32 v186, v64, v65
	v_cvt_pk_bf16_f32 v187, v66, v67
	global_store_dwordx2 v1, v[180:181], s[10:11] offset:0
	global_store_dwordx2 v1, v[182:183], s[10:11] offset:512
	global_store_dwordx2 v1, v[184:185], s[10:11] offset:1024
	global_store_dwordx2 v1, v[186:187], s[10:11] offset:1536
	v_lshlrev_b32_e32 v52, 16, v180
	v_and_b32_e32 v53, s34, v180
	v_lshlrev_b32_e32 v54, 16, v181
	v_and_b32_e32 v55, s34, v181
	v_lshlrev_b32_e32 v56, 16, v182
	v_and_b32_e32 v57, s34, v182
	v_lshlrev_b32_e32 v58, 16, v183
	v_and_b32_e32 v59, s34, v183
	v_lshlrev_b32_e32 v60, 16, v184
	v_and_b32_e32 v61, s34, v184
	v_lshlrev_b32_e32 v62, 16, v185
	v_and_b32_e32 v63, s34, v185
	v_lshlrev_b32_e32 v64, 16, v186
	v_and_b32_e32 v65, s34, v186
	v_lshlrev_b32_e32 v66, 16, v187
	v_and_b32_e32 v67, s34, v187
	v_pk_mul_f32 v[70:71], v[52:53], v[52:53]
	v_pk_mul_f32 v[72:73], v[54:55], v[54:55]
	v_pk_fma_f32 v[70:71], v[56:57], v[56:57], v[70:71]
	v_pk_fma_f32 v[72:73], v[58:59], v[58:59], v[72:73]
	v_pk_fma_f32 v[70:71], v[60:61], v[60:61], v[70:71]
	v_pk_fma_f32 v[72:73], v[62:63], v[62:63], v[72:73]
	v_pk_fma_f32 v[70:71], v[64:65], v[64:65], v[70:71]
	v_pk_fma_f32 v[72:73], v[66:67], v[66:67], v[72:73]
	v_pk_add_f32 v[70:71], v[70:71], v[72:73]
	s_nop 0
	v_add_f32_e32 v70, v70, v71
	s_nop 1
	v_add_f32_dpp v70, v70, v70 quad_perm:[1,0,3,2] row_mask:0xf bank_mask:0xf bound_ctrl:1
	s_nop 1
	v_add_f32_dpp v70, v70, v70 quad_perm:[2,3,0,1] row_mask:0xf bank_mask:0xf bound_ctrl:1
	s_nop 1
	v_add_f32_dpp v70, v70, v70 row_half_mirror row_mask:0xf bank_mask:0xf bound_ctrl:1
	s_nop 1
	v_add_f32_dpp v70, v70, v70 row_mirror row_mask:0xf bank_mask:0xf bound_ctrl:1
	v_mov_b32_e32 v71, v70
	s_nop 1
	v_permlane16_swap_b32_e32 v70, v71
	v_add_f32_e32 v70, v70, v71
	v_mov_b32_e32 v71, v70
	s_nop 1
	v_permlane32_swap_b32_e32 v70, v71
	v_add_f32_e32 v70, v70, v71
	v_fmamk_f32 v70, v70, 0x3a800000, v69
	v_mul_f32_e32 v71, 0x4f800000, v70
	v_cmp_gt_f32_e32 vcc, s35, v70
	s_nop 1
	v_cndmask_b32_e32 v70, v70, v71, vcc
	v_sqrt_f32_e32 v71, v70
	s_nop 1
	v_add_u32_e32 v72, -1, v71
	v_add_u32_e32 v73, 1, v71
	v_fma_f32 v74, -v72, v71, v70
	v_fma_f32 v75, -v73, v71, v70
	v_cmp_ge_f32_e64 s[0:1], 0, v74
	s_nop 1
	v_cndmask_b32_e64 v71, v71, v72, s[0:1]
	v_cmp_lt_f32_e64 s[0:1], 0, v75
	s_nop 1
	v_cndmask_b32_e64 v71, v71, v73, s[0:1]
	v_mul_f32_e32 v72, 0x37800000, v71
	s_nop 0
	v_cndmask_b32_e32 v71, v71, v72, vcc
	v_cmp_class_f32_e32 vcc, v70, v80
	s_nop 1
	v_cndmask_b32_e32 v70, v71, v70, vcc
	v_div_scale_f32 v71, s[0:1], v70, v70, 1.0
	v_rcp_f32_e32 v72, v71
	v_div_scale_f32 v73, vcc, 1.0, v70, 1.0
	v_fma_f32 v74, -v71, v72, 1.0
	v_fmac_f32_e32 v72, v74, v72
	v_mul_f32_e32 v74, v73, v72
	v_fma_f32 v75, -v71, v74, v73
	v_fmac_f32_e32 v74, v75, v72
	v_fma_f32 v71, -v71, v74, v73
	v_div_fmas_f32 v71, v71, v72, v74
	v_div_fixup_f32 v76, v71, v70, 1.0
	v_pk_mul_f32 v[52:53], v[52:53], v[76:77] op_sel_hi:[1,0]
	v_pk_mul_f32 v[54:55], v[54:55], v[76:77] op_sel_hi:[1,0]
	v_pk_mul_f32 v[56:57], v[56:57], v[76:77] op_sel_hi:[1,0]
	v_pk_mul_f32 v[58:59], v[58:59], v[76:77] op_sel_hi:[1,0]
	v_pk_mul_f32 v[60:61], v[60:61], v[76:77] op_sel_hi:[1,0]
	v_pk_mul_f32 v[62:63], v[62:63], v[76:77] op_sel_hi:[1,0]
	v_pk_mul_f32 v[64:65], v[64:65], v[76:77] op_sel_hi:[1,0]
	v_pk_mul_f32 v[66:67], v[66:67], v[76:77] op_sel_hi:[1,0]
	v_pk_mul_f32 v[52:53], v[52:53], v[20:21]
	v_pk_mul_f32 v[54:55], v[54:55], v[22:23]
	v_pk_mul_f32 v[56:57], v[56:57], v[24:25]
	v_pk_mul_f32 v[58:59], v[58:59], v[26:27]
	v_pk_mul_f32 v[60:61], v[60:61], v[28:29]
	v_pk_mul_f32 v[62:63], v[62:63], v[30:31]
	v_pk_mul_f32 v[64:65], v[64:65], v[32:33]
	v_pk_mul_f32 v[66:67], v[66:67], v[34:35]
	v_cvt_pk_bf16_f32 v180, v52, v53
	v_cvt_pk_bf16_f32 v181, v54, v55
	v_cvt_pk_bf16_f32 v182, v56, v57
	v_cvt_pk_bf16_f32 v183, v58, v59
	v_cvt_pk_bf16_f32 v184, v60, v61
	v_cvt_pk_bf16_f32 v185, v62, v63
	v_cvt_pk_bf16_f32 v186, v64, v65
	v_cvt_pk_bf16_f32 v187, v66, v67
	global_store_dwordx2 v1, v[180:181], s[12:13] offset:0
	global_store_dwordx2 v1, v[182:183], s[12:13] offset:512
	global_store_dwordx2 v1, v[184:185], s[12:13] offset:1024
	global_store_dwordx2 v1, v[186:187], s[12:13] offset:1536
	s_add_u32 s10, s10, s20
	s_addc_u32 s11, s11, 0
	s_add_u32 s12, s12, s20
	s_addc_u32 s13, s13, 0
	s_waitcnt vmcnt(24)
	v_lshlrev_b32_e32 v36, 16, v108
	v_and_b32_e32 v37, s34, v108
	v_lshlrev_b32_e32 v38, 16, v109
	v_and_b32_e32 v39, s34, v109
	v_lshlrev_b32_e32 v40, 16, v110
	v_and_b32_e32 v41, s34, v110
	v_lshlrev_b32_e32 v42, 16, v111
	v_and_b32_e32 v43, s34, v111
	v_lshlrev_b32_e32 v44, 16, v112
	v_and_b32_e32 v45, s34, v112
	v_lshlrev_b32_e32 v46, 16, v113
	v_and_b32_e32 v47, s34, v113
	v_lshlrev_b32_e32 v48, 16, v114
	v_and_b32_e32 v49, s34, v114
	v_lshlrev_b32_e32 v50, 16, v115
	v_and_b32_e32 v51, s34, v115
	v_pk_mul_f32 v[70:71], v[36:37], v[36:37]
	v_pk_mul_f32 v[72:73], v[38:39], v[38:39]
	v_pk_fma_f32 v[70:71], v[40:41], v[40:41], v[70:71]
	v_pk_fma_f32 v[72:73], v[42:43], v[42:43], v[72:73]
	v_pk_fma_f32 v[70:71], v[44:45], v[44:45], v[70:71]
	v_pk_fma_f32 v[72:73], v[46:47], v[46:47], v[72:73]
	v_pk_fma_f32 v[70:71], v[48:49], v[48:49], v[70:71]
	v_pk_fma_f32 v[72:73], v[50:51], v[50:51], v[72:73]
	v_pk_add_f32 v[70:71], v[70:71], v[72:73]
	s_nop 0
	v_add_f32_e32 v70, v70, v71
	s_nop 1
	v_add_f32_dpp v70, v70, v70 quad_perm:[1,0,3,2] row_mask:0xf bank_mask:0xf bound_ctrl:1
	s_nop 1
	v_add_f32_dpp v70, v70, v70 quad_perm:[2,3,0,1] row_mask:0xf bank_mask:0xf bound_ctrl:1
	s_nop 1
	v_add_f32_dpp v70, v70, v70 row_half_mirror row_mask:0xf bank_mask:0xf bound_ctrl:1
	s_nop 1
	v_add_f32_dpp v70, v70, v70 row_mirror row_mask:0xf bank_mask:0xf bound_ctrl:1
	v_mov_b32_e32 v71, v70
	s_nop 1
	v_permlane16_swap_b32_e32 v70, v71
	v_add_f32_e32 v70, v70, v71
	v_mov_b32_e32 v71, v70
	s_nop 1
	v_permlane32_swap_b32_e32 v70, v71
	v_add_f32_e32 v70, v70, v71
	v_fmamk_f32 v70, v70, 0x3a800000, v69
	v_mul_f32_e32 v71, 0x4f800000, v70
	v_cmp_gt_f32_e32 vcc, s35, v70
	s_nop 1
	v_cndmask_b32_e32 v70, v70, v71, vcc
	v_sqrt_f32_e32 v71, v70
	s_nop 1
	v_add_u32_e32 v72, -1, v71
	v_add_u32_e32 v73, 1, v71
	v_fma_f32 v74, -v72, v71, v70
	v_fma_f32 v75, -v73, v71, v70
	v_cmp_ge_f32_e64 s[0:1], 0, v74
	s_nop 1
	v_cndmask_b32_e64 v71, v71, v72, s[0:1]
	v_cmp_lt_f32_e64 s[0:1], 0, v75
	s_nop 1
	v_cndmask_b32_e64 v71, v71, v73, s[0:1]
	v_mul_f32_e32 v72, 0x37800000, v71
	s_nop 0
	v_cndmask_b32_e32 v71, v71, v72, vcc
	v_cmp_class_f32_e32 vcc, v70, v80
	s_nop 1
	v_cndmask_b32_e32 v70, v71, v70, vcc
	v_div_scale_f32 v71, s[0:1], v70, v70, 0.5
	v_rcp_f32_e32 v72, v71
	v_div_scale_f32 v73, vcc, 0.5, v70, 0.5
	v_fma_f32 v74, -v71, v72, 1.0
	v_fmac_f32_e32 v72, v74, v72
	v_mul_f32_e32 v74, v73, v72
	v_fma_f32 v75, -v71, v74, v73
	v_fmac_f32_e32 v74, v75, v72
	v_fma_f32 v71, -v71, v74, v73
	v_div_fmas_f32 v71, v71, v72, v74
	v_div_fixup_f32 v76, v71, v70, 0.5
	v_pk_mul_f32 v[36:37], v[36:37], v[76:77] op_sel_hi:[1,0]
	v_pk_mul_f32 v[38:39], v[38:39], v[76:77] op_sel_hi:[1,0]
	v_pk_mul_f32 v[40:41], v[40:41], v[76:77] op_sel_hi:[1,0]
	v_pk_mul_f32 v[42:43], v[42:43], v[76:77] op_sel_hi:[1,0]
	v_pk_mul_f32 v[44:45], v[44:45], v[76:77] op_sel_hi:[1,0]
	v_pk_mul_f32 v[46:47], v[46:47], v[76:77] op_sel_hi:[1,0]
	v_pk_mul_f32 v[48:49], v[48:49], v[76:77] op_sel_hi:[1,0]
	v_pk_mul_f32 v[50:51], v[50:51], v[76:77] op_sel_hi:[1,0]
	v_pk_fma_f32 v[52:53], v[36:37], v[2:3], v[116:117]
	v_pk_fma_f32 v[54:55], v[38:39], v[4:5], v[118:119]
	v_pk_fma_f32 v[56:57], v[40:41], v[6:7], v[120:121]
	v_pk_fma_f32 v[58:59], v[42:43], v[8:9], v[122:123]
	v_pk_fma_f32 v[60:61], v[44:45], v[10:11], v[124:125]
	v_pk_fma_f32 v[62:63], v[46:47], v[12:13], v[126:127]
	v_pk_fma_f32 v[64:65], v[48:49], v[14:15], v[128:129]
	v_pk_fma_f32 v[66:67], v[50:51], v[16:17], v[130:131]
	v_cvt_pk_bf16_f32 v180, v52, v53
	v_cvt_pk_bf16_f32 v181, v54, v55
	v_cvt_pk_bf16_f32 v182, v56, v57
	v_cvt_pk_bf16_f32 v183, v58, v59
	v_cvt_pk_bf16_f32 v184, v60, v61
	v_cvt_pk_bf16_f32 v185, v62, v63
	v_cvt_pk_bf16_f32 v186, v64, v65
	v_cvt_pk_bf16_f32 v187, v66, v67
	global_store_dwordx2 v1, v[180:181], s[10:11] offset:0
	global_store_dwordx2 v1, v[182:183], s[10:11] offset:512
	global_store_dwordx2 v1, v[184:185], s[10:11] offset:1024
	global_store_dwordx2 v1, v[186:187], s[10:11] offset:1536
	v_lshlrev_b32_e32 v52, 16, v180
	v_and_b32_e32 v53, s34, v180
	v_lshlrev_b32_e32 v54, 16, v181
	v_and_b32_e32 v55, s34, v181
	v_lshlrev_b32_e32 v56, 16, v182
	v_and_b32_e32 v57, s34, v182
	v_lshlrev_b32_e32 v58, 16, v183
	v_and_b32_e32 v59, s34, v183
	v_lshlrev_b32_e32 v60, 16, v184
	v_and_b32_e32 v61, s34, v184
	v_lshlrev_b32_e32 v62, 16, v185
	v_and_b32_e32 v63, s34, v185
	v_lshlrev_b32_e32 v64, 16, v186
	v_and_b32_e32 v65, s34, v186
	v_lshlrev_b32_e32 v66, 16, v187
	v_and_b32_e32 v67, s34, v187
	v_pk_mul_f32 v[70:71], v[52:53], v[52:53]
	v_pk_mul_f32 v[72:73], v[54:55], v[54:55]
	v_pk_fma_f32 v[70:71], v[56:57], v[56:57], v[70:71]
	v_pk_fma_f32 v[72:73], v[58:59], v[58:59], v[72:73]
	v_pk_fma_f32 v[70:71], v[60:61], v[60:61], v[70:71]
	v_pk_fma_f32 v[72:73], v[62:63], v[62:63], v[72:73]
	v_pk_fma_f32 v[70:71], v[64:65], v[64:65], v[70:71]
	v_pk_fma_f32 v[72:73], v[66:67], v[66:67], v[72:73]
	v_pk_add_f32 v[70:71], v[70:71], v[72:73]
	s_nop 0
	v_add_f32_e32 v70, v70, v71
	s_nop 1
	v_add_f32_dpp v70, v70, v70 quad_perm:[1,0,3,2] row_mask:0xf bank_mask:0xf bound_ctrl:1
	s_nop 1
	v_add_f32_dpp v70, v70, v70 quad_perm:[2,3,0,1] row_mask:0xf bank_mask:0xf bound_ctrl:1
	s_nop 1
	v_add_f32_dpp v70, v70, v70 row_half_mirror row_mask:0xf bank_mask:0xf bound_ctrl:1
	s_nop 1
	v_add_f32_dpp v70, v70, v70 row_mirror row_mask:0xf bank_mask:0xf bound_ctrl:1
	v_mov_b32_e32 v71, v70
	s_nop 1
	v_permlane16_swap_b32_e32 v70, v71
	v_add_f32_e32 v70, v70, v71
	v_mov_b32_e32 v71, v70
	s_nop 1
	v_permlane32_swap_b32_e32 v70, v71
	v_add_f32_e32 v70, v70, v71
	v_fmamk_f32 v70, v70, 0x3a800000, v69
	v_mul_f32_e32 v71, 0x4f800000, v70
	v_cmp_gt_f32_e32 vcc, s35, v70
	s_nop 1
	v_cndmask_b32_e32 v70, v70, v71, vcc
	v_sqrt_f32_e32 v71, v70
	s_nop 1
	v_add_u32_e32 v72, -1, v71
	v_add_u32_e32 v73, 1, v71
	v_fma_f32 v74, -v72, v71, v70
	v_fma_f32 v75, -v73, v71, v70
	v_cmp_ge_f32_e64 s[0:1], 0, v74
	s_nop 1
	v_cndmask_b32_e64 v71, v71, v72, s[0:1]
	v_cmp_lt_f32_e64 s[0:1], 0, v75
	s_nop 1
	v_cndmask_b32_e64 v71, v71, v73, s[0:1]
	v_mul_f32_e32 v72, 0x37800000, v71
	s_nop 0
	v_cndmask_b32_e32 v71, v71, v72, vcc
	v_cmp_class_f32_e32 vcc, v70, v80
	s_nop 1
	v_cndmask_b32_e32 v70, v71, v70, vcc
	v_div_scale_f32 v71, s[0:1], v70, v70, 1.0
	v_rcp_f32_e32 v72, v71
	v_div_scale_f32 v73, vcc, 1.0, v70, 1.0
	v_fma_f32 v74, -v71, v72, 1.0
	v_fmac_f32_e32 v72, v74, v72
	v_mul_f32_e32 v74, v73, v72
	v_fma_f32 v75, -v71, v74, v73
	v_fmac_f32_e32 v74, v75, v72
	v_fma_f32 v71, -v71, v74, v73
	v_div_fmas_f32 v71, v71, v72, v74
	v_div_fixup_f32 v76, v71, v70, 1.0
	v_pk_mul_f32 v[52:53], v[52:53], v[76:77] op_sel_hi:[1,0]
	v_pk_mul_f32 v[54:55], v[54:55], v[76:77] op_sel_hi:[1,0]
	v_pk_mul_f32 v[56:57], v[56:57], v[76:77] op_sel_hi:[1,0]
	v_pk_mul_f32 v[58:59], v[58:59], v[76:77] op_sel_hi:[1,0]
	v_pk_mul_f32 v[60:61], v[60:61], v[76:77] op_sel_hi:[1,0]
	v_pk_mul_f32 v[62:63], v[62:63], v[76:77] op_sel_hi:[1,0]
	v_pk_mul_f32 v[64:65], v[64:65], v[76:77] op_sel_hi:[1,0]
	v_pk_mul_f32 v[66:67], v[66:67], v[76:77] op_sel_hi:[1,0]
	v_pk_mul_f32 v[52:53], v[52:53], v[20:21]
	v_pk_mul_f32 v[54:55], v[54:55], v[22:23]
	v_pk_mul_f32 v[56:57], v[56:57], v[24:25]
	v_pk_mul_f32 v[58:59], v[58:59], v[26:27]
	v_pk_mul_f32 v[60:61], v[60:61], v[28:29]
	v_pk_mul_f32 v[62:63], v[62:63], v[30:31]
	v_pk_mul_f32 v[64:65], v[64:65], v[32:33]
	v_pk_mul_f32 v[66:67], v[66:67], v[34:35]
	v_cvt_pk_bf16_f32 v180, v52, v53
	v_cvt_pk_bf16_f32 v181, v54, v55
	v_cvt_pk_bf16_f32 v182, v56, v57
	v_cvt_pk_bf16_f32 v183, v58, v59
	v_cvt_pk_bf16_f32 v184, v60, v61
	v_cvt_pk_bf16_f32 v185, v62, v63
	v_cvt_pk_bf16_f32 v186, v64, v65
	v_cvt_pk_bf16_f32 v187, v66, v67
	global_store_dwordx2 v1, v[180:181], s[12:13] offset:0
	global_store_dwordx2 v1, v[182:183], s[12:13] offset:512
	global_store_dwordx2 v1, v[184:185], s[12:13] offset:1024
	global_store_dwordx2 v1, v[186:187], s[12:13] offset:1536
	s_add_u32 s10, s10, s20
	s_addc_u32 s11, s11, 0
	s_add_u32 s12, s12, s20
	s_addc_u32 s13, s13, 0
	s_waitcnt vmcnt(24)
	v_lshlrev_b32_e32 v36, 16, v132
	v_and_b32_e32 v37, s34, v132
	v_lshlrev_b32_e32 v38, 16, v133
	v_and_b32_e32 v39, s34, v133
	v_lshlrev_b32_e32 v40, 16, v134
	v_and_b32_e32 v41, s34, v134
	v_lshlrev_b32_e32 v42, 16, v135
	v_and_b32_e32 v43, s34, v135
	v_lshlrev_b32_e32 v44, 16, v136
	v_and_b32_e32 v45, s34, v136
	v_lshlrev_b32_e32 v46, 16, v137
	v_and_b32_e32 v47, s34, v137
	v_lshlrev_b32_e32 v48, 16, v138
	v_and_b32_e32 v49, s34, v138
	v_lshlrev_b32_e32 v50, 16, v139
	v_and_b32_e32 v51, s34, v139
	v_pk_mul_f32 v[70:71], v[36:37], v[36:37]
	v_pk_mul_f32 v[72:73], v[38:39], v[38:39]
	v_pk_fma_f32 v[70:71], v[40:41], v[40:41], v[70:71]
	v_pk_fma_f32 v[72:73], v[42:43], v[42:43], v[72:73]
	v_pk_fma_f32 v[70:71], v[44:45], v[44:45], v[70:71]
	v_pk_fma_f32 v[72:73], v[46:47], v[46:47], v[72:73]
	v_pk_fma_f32 v[70:71], v[48:49], v[48:49], v[70:71]
	v_pk_fma_f32 v[72:73], v[50:51], v[50:51], v[72:73]
	v_pk_add_f32 v[70:71], v[70:71], v[72:73]
	s_nop 0
	v_add_f32_e32 v70, v70, v71
	s_nop 1
	v_add_f32_dpp v70, v70, v70 quad_perm:[1,0,3,2] row_mask:0xf bank_mask:0xf bound_ctrl:1
	s_nop 1
	v_add_f32_dpp v70, v70, v70 quad_perm:[2,3,0,1] row_mask:0xf bank_mask:0xf bound_ctrl:1
	s_nop 1
	v_add_f32_dpp v70, v70, v70 row_half_mirror row_mask:0xf bank_mask:0xf bound_ctrl:1
	s_nop 1
	v_add_f32_dpp v70, v70, v70 row_mirror row_mask:0xf bank_mask:0xf bound_ctrl:1
	v_mov_b32_e32 v71, v70
	s_nop 1
	v_permlane16_swap_b32_e32 v70, v71
	v_add_f32_e32 v70, v70, v71
	v_mov_b32_e32 v71, v70
	s_nop 1
	v_permlane32_swap_b32_e32 v70, v71
	v_add_f32_e32 v70, v70, v71
	v_fmamk_f32 v70, v70, 0x3a800000, v69
	v_mul_f32_e32 v71, 0x4f800000, v70
	v_cmp_gt_f32_e32 vcc, s35, v70
	s_nop 1
	v_cndmask_b32_e32 v70, v70, v71, vcc
	v_sqrt_f32_e32 v71, v70
	s_nop 1
	v_add_u32_e32 v72, -1, v71
	v_add_u32_e32 v73, 1, v71
	v_fma_f32 v74, -v72, v71, v70
	v_fma_f32 v75, -v73, v71, v70
	v_cmp_ge_f32_e64 s[0:1], 0, v74
	s_nop 1
	v_cndmask_b32_e64 v71, v71, v72, s[0:1]
	v_cmp_lt_f32_e64 s[0:1], 0, v75
	s_nop 1
	v_cndmask_b32_e64 v71, v71, v73, s[0:1]
	v_mul_f32_e32 v72, 0x37800000, v71
	s_nop 0
	v_cndmask_b32_e32 v71, v71, v72, vcc
	v_cmp_class_f32_e32 vcc, v70, v80
	s_nop 1
	v_cndmask_b32_e32 v70, v71, v70, vcc
	v_div_scale_f32 v71, s[0:1], v70, v70, 0.5
	v_rcp_f32_e32 v72, v71
	v_div_scale_f32 v73, vcc, 0.5, v70, 0.5
	v_fma_f32 v74, -v71, v72, 1.0
	v_fmac_f32_e32 v72, v74, v72
	v_mul_f32_e32 v74, v73, v72
	v_fma_f32 v75, -v71, v74, v73
	v_fmac_f32_e32 v74, v75, v72
	v_fma_f32 v71, -v71, v74, v73
	v_div_fmas_f32 v71, v71, v72, v74
	v_div_fixup_f32 v76, v71, v70, 0.5
	v_pk_mul_f32 v[36:37], v[36:37], v[76:77] op_sel_hi:[1,0]
	v_pk_mul_f32 v[38:39], v[38:39], v[76:77] op_sel_hi:[1,0]
	v_pk_mul_f32 v[40:41], v[40:41], v[76:77] op_sel_hi:[1,0]
	v_pk_mul_f32 v[42:43], v[42:43], v[76:77] op_sel_hi:[1,0]
	v_pk_mul_f32 v[44:45], v[44:45], v[76:77] op_sel_hi:[1,0]
	v_pk_mul_f32 v[46:47], v[46:47], v[76:77] op_sel_hi:[1,0]
	v_pk_mul_f32 v[48:49], v[48:49], v[76:77] op_sel_hi:[1,0]
	v_pk_mul_f32 v[50:51], v[50:51], v[76:77] op_sel_hi:[1,0]
	v_pk_fma_f32 v[52:53], v[36:37], v[2:3], v[140:141]
	v_pk_fma_f32 v[54:55], v[38:39], v[4:5], v[142:143]
	v_pk_fma_f32 v[56:57], v[40:41], v[6:7], v[144:145]
	v_pk_fma_f32 v[58:59], v[42:43], v[8:9], v[146:147]
	v_pk_fma_f32 v[60:61], v[44:45], v[10:11], v[148:149]
	v_pk_fma_f32 v[62:63], v[46:47], v[12:13], v[150:151]
	v_pk_fma_f32 v[64:65], v[48:49], v[14:15], v[152:153]
	v_pk_fma_f32 v[66:67], v[50:51], v[16:17], v[154:155]
	v_cvt_pk_bf16_f32 v180, v52, v53
	v_cvt_pk_bf16_f32 v181, v54, v55
	v_cvt_pk_bf16_f32 v182, v56, v57
	v_cvt_pk_bf16_f32 v183, v58, v59
	v_cvt_pk_bf16_f32 v184, v60, v61
	v_cvt_pk_bf16_f32 v185, v62, v63
	v_cvt_pk_bf16_f32 v186, v64, v65
	v_cvt_pk_bf16_f32 v187, v66, v67
	global_store_dwordx2 v1, v[180:181], s[10:11] offset:0
	global_store_dwordx2 v1, v[182:183], s[10:11] offset:512
	global_store_dwordx2 v1, v[184:185], s[10:11] offset:1024
	global_store_dwordx2 v1, v[186:187], s[10:11] offset:1536
	v_lshlrev_b32_e32 v52, 16, v180
	v_and_b32_e32 v53, s34, v180
	v_lshlrev_b32_e32 v54, 16, v181
	v_and_b32_e32 v55, s34, v181
	v_lshlrev_b32_e32 v56, 16, v182
	v_and_b32_e32 v57, s34, v182
	v_lshlrev_b32_e32 v58, 16, v183
	v_and_b32_e32 v59, s34, v183
	v_lshlrev_b32_e32 v60, 16, v184
	v_and_b32_e32 v61, s34, v184
	v_lshlrev_b32_e32 v62, 16, v185
	v_and_b32_e32 v63, s34, v185
	v_lshlrev_b32_e32 v64, 16, v186
	v_and_b32_e32 v65, s34, v186
	v_lshlrev_b32_e32 v66, 16, v187
	v_and_b32_e32 v67, s34, v187
	v_pk_mul_f32 v[70:71], v[52:53], v[52:53]
	v_pk_mul_f32 v[72:73], v[54:55], v[54:55]
	v_pk_fma_f32 v[70:71], v[56:57], v[56:57], v[70:71]
	v_pk_fma_f32 v[72:73], v[58:59], v[58:59], v[72:73]
	v_pk_fma_f32 v[70:71], v[60:61], v[60:61], v[70:71]
	v_pk_fma_f32 v[72:73], v[62:63], v[62:63], v[72:73]
	v_pk_fma_f32 v[70:71], v[64:65], v[64:65], v[70:71]
	v_pk_fma_f32 v[72:73], v[66:67], v[66:67], v[72:73]
	v_pk_add_f32 v[70:71], v[70:71], v[72:73]
	s_nop 0
	v_add_f32_e32 v70, v70, v71
	s_nop 1
	v_add_f32_dpp v70, v70, v70 quad_perm:[1,0,3,2] row_mask:0xf bank_mask:0xf bound_ctrl:1
	s_nop 1
	v_add_f32_dpp v70, v70, v70 quad_perm:[2,3,0,1] row_mask:0xf bank_mask:0xf bound_ctrl:1
	s_nop 1
	v_add_f32_dpp v70, v70, v70 row_half_mirror row_mask:0xf bank_mask:0xf bound_ctrl:1
	s_nop 1
	v_add_f32_dpp v70, v70, v70 row_mirror row_mask:0xf bank_mask:0xf bound_ctrl:1
	v_mov_b32_e32 v71, v70
	s_nop 1
	v_permlane16_swap_b32_e32 v70, v71
	v_add_f32_e32 v70, v70, v71
	v_mov_b32_e32 v71, v70
	s_nop 1
	v_permlane32_swap_b32_e32 v70, v71
	v_add_f32_e32 v70, v70, v71
	v_fmamk_f32 v70, v70, 0x3a800000, v69
	v_mul_f32_e32 v71, 0x4f800000, v70
	v_cmp_gt_f32_e32 vcc, s35, v70
	s_nop 1
	v_cndmask_b32_e32 v70, v70, v71, vcc
	v_sqrt_f32_e32 v71, v70
	s_nop 1
	v_add_u32_e32 v72, -1, v71
	v_add_u32_e32 v73, 1, v71
	v_fma_f32 v74, -v72, v71, v70
	v_fma_f32 v75, -v73, v71, v70
	v_cmp_ge_f32_e64 s[0:1], 0, v74
	s_nop 1
	v_cndmask_b32_e64 v71, v71, v72, s[0:1]
	v_cmp_lt_f32_e64 s[0:1], 0, v75
	s_nop 1
	v_cndmask_b32_e64 v71, v71, v73, s[0:1]
	v_mul_f32_e32 v72, 0x37800000, v71
	s_nop 0
	v_cndmask_b32_e32 v71, v71, v72, vcc
	v_cmp_class_f32_e32 vcc, v70, v80
	s_nop 1
	v_cndmask_b32_e32 v70, v71, v70, vcc
	v_div_scale_f32 v71, s[0:1], v70, v70, 1.0
	v_rcp_f32_e32 v72, v71
	v_div_scale_f32 v73, vcc, 1.0, v70, 1.0
	v_fma_f32 v74, -v71, v72, 1.0
	v_fmac_f32_e32 v72, v74, v72
	v_mul_f32_e32 v74, v73, v72
	v_fma_f32 v75, -v71, v74, v73
	v_fmac_f32_e32 v74, v75, v72
	v_fma_f32 v71, -v71, v74, v73
	v_div_fmas_f32 v71, v71, v72, v74
	v_div_fixup_f32 v76, v71, v70, 1.0
	v_pk_mul_f32 v[52:53], v[52:53], v[76:77] op_sel_hi:[1,0]
	v_pk_mul_f32 v[54:55], v[54:55], v[76:77] op_sel_hi:[1,0]
	v_pk_mul_f32 v[56:57], v[56:57], v[76:77] op_sel_hi:[1,0]
	v_pk_mul_f32 v[58:59], v[58:59], v[76:77] op_sel_hi:[1,0]
	v_pk_mul_f32 v[60:61], v[60:61], v[76:77] op_sel_hi:[1,0]
	v_pk_mul_f32 v[62:63], v[62:63], v[76:77] op_sel_hi:[1,0]
	v_pk_mul_f32 v[64:65], v[64:65], v[76:77] op_sel_hi:[1,0]
	v_pk_mul_f32 v[66:67], v[66:67], v[76:77] op_sel_hi:[1,0]
	v_pk_mul_f32 v[52:53], v[52:53], v[20:21]
	v_pk_mul_f32 v[54:55], v[54:55], v[22:23]
	v_pk_mul_f32 v[56:57], v[56:57], v[24:25]
	v_pk_mul_f32 v[58:59], v[58:59], v[26:27]
	v_pk_mul_f32 v[60:61], v[60:61], v[28:29]
	v_pk_mul_f32 v[62:63], v[62:63], v[30:31]
	v_pk_mul_f32 v[64:65], v[64:65], v[32:33]
	v_pk_mul_f32 v[66:67], v[66:67], v[34:35]
	v_cvt_pk_bf16_f32 v180, v52, v53
	v_cvt_pk_bf16_f32 v181, v54, v55
	v_cvt_pk_bf16_f32 v182, v56, v57
	v_cvt_pk_bf16_f32 v183, v58, v59
	v_cvt_pk_bf16_f32 v184, v60, v61
	v_cvt_pk_bf16_f32 v185, v62, v63
	v_cvt_pk_bf16_f32 v186, v64, v65
	v_cvt_pk_bf16_f32 v187, v66, v67
	global_store_dwordx2 v1, v[180:181], s[12:13] offset:0
	global_store_dwordx2 v1, v[182:183], s[12:13] offset:512
	global_store_dwordx2 v1, v[184:185], s[12:13] offset:1024
	global_store_dwordx2 v1, v[186:187], s[12:13] offset:1536
	s_add_u32 s10, s10, s20
	s_addc_u32 s11, s11, 0
	s_add_u32 s12, s12, s20
	s_addc_u32 s13, s13, 0
	s_waitcnt vmcnt(24)
	v_lshlrev_b32_e32 v36, 16, v156
	v_and_b32_e32 v37, s34, v156
	v_lshlrev_b32_e32 v38, 16, v157
	v_and_b32_e32 v39, s34, v157
	v_lshlrev_b32_e32 v40, 16, v158
	v_and_b32_e32 v41, s34, v158
	v_lshlrev_b32_e32 v42, 16, v159
	v_and_b32_e32 v43, s34, v159
	v_lshlrev_b32_e32 v44, 16, v160
	v_and_b32_e32 v45, s34, v160
	v_lshlrev_b32_e32 v46, 16, v161
	v_and_b32_e32 v47, s34, v161
	v_lshlrev_b32_e32 v48, 16, v162
	v_and_b32_e32 v49, s34, v162
	v_lshlrev_b32_e32 v50, 16, v163
	v_and_b32_e32 v51, s34, v163
	v_pk_mul_f32 v[70:71], v[36:37], v[36:37]
	v_pk_mul_f32 v[72:73], v[38:39], v[38:39]
	v_pk_fma_f32 v[70:71], v[40:41], v[40:41], v[70:71]
	v_pk_fma_f32 v[72:73], v[42:43], v[42:43], v[72:73]
	v_pk_fma_f32 v[70:71], v[44:45], v[44:45], v[70:71]
	v_pk_fma_f32 v[72:73], v[46:47], v[46:47], v[72:73]
	v_pk_fma_f32 v[70:71], v[48:49], v[48:49], v[70:71]
	v_pk_fma_f32 v[72:73], v[50:51], v[50:51], v[72:73]
	v_pk_add_f32 v[70:71], v[70:71], v[72:73]
	s_nop 0
	v_add_f32_e32 v70, v70, v71
	s_nop 1
	v_add_f32_dpp v70, v70, v70 quad_perm:[1,0,3,2] row_mask:0xf bank_mask:0xf bound_ctrl:1
	s_nop 1
	v_add_f32_dpp v70, v70, v70 quad_perm:[2,3,0,1] row_mask:0xf bank_mask:0xf bound_ctrl:1
	s_nop 1
	v_add_f32_dpp v70, v70, v70 row_half_mirror row_mask:0xf bank_mask:0xf bound_ctrl:1
	s_nop 1
	v_add_f32_dpp v70, v70, v70 row_mirror row_mask:0xf bank_mask:0xf bound_ctrl:1
	v_mov_b32_e32 v71, v70
	s_nop 1
	v_permlane16_swap_b32_e32 v70, v71
	v_add_f32_e32 v70, v70, v71
	v_mov_b32_e32 v71, v70
	s_nop 1
	v_permlane32_swap_b32_e32 v70, v71
	v_add_f32_e32 v70, v70, v71
	v_fmamk_f32 v70, v70, 0x3a800000, v69
	v_mul_f32_e32 v71, 0x4f800000, v70
	v_cmp_gt_f32_e32 vcc, s35, v70
	s_nop 1
	v_cndmask_b32_e32 v70, v70, v71, vcc
	v_sqrt_f32_e32 v71, v70
	s_nop 1
	v_add_u32_e32 v72, -1, v71
	v_add_u32_e32 v73, 1, v71
	v_fma_f32 v74, -v72, v71, v70
	v_fma_f32 v75, -v73, v71, v70
	v_cmp_ge_f32_e64 s[0:1], 0, v74
	s_nop 1
	v_cndmask_b32_e64 v71, v71, v72, s[0:1]
	v_cmp_lt_f32_e64 s[0:1], 0, v75
	s_nop 1
	v_cndmask_b32_e64 v71, v71, v73, s[0:1]
	v_mul_f32_e32 v72, 0x37800000, v71
	s_nop 0
	v_cndmask_b32_e32 v71, v71, v72, vcc
	v_cmp_class_f32_e32 vcc, v70, v80
	s_nop 1
	v_cndmask_b32_e32 v70, v71, v70, vcc
	v_div_scale_f32 v71, s[0:1], v70, v70, 0.5
	v_rcp_f32_e32 v72, v71
	v_div_scale_f32 v73, vcc, 0.5, v70, 0.5
	v_fma_f32 v74, -v71, v72, 1.0
	v_fmac_f32_e32 v72, v74, v72
	v_mul_f32_e32 v74, v73, v72
	v_fma_f32 v75, -v71, v74, v73
	v_fmac_f32_e32 v74, v75, v72
	v_fma_f32 v71, -v71, v74, v73
	v_div_fmas_f32 v71, v71, v72, v74
	v_div_fixup_f32 v76, v71, v70, 0.5
	v_pk_mul_f32 v[36:37], v[36:37], v[76:77] op_sel_hi:[1,0]
	v_pk_mul_f32 v[38:39], v[38:39], v[76:77] op_sel_hi:[1,0]
	v_pk_mul_f32 v[40:41], v[40:41], v[76:77] op_sel_hi:[1,0]
	v_pk_mul_f32 v[42:43], v[42:43], v[76:77] op_sel_hi:[1,0]
	v_pk_mul_f32 v[44:45], v[44:45], v[76:77] op_sel_hi:[1,0]
	v_pk_mul_f32 v[46:47], v[46:47], v[76:77] op_sel_hi:[1,0]
	v_pk_mul_f32 v[48:49], v[48:49], v[76:77] op_sel_hi:[1,0]
	v_pk_mul_f32 v[50:51], v[50:51], v[76:77] op_sel_hi:[1,0]
	v_pk_fma_f32 v[52:53], v[36:37], v[2:3], v[164:165]
	v_pk_fma_f32 v[54:55], v[38:39], v[4:5], v[166:167]
	v_pk_fma_f32 v[56:57], v[40:41], v[6:7], v[168:169]
	v_pk_fma_f32 v[58:59], v[42:43], v[8:9], v[170:171]
	v_pk_fma_f32 v[60:61], v[44:45], v[10:11], v[172:173]
	v_pk_fma_f32 v[62:63], v[46:47], v[12:13], v[174:175]
	v_pk_fma_f32 v[64:65], v[48:49], v[14:15], v[176:177]
	v_pk_fma_f32 v[66:67], v[50:51], v[16:17], v[178:179]
	v_cvt_pk_bf16_f32 v180, v52, v53
	v_cvt_pk_bf16_f32 v181, v54, v55
	v_cvt_pk_bf16_f32 v182, v56, v57
	v_cvt_pk_bf16_f32 v183, v58, v59
	v_cvt_pk_bf16_f32 v184, v60, v61
	v_cvt_pk_bf16_f32 v185, v62, v63
	v_cvt_pk_bf16_f32 v186, v64, v65
	v_cvt_pk_bf16_f32 v187, v66, v67
	global_store_dwordx2 v1, v[180:181], s[10:11] offset:0
	global_store_dwordx2 v1, v[182:183], s[10:11] offset:512
	global_store_dwordx2 v1, v[184:185], s[10:11] offset:1024
	global_store_dwordx2 v1, v[186:187], s[10:11] offset:1536
	v_lshlrev_b32_e32 v52, 16, v180
	v_and_b32_e32 v53, s34, v180
	v_lshlrev_b32_e32 v54, 16, v181
	v_and_b32_e32 v55, s34, v181
	v_lshlrev_b32_e32 v56, 16, v182
	v_and_b32_e32 v57, s34, v182
	v_lshlrev_b32_e32 v58, 16, v183
	v_and_b32_e32 v59, s34, v183
	v_lshlrev_b32_e32 v60, 16, v184
	v_and_b32_e32 v61, s34, v184
	v_lshlrev_b32_e32 v62, 16, v185
	v_and_b32_e32 v63, s34, v185
	v_lshlrev_b32_e32 v64, 16, v186
	v_and_b32_e32 v65, s34, v186
	v_lshlrev_b32_e32 v66, 16, v187
	v_and_b32_e32 v67, s34, v187
	v_pk_mul_f32 v[70:71], v[52:53], v[52:53]
	v_pk_mul_f32 v[72:73], v[54:55], v[54:55]
	v_pk_fma_f32 v[70:71], v[56:57], v[56:57], v[70:71]
	v_pk_fma_f32 v[72:73], v[58:59], v[58:59], v[72:73]
	v_pk_fma_f32 v[70:71], v[60:61], v[60:61], v[70:71]
	v_pk_fma_f32 v[72:73], v[62:63], v[62:63], v[72:73]
	v_pk_fma_f32 v[70:71], v[64:65], v[64:65], v[70:71]
	v_pk_fma_f32 v[72:73], v[66:67], v[66:67], v[72:73]
	v_pk_add_f32 v[70:71], v[70:71], v[72:73]
	s_nop 0
	v_add_f32_e32 v70, v70, v71
	s_nop 1
	v_add_f32_dpp v70, v70, v70 quad_perm:[1,0,3,2] row_mask:0xf bank_mask:0xf bound_ctrl:1
	s_nop 1
	v_add_f32_dpp v70, v70, v70 quad_perm:[2,3,0,1] row_mask:0xf bank_mask:0xf bound_ctrl:1
	s_nop 1
	v_add_f32_dpp v70, v70, v70 row_half_mirror row_mask:0xf bank_mask:0xf bound_ctrl:1
	s_nop 1
	v_add_f32_dpp v70, v70, v70 row_mirror row_mask:0xf bank_mask:0xf bound_ctrl:1
	v_mov_b32_e32 v71, v70
	s_nop 1
	v_permlane16_swap_b32_e32 v70, v71
	v_add_f32_e32 v70, v70, v71
	v_mov_b32_e32 v71, v70
	s_nop 1
	v_permlane32_swap_b32_e32 v70, v71
	v_add_f32_e32 v70, v70, v71
	v_fmamk_f32 v70, v70, 0x3a800000, v69
	v_mul_f32_e32 v71, 0x4f800000, v70
	v_cmp_gt_f32_e32 vcc, s35, v70
	s_nop 1
	v_cndmask_b32_e32 v70, v70, v71, vcc
	v_sqrt_f32_e32 v71, v70
	s_nop 1
	v_add_u32_e32 v72, -1, v71
	v_add_u32_e32 v73, 1, v71
	v_fma_f32 v74, -v72, v71, v70
	v_fma_f32 v75, -v73, v71, v70
	v_cmp_ge_f32_e64 s[0:1], 0, v74
	s_nop 1
	v_cndmask_b32_e64 v71, v71, v72, s[0:1]
	v_cmp_lt_f32_e64 s[0:1], 0, v75
	s_nop 1
	v_cndmask_b32_e64 v71, v71, v73, s[0:1]
	v_mul_f32_e32 v72, 0x37800000, v71
	s_nop 0
	v_cndmask_b32_e32 v71, v71, v72, vcc
	v_cmp_class_f32_e32 vcc, v70, v80
	s_nop 1
	v_cndmask_b32_e32 v70, v71, v70, vcc
	v_div_scale_f32 v71, s[0:1], v70, v70, 1.0
	v_rcp_f32_e32 v72, v71
	v_div_scale_f32 v73, vcc, 1.0, v70, 1.0
	v_fma_f32 v74, -v71, v72, 1.0
	v_fmac_f32_e32 v72, v74, v72
	v_mul_f32_e32 v74, v73, v72
	v_fma_f32 v75, -v71, v74, v73
	v_fmac_f32_e32 v74, v75, v72
	v_fma_f32 v71, -v71, v74, v73
	v_div_fmas_f32 v71, v71, v72, v74
	v_div_fixup_f32 v76, v71, v70, 1.0
	v_pk_mul_f32 v[52:53], v[52:53], v[76:77] op_sel_hi:[1,0]
	v_pk_mul_f32 v[54:55], v[54:55], v[76:77] op_sel_hi:[1,0]
	v_pk_mul_f32 v[56:57], v[56:57], v[76:77] op_sel_hi:[1,0]
	v_pk_mul_f32 v[58:59], v[58:59], v[76:77] op_sel_hi:[1,0]
	v_pk_mul_f32 v[60:61], v[60:61], v[76:77] op_sel_hi:[1,0]
	v_pk_mul_f32 v[62:63], v[62:63], v[76:77] op_sel_hi:[1,0]
	v_pk_mul_f32 v[64:65], v[64:65], v[76:77] op_sel_hi:[1,0]
	v_pk_mul_f32 v[66:67], v[66:67], v[76:77] op_sel_hi:[1,0]
	v_pk_mul_f32 v[52:53], v[52:53], v[20:21]
	v_pk_mul_f32 v[54:55], v[54:55], v[22:23]
	v_pk_mul_f32 v[56:57], v[56:57], v[24:25]
	v_pk_mul_f32 v[58:59], v[58:59], v[26:27]
	v_pk_mul_f32 v[60:61], v[60:61], v[28:29]
	v_pk_mul_f32 v[62:63], v[62:63], v[30:31]
	v_pk_mul_f32 v[64:65], v[64:65], v[32:33]
	v_pk_mul_f32 v[66:67], v[66:67], v[34:35]
	v_cvt_pk_bf16_f32 v180, v52, v53
	v_cvt_pk_bf16_f32 v181, v54, v55
	v_cvt_pk_bf16_f32 v182, v56, v57
	v_cvt_pk_bf16_f32 v183, v58, v59
	v_cvt_pk_bf16_f32 v184, v60, v61
	v_cvt_pk_bf16_f32 v185, v62, v63
	v_cvt_pk_bf16_f32 v186, v64, v65
	v_cvt_pk_bf16_f32 v187, v66, v67
	global_store_dwordx2 v1, v[180:181], s[12:13] offset:0
	global_store_dwordx2 v1, v[182:183], s[12:13] offset:512
	global_store_dwordx2 v1, v[184:185], s[12:13] offset:1024
	global_store_dwordx2 v1, v[186:187], s[12:13] offset:1536
	s_add_u32 s10, s10, s20
	s_addc_u32 s11, s11, 0
	s_add_u32 s12, s12, s20
	s_addc_u32 s13, s13, 0
	s_lshl_b32 s36, s23, 2
	s_add_i32 s5, s5, s36
	s_branch .Lrw3_batch
.Lrw3_single:
	s_cmpk_lt_i32 s5, 0x4200
	s_cbranch_scc0 .Lrw3_done
	s_cmpk_lt_i32 s5, 0x4000
	s_cbranch_scc0 .Lrw3_sample
	global_load_dwordx2 v[84:85], v1, s[6:7] offset:0
	global_load_dwordx2 v[86:87], v1, s[6:7] offset:512
	global_load_dwordx2 v[88:89], v1, s[6:7] offset:1024
	global_load_dwordx2 v[90:91], v1, s[6:7] offset:1536
	global_load_dwordx4 v[92:95], v19, s[8:9] offset:0 nt
	global_load_dwordx4 v[96:99], v19, s[8:9] offset:1024 nt
	global_load_dwordx4 v[100:103], v19, s[8:9] offset:2048 nt
	global_load_dwordx4 v[104:107], v19, s[8:9] offset:3072 nt
	s_waitcnt vmcnt(0)
	v_lshlrev_b32_e32 v36, 16, v84
	v_and_b32_e32 v37, s34, v84
	v_lshlrev_b32_e32 v38, 16, v85
	v_and_b32_e32 v39, s34, v85
	v_lshlrev_b32_e32 v40, 16, v86
	v_and_b32_e32 v41, s34, v86
	v_lshlrev_b32_e32 v42, 16, v87
	v_and_b32_e32 v43, s34, v87
	v_lshlrev_b32_e32 v44, 16, v88
	v_and_b32_e32 v45, s34, v88
	v_lshlrev_b32_e32 v46, 16, v89
	v_and_b32_e32 v47, s34, v89
	v_lshlrev_b32_e32 v48, 16, v90
	v_and_b32_e32 v49, s34, v90
	v_lshlrev_b32_e32 v50, 16, v91
	v_and_b32_e32 v51, s34, v91
	v_pk_mul_f32 v[70:71], v[36:37], v[36:37]
	v_pk_mul_f32 v[72:73], v[38:39], v[38:39]
	v_pk_fma_f32 v[70:71], v[40:41], v[40:41], v[70:71]
	v_pk_fma_f32 v[72:73], v[42:43], v[42:43], v[72:73]
	v_pk_fma_f32 v[70:71], v[44:45], v[44:45], v[70:71]
	v_pk_fma_f32 v[72:73], v[46:47], v[46:47], v[72:73]
	v_pk_fma_f32 v[70:71], v[48:49], v[48:49], v[70:71]
	v_pk_fma_f32 v[72:73], v[50:51], v[50:51], v[72:73]
	v_pk_add_f32 v[70:71], v[70:71], v[72:73]
	s_nop 0
	v_add_f32_e32 v70, v70, v71
	s_nop 1
	v_add_f32_dpp v70, v70, v70 quad_perm:[1,0,3,2] row_mask:0xf bank_mask:0xf bound_ctrl:1
	s_nop 1
	v_add_f32_dpp v70, v70, v70 quad_perm:[2,3,0,1] row_mask:0xf bank_mask:0xf bound_ctrl:1
	s_nop 1
	v_add_f32_dpp v70, v70, v70 row_half_mirror row_mask:0xf bank_mask:0xf bound_ctrl:1
	s_nop 1
	v_add_f32_dpp v70, v70, v70 row_mirror row_mask:0xf bank_mask:0xf bound_ctrl:1
	v_mov_b32_e32 v71, v70
	s_nop 1
	v_permlane16_swap_b32_e32 v70, v71
	v_add_f32_e32 v70, v70, v71
	v_mov_b32_e32 v71, v70
	s_nop 1
	v_permlane32_swap_b32_e32 v70, v71
	v_add_f32_e32 v70, v70, v71
	v_fmamk_f32 v70, v70, 0x3a800000, v69
	v_mul_f32_e32 v71, 0x4f800000, v70
	v_cmp_gt_f32_e32 vcc, s35, v70
	s_nop 1
	v_cndmask_b32_e32 v70, v70, v71, vcc
	v_sqrt_f32_e32 v71, v70
	s_nop 1
	v_add_u32_e32 v72, -1, v71
	v_add_u32_e32 v73, 1, v71
	v_fma_f32 v74, -v72, v71, v70
	v_fma_f32 v75, -v73, v71, v70
	v_cmp_ge_f32_e64 s[0:1], 0, v74
	s_nop 1
	v_cndmask_b32_e64 v71, v71, v72, s[0:1]
	v_cmp_lt_f32_e64 s[0:1], 0, v75
	s_nop 1
	v_cndmask_b32_e64 v71, v71, v73, s[0:1]
	v_mul_f32_e32 v72, 0x37800000, v71
	s_nop 0
	v_cndmask_b32_e32 v71, v71, v72, vcc
	v_cmp_class_f32_e32 vcc, v70, v80
	s_nop 1
	v_cndmask_b32_e32 v70, v71, v70, vcc
	v_div_scale_f32 v71, s[0:1], v70, v70, 0.5
	v_rcp_f32_e32 v72, v71
	v_div_scale_f32 v73, vcc, 0.5, v70, 0.5
	v_fma_f32 v74, -v71, v72, 1.0
	v_fmac_f32_e32 v72, v74, v72
	v_mul_f32_e32 v74, v73, v72
	v_fma_f32 v75, -v71, v74, v73
	v_fmac_f32_e32 v74, v75, v72
	v_fma_f32 v71, -v71, v74, v73
	v_div_fmas_f32 v71, v71, v72, v74
	v_div_fixup_f32 v76, v71, v70, 0.5
	v_pk_mul_f32 v[36:37], v[36:37], v[76:77] op_sel_hi:[1,0]
	v_pk_mul_f32 v[38:39], v[38:39], v[76:77] op_sel_hi:[1,0]
	v_pk_mul_f32 v[40:41], v[40:41], v[76:77] op_sel_hi:[1,0]
	v_pk_mul_f32 v[42:43], v[42:43], v[76:77] op_sel_hi:[1,0]
	v_pk_mul_f32 v[44:45], v[44:45], v[76:77] op_sel_hi:[1,0]
	v_pk_mul_f32 v[46:47], v[46:47], v[76:77] op_sel_hi:[1,0]
	v_pk_mul_f32 v[48:49], v[48:49], v[76:77] op_sel_hi:[1,0]
	v_pk_mul_f32 v[50:51], v[50:51], v[76:77] op_sel_hi:[1,0]
	v_pk_fma_f32 v[52:53], v[36:37], v[2:3], v[92:93]
	v_pk_fma_f32 v[54:55], v[38:39], v[4:5], v[94:95]
	v_pk_fma_f32 v[56:57], v[40:41], v[6:7], v[96:97]
	v_pk_fma_f32 v[58:59], v[42:43], v[8:9], v[98:99]
	v_pk_fma_f32 v[60:61], v[44:45], v[10:11], v[100:101]
	v_pk_fma_f32 v[62:63], v[46:47], v[12:13], v[102:103]
	v_pk_fma_f32 v[64:65], v[48:49], v[14:15], v[104:105]
	v_pk_fma_f32 v[66:67], v[50:51], v[16:17], v[106:107]
	v_cvt_pk_bf16_f32 v180, v52, v53
	v_cvt_pk_bf16_f32 v181, v54, v55
	v_cvt_pk_bf16_f32 v182, v56, v57
	v_cvt_pk_bf16_f32 v183, v58, v59
	v_cvt_pk_bf16_f32 v184, v60, v61
	v_cvt_pk_bf16_f32 v185, v62, v63
	v_cvt_pk_bf16_f32 v186, v64, v65
	v_cvt_pk_bf16_f32 v187, v66, v67
	global_store_dwordx2 v1, v[180:181], s[10:11] offset:0
	global_store_dwordx2 v1, v[182:183], s[10:11] offset:512
	global_store_dwordx2 v1, v[184:185], s[10:11] offset:1024
	global_store_dwordx2 v1, v[186:187], s[10:11] offset:1536
	v_lshlrev_b32_e32 v52, 16, v180
	v_and_b32_e32 v53, s34, v180
	v_lshlrev_b32_e32 v54, 16, v181
	v_and_b32_e32 v55, s34, v181
	v_lshlrev_b32_e32 v56, 16, v182
	v_and_b32_e32 v57, s34, v182
	v_lshlrev_b32_e32 v58, 16, v183
	v_and_b32_e32 v59, s34, v183
	v_lshlrev_b32_e32 v60, 16, v184
	v_and_b32_e32 v61, s34, v184
	v_lshlrev_b32_e32 v62, 16, v185
	v_and_b32_e32 v63, s34, v185
	v_lshlrev_b32_e32 v64, 16, v186
	v_and_b32_e32 v65, s34, v186
	v_lshlrev_b32_e32 v66, 16, v187
	v_and_b32_e32 v67, s34, v187
	v_pk_mul_f32 v[70:71], v[52:53], v[52:53]
	v_pk_mul_f32 v[72:73], v[54:55], v[54:55]
	v_pk_fma_f32 v[70:71], v[56:57], v[56:57], v[70:71]
	v_pk_fma_f32 v[72:73], v[58:59], v[58:59], v[72:73]
	v_pk_fma_f32 v[70:71], v[60:61], v[60:61], v[70:71]
	v_pk_fma_f32 v[72:73], v[62:63], v[62:63], v[72:73]
	v_pk_fma_f32 v[70:71], v[64:65], v[64:65], v[70:71]
	v_pk_fma_f32 v[72:73], v[66:67], v[66:67], v[72:73]
	v_pk_add_f32 v[70:71], v[70:71], v[72:73]
	s_nop 0
	v_add_f32_e32 v70, v70, v71
	s_nop 1
	v_add_f32_dpp v70, v70, v70 quad_perm:[1,0,3,2] row_mask:0xf bank_mask:0xf bound_ctrl:1
	s_nop 1
	v_add_f32_dpp v70, v70, v70 quad_perm:[2,3,0,1] row_mask:0xf bank_mask:0xf bound_ctrl:1
	s_nop 1
	v_add_f32_dpp v70, v70, v70 row_half_mirror row_mask:0xf bank_mask:0xf bound_ctrl:1
	s_nop 1
	v_add_f32_dpp v70, v70, v70 row_mirror row_mask:0xf bank_mask:0xf bound_ctrl:1
	v_mov_b32_e32 v71, v70
	s_nop 1
	v_permlane16_swap_b32_e32 v70, v71
	v_add_f32_e32 v70, v70, v71
	v_mov_b32_e32 v71, v70
	s_nop 1
	v_permlane32_swap_b32_e32 v70, v71
	v_add_f32_e32 v70, v70, v71
	v_fmamk_f32 v70, v70, 0x3a800000, v69
	v_mul_f32_e32 v71, 0x4f800000, v70
	v_cmp_gt_f32_e32 vcc, s35, v70
	s_nop 1
	v_cndmask_b32_e32 v70, v70, v71, vcc
	v_sqrt_f32_e32 v71, v70
	s_nop 1
	v_add_u32_e32 v72, -1, v71
	v_add_u32_e32 v73, 1, v71
	v_fma_f32 v74, -v72, v71, v70
	v_fma_f32 v75, -v73, v71, v70
	v_cmp_ge_f32_e64 s[0:1], 0, v74
	s_nop 1
	v_cndmask_b32_e64 v71, v71, v72, s[0:1]
	v_cmp_lt_f32_e64 s[0:1], 0, v75
	s_nop 1
	v_cndmask_b32_e64 v71, v71, v73, s[0:1]
	v_mul_f32_e32 v72, 0x37800000, v71
	s_nop 0
	v_cndmask_b32_e32 v71, v71, v72, vcc
	v_cmp_class_f32_e32 vcc, v70, v80
	s_nop 1
	v_cndmask_b32_e32 v70, v71, v70, vcc
	v_div_scale_f32 v71, s[0:1], v70, v70, 1.0
	v_rcp_f32_e32 v72, v71
	v_div_scale_f32 v73, vcc, 1.0, v70, 1.0
	v_fma_f32 v74, -v71, v72, 1.0
	v_fmac_f32_e32 v72, v74, v72
	v_mul_f32_e32 v74, v73, v72
	v_fma_f32 v75, -v71, v74, v73
	v_fmac_f32_e32 v74, v75, v72
	v_fma_f32 v71, -v71, v74, v73
	v_div_fmas_f32 v71, v71, v72, v74
	v_div_fixup_f32 v76, v71, v70, 1.0
	v_pk_mul_f32 v[52:53], v[52:53], v[76:77] op_sel_hi:[1,0]
	v_pk_mul_f32 v[54:55], v[54:55], v[76:77] op_sel_hi:[1,0]
	v_pk_mul_f32 v[56:57], v[56:57], v[76:77] op_sel_hi:[1,0]
	v_pk_mul_f32 v[58:59], v[58:59], v[76:77] op_sel_hi:[1,0]
	v_pk_mul_f32 v[60:61], v[60:61], v[76:77] op_sel_hi:[1,0]
	v_pk_mul_f32 v[62:63], v[62:63], v[76:77] op_sel_hi:[1,0]
	v_pk_mul_f32 v[64:65], v[64:65], v[76:77] op_sel_hi:[1,0]
	v_pk_mul_f32 v[66:67], v[66:67], v[76:77] op_sel_hi:[1,0]
	v_pk_mul_f32 v[52:53], v[52:53], v[20:21]
	v_pk_mul_f32 v[54:55], v[54:55], v[22:23]
	v_pk_mul_f32 v[56:57], v[56:57], v[24:25]
	v_pk_mul_f32 v[58:59], v[58:59], v[26:27]
	v_pk_mul_f32 v[60:61], v[60:61], v[28:29]
	v_pk_mul_f32 v[62:63], v[62:63], v[30:31]
	v_pk_mul_f32 v[64:65], v[64:65], v[32:33]
	v_pk_mul_f32 v[66:67], v[66:67], v[34:35]
	v_cvt_pk_bf16_f32 v180, v52, v53
	v_cvt_pk_bf16_f32 v181, v54, v55
	v_cvt_pk_bf16_f32 v182, v56, v57
	v_cvt_pk_bf16_f32 v183, v58, v59
	v_cvt_pk_bf16_f32 v184, v60, v61
	v_cvt_pk_bf16_f32 v185, v62, v63
	v_cvt_pk_bf16_f32 v186, v64, v65
	v_cvt_pk_bf16_f32 v187, v66, v67
	global_store_dwordx2 v1, v[180:181], s[12:13] offset:0
	global_store_dwordx2 v1, v[182:183], s[12:13] offset:512
	global_store_dwordx2 v1, v[184:185], s[12:13] offset:1024
	global_store_dwordx2 v1, v[186:187], s[12:13] offset:1536
	s_branch .Lrw3_next
.Lrw3_sample:
	s_sub_i32 s36, s5, 0x4000
	s_lshl_b32 s36, s36, 12
	s_add_u32 s14, s26, 0x32200000
	s_addc_u32 s15, s27, 0
	s_add_u32 s14, s14, s36
	s_addc_u32 s15, s15, 0
	s_add_u32 s16, s54, s36
	s_addc_u32 s17, s55, 0
	global_load_dwordx4 v[52:55], v19, s[16:17] offset:0 nt
	global_load_dwordx4 v[56:59], v19, s[16:17] offset:1024 nt
	global_load_dwordx4 v[60:63], v19, s[16:17] offset:2048 nt
	global_load_dwordx4 v[64:67], v19, s[16:17] offset:3072 nt
	v_mov_b32_e32 v36, 0
	v_mov_b32_e32 v37, 0
	v_mov_b32_e32 v38, 0
	v_mov_b32_e32 v39, 0
	v_mov_b32_e32 v40, 0
	v_mov_b32_e32 v41, 0
	v_mov_b32_e32 v42, 0
	v_mov_b32_e32 v43, 0
	v_mov_b32_e32 v44, 0
	v_mov_b32_e32 v45, 0
	v_mov_b32_e32 v46, 0
	v_mov_b32_e32 v47, 0
	v_mov_b32_e32 v48, 0
	v_mov_b32_e32 v49, 0
	v_mov_b32_e32 v50, 0
	v_mov_b32_e32 v51, 0
	global_load_dwordx4 v[84:87], v19, s[14:15] offset:0
	global_load_dwordx4 v[88:91], v19, s[14:15] offset:1024
	global_load_dwordx4 v[92:95], v19, s[14:15] offset:2048
	global_load_dwordx4 v[96:99], v19, s[14:15] offset:3072
	s_add_u32 s14, s14, 0x200000
	s_addc_u32 s15, s15, 0
	global_load_dwordx4 v[100:103], v19, s[14:15] offset:0
	global_load_dwordx4 v[104:107], v19, s[14:15] offset:1024
	global_load_dwordx4 v[108:111], v19, s[14:15] offset:2048
	global_load_dwordx4 v[112:115], v19, s[14:15] offset:3072
	s_add_u32 s14, s14, 0x200000
	s_addc_u32 s15, s15, 0
	global_load_dwordx4 v[116:119], v19, s[14:15] offset:0
	global_load_dwordx4 v[120:123], v19, s[14:15] offset:1024
	global_load_dwordx4 v[124:127], v19, s[14:15] offset:2048
	global_load_dwordx4 v[128:131], v19, s[14:15] offset:3072
	s_add_u32 s14, s14, 0x200000
	s_addc_u32 s15, s15, 0
	global_load_dwordx4 v[132:135], v19, s[14:15] offset:0
	global_load_dwordx4 v[136:139], v19, s[14:15] offset:1024
	global_load_dwordx4 v[140:143], v19, s[14:15] offset:2048
	global_load_dwordx4 v[144:147], v19, s[14:15] offset:3072
	s_add_u32 s14, s14, 0x200000
	s_addc_u32 s15, s15, 0
	global_load_dwordx4 v[148:151], v19, s[14:15] offset:0
	global_load_dwordx4 v[152:155], v19, s[14:15] offset:1024
	global_load_dwordx4 v[156:159], v19, s[14:15] offset:2048
	global_load_dwordx4 v[160:163], v19, s[14:15] offset:3072
	s_add_u32 s14, s14, 0x200000
	s_addc_u32 s15, s15, 0
	global_load_dwordx4 v[164:167], v19, s[14:15] offset:0
	global_load_dwordx4 v[168:171], v19, s[14:15] offset:1024
	global_load_dwordx4 v[172:175], v19, s[14:15] offset:2048
	global_load_dwordx4 v[176:179], v19, s[14:15] offset:3072
	s_add_u32 s14, s14, 0x200000
	s_addc_u32 s15, s15, 0
	s_waitcnt vmcnt(20)
	v_pk_add_f32 v[36:37], v[36:37], v[84:85]
	v_pk_add_f32 v[38:39], v[38:39], v[86:87]
	v_pk_add_f32 v[40:41], v[40:41], v[88:89]
	v_pk_add_f32 v[42:43], v[42:43], v[90:91]
	v_pk_add_f32 v[44:45], v[44:45], v[92:93]
	v_pk_add_f32 v[46:47], v[46:47], v[94:95]
	v_pk_add_f32 v[48:49], v[48:49], v[96:97]
	v_pk_add_f32 v[50:51], v[50:51], v[98:99]
	s_waitcnt vmcnt(16)
	v_pk_add_f32 v[36:37], v[36:37], v[100:101]
	v_pk_add_f32 v[38:39], v[38:39], v[102:103]
	v_pk_add_f32 v[40:41], v[40:41], v[104:105]
	v_pk_add_f32 v[42:43], v[42:43], v[106:107]
	v_pk_add_f32 v[44:45], v[44:45], v[108:109]
	v_pk_add_f32 v[46:47], v[46:47], v[110:111]
	v_pk_add_f32 v[48:49], v[48:49], v[112:113]
	v_pk_add_f32 v[50:51], v[50:51], v[114:115]
	s_waitcnt vmcnt(12)
	v_pk_add_f32 v[36:37], v[36:37], v[116:117]
	v_pk_add_f32 v[38:39], v[38:39], v[118:119]
	v_pk_add_f32 v[40:41], v[40:41], v[120:121]
	v_pk_add_f32 v[42:43], v[42:43], v[122:123]
	v_pk_add_f32 v[44:45], v[44:45], v[124:125]
	v_pk_add_f32 v[46:47], v[46:47], v[126:127]
	v_pk_add_f32 v[48:49], v[48:49], v[128:129]
	v_pk_add_f32 v[50:51], v[50:51], v[130:131]
	s_waitcnt vmcnt(8)
	v_pk_add_f32 v[36:37], v[36:37], v[132:133]
	v_pk_add_f32 v[38:39], v[38:39], v[134:135]
	v_pk_add_f32 v[40:41], v[40:41], v[136:137]
	v_pk_add_f32 v[42:43], v[42:43], v[138:139]
	v_pk_add_f32 v[44:45], v[44:45], v[140:141]
	v_pk_add_f32 v[46:47], v[46:47], v[142:143]
	v_pk_add_f32 v[48:49], v[48:49], v[144:145]
	v_pk_add_f32 v[50:51], v[50:51], v[146:147]
	s_waitcnt vmcnt(4)
	v_pk_add_f32 v[36:37], v[36:37], v[148:149]
	v_pk_add_f32 v[38:39], v[38:39], v[150:151]
	v_pk_add_f32 v[40:41], v[40:41], v[152:153]
	v_pk_add_f32 v[42:43], v[42:43], v[154:155]
	v_pk_add_f32 v[44:45], v[44:45], v[156:157]
	v_pk_add_f32 v[46:47], v[46:47], v[158:159]
	v_pk_add_f32 v[48:49], v[48:49], v[160:161]
	v_pk_add_f32 v[50:51], v[50:51], v[162:163]
	s_waitcnt vmcnt(0)
	v_pk_add_f32 v[36:37], v[36:37], v[164:165]
	v_pk_add_f32 v[38:39], v[38:39], v[166:167]
	v_pk_add_f32 v[40:41], v[40:41], v[168:169]
	v_pk_add_f32 v[42:43], v[42:43], v[170:171]
	v_pk_add_f32 v[44:45], v[44:45], v[172:173]
	v_pk_add_f32 v[46:47], v[46:47], v[174:175]
	v_pk_add_f32 v[48:49], v[48:49], v[176:177]
	v_pk_add_f32 v[50:51], v[50:51], v[178:179]
	global_load_dwordx4 v[84:87], v19, s[14:15] offset:0
	global_load_dwordx4 v[88:91], v19, s[14:15] offset:1024
	global_load_dwordx4 v[92:95], v19, s[14:15] offset:2048
	global_load_dwordx4 v[96:99], v19, s[14:15] offset:3072
	s_add_u32 s14, s14, 0x200000
	s_addc_u32 s15, s15, 0
	global_load_dwordx4 v[100:103], v19, s[14:15] offset:0
	global_load_dwordx4 v[104:107], v19, s[14:15] offset:1024
	global_load_dwordx4 v[108:111], v19, s[14:15] offset:2048
	global_load_dwordx4 v[112:115], v19, s[14:15] offset:3072
	s_add_u32 s14, s14, 0x200000
	s_addc_u32 s15, s15, 0
	global_load_dwordx4 v[116:119], v19, s[14:15] offset:0
	global_load_dwordx4 v[120:123], v19, s[14:15] offset:1024
	global_load_dwordx4 v[124:127], v19, s[14:15] offset:2048
	global_load_dwordx4 v[128:131], v19, s[14:15] offset:3072
	s_add_u32 s14, s14, 0x200000
	s_addc_u32 s15, s15, 0
	global_load_dwordx4 v[132:135], v19, s[14:15] offset:0
	global_load_dwordx4 v[136:139], v19, s[14:15] offset:1024
	global_load_dwordx4 v[140:143], v19, s[14:15] offset:2048
	global_load_dwordx4 v[144:147], v19, s[14:15] offset:3072
	s_add_u32 s14, s14, 0x200000
	s_addc_u32 s15, s15, 0
	global_load_dwordx4 v[148:151], v19, s[14:15] offset:0
	global_load_dwordx4 v[152:155], v19, s[14:15] offset:1024
	global_load_dwordx4 v[156:159], v19, s[14:15] offset:2048
	global_load_dwordx4 v[160:163], v19, s[14:15] offset:3072
	s_add_u32 s14, s14, 0x200000
	s_addc_u32 s15, s15, 0
	s_waitcnt vmcnt(16)
	v_pk_add_f32 v[36:37], v[36:37], v[84:85]
	v_pk_add_f32 v[38:39], v[38:39], v[86:87]
	v_pk_add_f32 v[40:41], v[40:41], v[88:89]
	v_pk_add_f32 v[42:43], v[42:43], v[90:91]
	v_pk_add_f32 v[44:45], v[44:45], v[92:93]
	v_pk_add_f32 v[46:47], v[46:47], v[94:95]
	v_pk_add_f32 v[48:49], v[48:49], v[96:97]
	v_pk_add_f32 v[50:51], v[50:51], v[98:99]
	s_waitcnt vmcnt(12)
	v_pk_add_f32 v[36:37], v[36:37], v[100:101]
	v_pk_add_f32 v[38:39], v[38:39], v[102:103]
	v_pk_add_f32 v[40:41], v[40:41], v[104:105]
	v_pk_add_f32 v[42:43], v[42:43], v[106:107]
	v_pk_add_f32 v[44:45], v[44:45], v[108:109]
	v_pk_add_f32 v[46:47], v[46:47], v[110:111]
	v_pk_add_f32 v[48:49], v[48:49], v[112:113]
	v_pk_add_f32 v[50:51], v[50:51], v[114:115]
	s_waitcnt vmcnt(8)
	v_pk_add_f32 v[36:37], v[36:37], v[116:117]
	v_pk_add_f32 v[38:39], v[38:39], v[118:119]
	v_pk_add_f32 v[40:41], v[40:41], v[120:121]
	v_pk_add_f32 v[42:43], v[42:43], v[122:123]
	v_pk_add_f32 v[44:45], v[44:45], v[124:125]
	v_pk_add_f32 v[46:47], v[46:47], v[126:127]
	v_pk_add_f32 v[48:49], v[48:49], v[128:129]
	v_pk_add_f32 v[50:51], v[50:51], v[130:131]
	s_waitcnt vmcnt(4)
	v_pk_add_f32 v[36:37], v[36:37], v[132:133]
	v_pk_add_f32 v[38:39], v[38:39], v[134:135]
	v_pk_add_f32 v[40:41], v[40:41], v[136:137]
	v_pk_add_f32 v[42:43], v[42:43], v[138:139]
	v_pk_add_f32 v[44:45], v[44:45], v[140:141]
	v_pk_add_f32 v[46:47], v[46:47], v[142:143]
	v_pk_add_f32 v[48:49], v[48:49], v[144:145]
	v_pk_add_f32 v[50:51], v[50:51], v[146:147]
	s_waitcnt vmcnt(0)
	v_pk_add_f32 v[36:37], v[36:37], v[148:149]
	v_pk_add_f32 v[38:39], v[38:39], v[150:151]
	v_pk_add_f32 v[40:41], v[40:41], v[152:153]
	v_pk_add_f32 v[42:43], v[42:43], v[154:155]
	v_pk_add_f32 v[44:45], v[44:45], v[156:157]
	v_pk_add_f32 v[46:47], v[46:47], v[158:159]
	v_pk_add_f32 v[48:49], v[48:49], v[160:161]
	v_pk_add_f32 v[50:51], v[50:51], v[162:163]
	v_pk_mul_f32 v[70:71], v[36:37], v[36:37]
	v_pk_mul_f32 v[72:73], v[38:39], v[38:39]
	v_pk_fma_f32 v[70:71], v[40:41], v[40:41], v[70:71]
	v_pk_fma_f32 v[72:73], v[42:43], v[42:43], v[72:73]
	v_pk_fma_f32 v[70:71], v[44:45], v[44:45], v[70:71]
	v_pk_fma_f32 v[72:73], v[46:47], v[46:47], v[72:73]
	v_pk_fma_f32 v[70:71], v[48:49], v[48:49], v[70:71]
	v_pk_fma_f32 v[72:73], v[50:51], v[50:51], v[72:73]
	v_pk_add_f32 v[70:71], v[70:71], v[72:73]
	s_nop 0
	v_add_f32_e32 v70, v70, v71
	s_nop 1
	v_add_f32_dpp v70, v70, v70 quad_perm:[1,0,3,2] row_mask:0xf bank_mask:0xf bound_ctrl:1
	s_nop 1
	v_add_f32_dpp v70, v70, v70 quad_perm:[2,3,0,1] row_mask:0xf bank_mask:0xf bound_ctrl:1
	s_nop 1
	v_add_f32_dpp v70, v70, v70 row_half_mirror row_mask:0xf bank_mask:0xf bound_ctrl:1
	s_nop 1
	v_add_f32_dpp v70, v70, v70 row_mirror row_mask:0xf bank_mask:0xf bound_ctrl:1
	v_mov_b32_e32 v71, v70
	s_nop 1
	v_permlane16_swap_b32_e32 v70, v71
	v_add_f32_e32 v70, v70, v71
	v_mov_b32_e32 v71, v70
	s_nop 1
	v_permlane32_swap_b32_e32 v70, v71
	v_add_f32_e32 v70, v70, v71
	v_fmamk_f32 v70, v70, 0x3a800000, v69
	v_mul_f32_e32 v71, 0x4f800000, v70
	v_cmp_gt_f32_e32 vcc, s35, v70
	s_nop 1
	v_cndmask_b32_e32 v70, v70, v71, vcc
	v_sqrt_f32_e32 v71, v70
	s_nop 1
	v_add_u32_e32 v72, -1, v71
	v_add_u32_e32 v73, 1, v71
	v_fma_f32 v74, -v72, v71, v70
	v_fma_f32 v75, -v73, v71, v70
	v_cmp_ge_f32_e64 s[0:1], 0, v74
	s_nop 1
	v_cndmask_b32_e64 v71, v71, v72, s[0:1]
	v_cmp_lt_f32_e64 s[0:1], 0, v75
	s_nop 1
	v_cndmask_b32_e64 v71, v71, v73, s[0:1]
	v_mul_f32_e32 v72, 0x37800000, v71
	s_nop 0
	v_cndmask_b32_e32 v71, v71, v72, vcc
	v_cmp_class_f32_e32 vcc, v70, v80
	s_nop 1
	v_cndmask_b32_e32 v70, v71, v70, vcc
	v_div_scale_f32 v71, s[0:1], v70, v70, 0.5
	v_rcp_f32_e32 v72, v71
	v_div_scale_f32 v73, vcc, 0.5, v70, 0.5
	v_fma_f32 v74, -v71, v72, 1.0
	v_fmac_f32_e32 v72, v74, v72
	v_mul_f32_e32 v74, v73, v72
	v_fma_f32 v75, -v71, v74, v73
	v_fmac_f32_e32 v74, v75, v72
	v_fma_f32 v71, -v71, v74, v73
	v_div_fmas_f32 v71, v71, v72, v74
	v_div_fixup_f32 v76, v71, v70, 0.5
	v_pk_mul_f32 v[36:37], v[36:37], v[76:77] op_sel_hi:[1,0]
	v_pk_mul_f32 v[38:39], v[38:39], v[76:77] op_sel_hi:[1,0]
	v_pk_mul_f32 v[40:41], v[40:41], v[76:77] op_sel_hi:[1,0]
	v_pk_mul_f32 v[42:43], v[42:43], v[76:77] op_sel_hi:[1,0]
	v_pk_mul_f32 v[44:45], v[44:45], v[76:77] op_sel_hi:[1,0]
	v_pk_mul_f32 v[46:47], v[46:47], v[76:77] op_sel_hi:[1,0]
	v_pk_mul_f32 v[48:49], v[48:49], v[76:77] op_sel_hi:[1,0]
	v_pk_mul_f32 v[50:51], v[50:51], v[76:77] op_sel_hi:[1,0]
	v_pk_fma_f32 v[52:53], v[36:37], v[2:3], v[52:53]
	v_pk_fma_f32 v[54:55], v[38:39], v[4:5], v[54:55]
	v_pk_fma_f32 v[56:57], v[40:41], v[6:7], v[56:57]
	v_pk_fma_f32 v[58:59], v[42:43], v[8:9], v[58:59]
	v_pk_fma_f32 v[60:61], v[44:45], v[10:11], v[60:61]
	v_pk_fma_f32 v[62:63], v[46:47], v[12:13], v[62:63]
	v_pk_fma_f32 v[64:65], v[48:49], v[14:15], v[64:65]
	v_pk_fma_f32 v[66:67], v[50:51], v[16:17], v[66:67]
	v_cvt_pk_bf16_f32 v180, v52, v53
	v_cvt_pk_bf16_f32 v181, v54, v55
	v_cvt_pk_bf16_f32 v182, v56, v57
	v_cvt_pk_bf16_f32 v183, v58, v59
	v_cvt_pk_bf16_f32 v184, v60, v61
	v_cvt_pk_bf16_f32 v185, v62, v63
	v_cvt_pk_bf16_f32 v186, v64, v65
	v_cvt_pk_bf16_f32 v187, v66, v67
	global_store_dwordx2 v1, v[180:181], s[10:11] offset:0
	global_store_dwordx2 v1, v[182:183], s[10:11] offset:512
	global_store_dwordx2 v1, v[184:185], s[10:11] offset:1024
	global_store_dwordx2 v1, v[186:187], s[10:11] offset:1536
	v_lshlrev_b32_e32 v52, 16, v180
	v_and_b32_e32 v53, s34, v180
	v_lshlrev_b32_e32 v54, 16, v181
	v_and_b32_e32 v55, s34, v181
	v_lshlrev_b32_e32 v56, 16, v182
	v_and_b32_e32 v57, s34, v182
	v_lshlrev_b32_e32 v58, 16, v183
	v_and_b32_e32 v59, s34, v183
	v_lshlrev_b32_e32 v60, 16, v184
	v_and_b32_e32 v61, s34, v184
	v_lshlrev_b32_e32 v62, 16, v185
	v_and_b32_e32 v63, s34, v185
	v_lshlrev_b32_e32 v64, 16, v186
	v_and_b32_e32 v65, s34, v186
	v_lshlrev_b32_e32 v66, 16, v187
	v_and_b32_e32 v67, s34, v187
	v_pk_mul_f32 v[70:71], v[52:53], v[52:53]
	v_pk_mul_f32 v[72:73], v[54:55], v[54:55]
	v_pk_fma_f32 v[70:71], v[56:57], v[56:57], v[70:71]
	v_pk_fma_f32 v[72:73], v[58:59], v[58:59], v[72:73]
	v_pk_fma_f32 v[70:71], v[60:61], v[60:61], v[70:71]
	v_pk_fma_f32 v[72:73], v[62:63], v[62:63], v[72:73]
	v_pk_fma_f32 v[70:71], v[64:65], v[64:65], v[70:71]
	v_pk_fma_f32 v[72:73], v[66:67], v[66:67], v[72:73]
	v_pk_add_f32 v[70:71], v[70:71], v[72:73]
	s_nop 0
	v_add_f32_e32 v70, v70, v71
	s_nop 1
	v_add_f32_dpp v70, v70, v70 quad_perm:[1,0,3,2] row_mask:0xf bank_mask:0xf bound_ctrl:1
	s_nop 1
	v_add_f32_dpp v70, v70, v70 quad_perm:[2,3,0,1] row_mask:0xf bank_mask:0xf bound_ctrl:1
	s_nop 1
	v_add_f32_dpp v70, v70, v70 row_half_mirror row_mask:0xf bank_mask:0xf bound_ctrl:1
	s_nop 1
	v_add_f32_dpp v70, v70, v70 row_mirror row_mask:0xf bank_mask:0xf bound_ctrl:1
	v_mov_b32_e32 v71, v70
	s_nop 1
	v_permlane16_swap_b32_e32 v70, v71
	v_add_f32_e32 v70, v70, v71
	v_mov_b32_e32 v71, v70
	s_nop 1
	v_permlane32_swap_b32_e32 v70, v71
	v_add_f32_e32 v70, v70, v71
	v_fmamk_f32 v70, v70, 0x3a800000, v69
	v_mul_f32_e32 v71, 0x4f800000, v70
	v_cmp_gt_f32_e32 vcc, s35, v70
	s_nop 1
	v_cndmask_b32_e32 v70, v70, v71, vcc
	v_sqrt_f32_e32 v71, v70
	s_nop 1
	v_add_u32_e32 v72, -1, v71
	v_add_u32_e32 v73, 1, v71
	v_fma_f32 v74, -v72, v71, v70
	v_fma_f32 v75, -v73, v71, v70
	v_cmp_ge_f32_e64 s[0:1], 0, v74
	s_nop 1
	v_cndmask_b32_e64 v71, v71, v72, s[0:1]
	v_cmp_lt_f32_e64 s[0:1], 0, v75
	s_nop 1
	v_cndmask_b32_e64 v71, v71, v73, s[0:1]
	v_mul_f32_e32 v72, 0x37800000, v71
	s_nop 0
	v_cndmask_b32_e32 v71, v71, v72, vcc
	v_cmp_class_f32_e32 vcc, v70, v80
	s_nop 1
	v_cndmask_b32_e32 v70, v71, v70, vcc
	v_div_scale_f32 v71, s[0:1], v70, v70, 1.0
	v_rcp_f32_e32 v72, v71
	v_div_scale_f32 v73, vcc, 1.0, v70, 1.0
	v_fma_f32 v74, -v71, v72, 1.0
	v_fmac_f32_e32 v72, v74, v72
	v_mul_f32_e32 v74, v73, v72
	v_fma_f32 v75, -v71, v74, v73
	v_fmac_f32_e32 v74, v75, v72
	v_fma_f32 v71, -v71, v74, v73
	v_div_fmas_f32 v71, v71, v72, v74
	v_div_fixup_f32 v76, v71, v70, 1.0
	v_pk_mul_f32 v[52:53], v[52:53], v[76:77] op_sel_hi:[1,0]
	v_pk_mul_f32 v[54:55], v[54:55], v[76:77] op_sel_hi:[1,0]
	v_pk_mul_f32 v[56:57], v[56:57], v[76:77] op_sel_hi:[1,0]
	v_pk_mul_f32 v[58:59], v[58:59], v[76:77] op_sel_hi:[1,0]
	v_pk_mul_f32 v[60:61], v[60:61], v[76:77] op_sel_hi:[1,0]
	v_pk_mul_f32 v[62:63], v[62:63], v[76:77] op_sel_hi:[1,0]
	v_pk_mul_f32 v[64:65], v[64:65], v[76:77] op_sel_hi:[1,0]
	v_pk_mul_f32 v[66:67], v[66:67], v[76:77] op_sel_hi:[1,0]
	v_pk_mul_f32 v[52:53], v[52:53], v[20:21]
	v_pk_mul_f32 v[54:55], v[54:55], v[22:23]
	v_pk_mul_f32 v[56:57], v[56:57], v[24:25]
	v_pk_mul_f32 v[58:59], v[58:59], v[26:27]
	v_pk_mul_f32 v[60:61], v[60:61], v[28:29]
	v_pk_mul_f32 v[62:63], v[62:63], v[30:31]
	v_pk_mul_f32 v[64:65], v[64:65], v[32:33]
	v_pk_mul_f32 v[66:67], v[66:67], v[34:35]
	v_cvt_pk_bf16_f32 v180, v52, v53
	v_cvt_pk_bf16_f32 v181, v54, v55
	v_cvt_pk_bf16_f32 v182, v56, v57
	v_cvt_pk_bf16_f32 v183, v58, v59
	v_cvt_pk_bf16_f32 v184, v60, v61
	v_cvt_pk_bf16_f32 v185, v62, v63
	v_cvt_pk_bf16_f32 v186, v64, v65
	v_cvt_pk_bf16_f32 v187, v66, v67
	global_store_dwordx2 v1, v[180:181], s[12:13] offset:0
	global_store_dwordx2 v1, v[182:183], s[12:13] offset:512
	global_store_dwordx2 v1, v[184:185], s[12:13] offset:1024
	global_store_dwordx2 v1, v[186:187], s[12:13] offset:1536
.Lrw3_next:
	s_add_u32 s6, s6, s20
	s_addc_u32 s7, s7, 0
	s_add_u32 s8, s8, s21
	s_addc_u32 s9, s9, 0
	s_add_u32 s10, s10, s20
	s_addc_u32 s11, s11, 0
	s_add_u32 s12, s12, s20
	s_addc_u32 s13, s13, 0
	s_add_i32 s5, s5, s23
	s_branch .Lrw3_single
.Lrw3_done:
.LBB0_327:
	v_readlane_b32 s36, v255, 40
	s_cmp_lt_i32 s91, 5
	v_readlane_b32 s40, v255, 44
	v_readlane_b32 s41, v255, 45
	v_readlane_b32 s42, v255, 46
	v_readlane_b32 s43, v255, 47
	v_readlane_b32 s46, v255, 50
	v_readlane_b32 s47, v255, 51
	v_readlane_b32 s37, v255, 41
	v_readlane_b32 s38, v255, 42
	v_readlane_b32 s39, v255, 43
	v_readlane_b32 s44, v255, 48
	v_readlane_b32 s45, v255, 49
	v_readlane_b32 s48, v255, 52
	v_readlane_b32 s49, v255, 53
	v_readlane_b32 s50, v255, 54
	v_readlane_b32 s51, v255, 55
	s_cbranch_scc1 .LBB0_382
	s_waitcnt vmcnt(0)
	s_waitcnt vmcnt(0) lgkmcnt(0)
	s_barrier
	s_mov_b64 s[0:1], exec
	v_readlane_b32 s2, v255, 5
	v_readlane_b32 s3, v255, 6
	s_and_b64 s[2:3], s[0:1], s[2:3]
	s_mov_b64 exec, s[2:3]
	s_cbranch_execz .LBB0_381
	s_add_u32 s2, s26, 0x4200
	s_addc_u32 s3, s27, 0
	s_add_i32 s4, 0, 0x24160
	v_mov_b32_e32 v1, s4
	s_waitcnt vmcnt(0) expcnt(0) lgkmcnt(0)
	ds_read_b32 v3, v1
	s_add_i32 s4, 0, 0x24164
	v_mov_b32_e32 v1, s4
	ds_read_b32 v1, v1
	s_waitcnt lgkmcnt(1)
	v_cmp_ne_u32_e32 vcc, 0, v3
	s_cbranch_vccnz .LBB0_345
	s_add_u32 s4, s26, 0x4400
	s_addc_u32 s5, s27, 0
	s_add_u32 s6, s26, 0x4500
	s_addc_u32 s7, s27, 0
	s_add_u32 s8, s26, 0x4600
	s_addc_u32 s9, s27, 0
	s_add_u32 s10, s26, 0x4700
	s_addc_u32 s11, s27, 0
	s_add_u32 s12, s26, 0x4800
	s_addc_u32 s13, s27, 0
	s_add_u32 s14, s26, 0x4900
	s_addc_u32 s15, s27, 0
	s_add_u32 s16, s26, 0x4a00
	s_addc_u32 s17, s27, 0
	s_add_u32 s18, s26, 0x4b00
	s_addc_u32 s19, s27, 0
	s_add_u32 s20, s26, 0x4c00
	s_addc_u32 s21, s27, 0
	s_add_u32 s22, s26, 0x4d00
	s_addc_u32 s23, s27, 0
	s_add_u32 s30, s26, 0x4e00
	s_addc_u32 s31, s27, 0
	s_add_u32 s34, s26, 0x4f00
	s_addc_u32 s35, s27, 0
	v_readlane_b32 s40, v255, 0
	s_add_u32 s36, s26, 0x5000
	v_readlane_b32 s41, v255, 1
	s_addc_u32 s37, s27, 0
	s_load_dwordx2 s[28:29], s[40:41], 0x4
	s_add_u32 s38, s26, 0x5100
	s_addc_u32 s39, s27, 0
	s_add_u32 s44, s26, 0x5200
	s_addc_u32 s45, s27, 0
	s_add_u32 s52, s26, 0x5300
	s_waitcnt lgkmcnt(0)
	s_mul_i32 s25, s28, s33
	s_addc_u32 s53, s27, 0
	s_mul_i32 s25, s25, s29
	s_mov_b32 s28, 1
	v_mov_b32_e32 v17, 0
	s_branch .LBB0_333

.LBB0_1590:
	s_cmp_lt_i32 s90, 10
	s_cselect_b64 s[0:1], -1, 0
	s_cmp_gt_i32 s91, 9
	s_cselect_b64 s[2:3], -1, 0
	s_and_b64 s[0:1], s[0:1], s[2:3]
	s_andn2_b64 vcc, exec, s[0:1]
	s_cbranch_vccnz .LBB0_1685
	s_lshl_b32 s0, s82, 3
	s_add_i32 s0, s0, s83
	s_cmpk_gt_i32 s0, 0x41ff
	s_waitcnt vmcnt(0)
	v_mbcnt_lo_u32_b32 v18, -1, 0
	v_mbcnt_hi_u32_b32 v18, -1, v18
	s_cbranch_scc1 .LBB0_1631
	s_waitcnt lgkmcnt(0)
	s_mov_b32 s4, s0
	v_mbcnt_lo_u32_b32 v1, -1, 0
	v_mbcnt_hi_u32_b32 v1, -1, v1
	v_lshlrev_b32_e32 v19, 4, v1
	v_lshlrev_b32_e32 v1, 3, v1
	s_add_u32 s14, s66, 0x3000
	s_addc_u32 s15, s67, 0
	global_load_dwordx4 v[2:5], v19, s[14:15] offset:0
	global_load_dwordx4 v[6:9], v19, s[14:15] offset:1024
	global_load_dwordx4 v[10:13], v19, s[14:15] offset:2048
	global_load_dwordx4 v[14:17], v19, s[14:15] offset:3072
	s_add_u32 s14, s66, 0x4000
	s_addc_u32 s15, s67, 0
	global_load_dwordx4 v[20:23], v19, s[14:15] offset:0
	global_load_dwordx4 v[24:27], v19, s[14:15] offset:1024
	global_load_dwordx4 v[28:31], v19, s[14:15] offset:2048
	global_load_dwordx4 v[32:35], v19, s[14:15] offset:3072
	s_mov_b32 s34, 0xffff0000
	s_mov_b32 s35, 0xf800000
	v_mov_b32_e32 v69, 0x358637bd
	v_mov_b32_e32 v80, 0x260
	s_lshl_b32 s23, s33, 3
	s_lshl_b32 s20, s33, 14
	s_lshl_b32 s21, s33, 15
	s_mul_i32 s22, s23, 3
	s_sub_i32 s22, 0x4000, s22
	s_mov_b32 s5, s4
	s_lshl_b32 s36, s4, 11
	s_lshl_b32 s37, s4, 12
	s_add_u32 s6, s26, 0xae00000
	s_addc_u32 s7, s27, 0
	s_add_u32 s6, s6, s36
	s_addc_u32 s7, s7, 0
	s_add_u32 s8, s26, 0xf000000
	s_addc_u32 s9, s27, 0
	s_add_u32 s8, s8, s36
	s_addc_u32 s9, s9, 0
	s_add_u32 s10, s26, 0xf000000
	s_addc_u32 s11, s27, 0
	s_add_u32 s10, s10, s36
	s_addc_u32 s11, s11, 0
	s_add_u32 s12, s26, 0x3000000
	s_addc_u32 s13, s27, 0
	s_add_u32 s12, s12, s36
	s_addc_u32 s13, s13, 0
.Lrw9_batch:
	s_cmp_lt_i32 s5, s22
	s_cbranch_scc0 .Lrw9_single
	global_load_dwordx2 v[84:85], v1, s[6:7] offset:0
	global_load_dwordx2 v[86:87], v1, s[6:7] offset:512
	global_load_dwordx2 v[88:89], v1, s[6:7] offset:1024
	global_load_dwordx2 v[90:91], v1, s[6:7] offset:1536
	global_load_dwordx2 v[92:93], v1, s[8:9] offset:0
	global_load_dwordx2 v[94:95], v1, s[8:9] offset:512
	global_load_dwordx2 v[96:97], v1, s[8:9] offset:1024
	global_load_dwordx2 v[98:99], v1, s[8:9] offset:1536
	s_add_u32 s6, s6, s20
	s_addc_u32 s7, s7, 0
	s_add_u32 s8, s8, s20
	s_addc_u32 s9, s9, 0
	global_load_dwordx2 v[100:101], v1, s[6:7] offset:0
	global_load_dwordx2 v[102:103], v1, s[6:7] offset:512
	global_load_dwordx2 v[104:105], v1, s[6:7] offset:1024
	global_load_dwordx2 v[106:107], v1, s[6:7] offset:1536
	global_load_dwordx2 v[108:109], v1, s[8:9] offset:0
	global_load_dwordx2 v[110:111], v1, s[8:9] offset:512
	global_load_dwordx2 v[112:113], v1, s[8:9] offset:1024
	global_load_dwordx2 v[114:115], v1, s[8:9] offset:1536
	s_add_u32 s6, s6, s20
	s_addc_u32 s7, s7, 0
	s_add_u32 s8, s8, s20
	s_addc_u32 s9, s9, 0
	global_load_dwordx2 v[116:117], v1, s[6:7] offset:0
	global_load_dwordx2 v[118:119], v1, s[6:7] offset:512
	global_load_dwordx2 v[120:121], v1, s[6:7] offset:1024
	global_load_dwordx2 v[122:123], v1, s[6:7] offset:1536
	global_load_dwordx2 v[124:125], v1, s[8:9] offset:0
	global_load_dwordx2 v[126:127], v1, s[8:9] offset:512
	global_load_dwordx2 v[128:129], v1, s[8:9] offset:1024
	global_load_dwordx2 v[130:131], v1, s[8:9] offset:1536
	s_add_u32 s6, s6, s20
	s_addc_u32 s7, s7, 0
	s_add_u32 s8, s8, s20
	s_addc_u32 s9, s9, 0
	global_load_dwordx2 v[132:133], v1, s[6:7] offset:0
	global_load_dwordx2 v[134:135], v1, s[6:7] offset:512
	global_load_dwordx2 v[136:137], v1, s[6:7] offset:1024
	global_load_dwordx2 v[138:139], v1, s[6:7] offset:1536
	global_load_dwordx2 v[140:141], v1, s[8:9] offset:0
	global_load_dwordx2 v[142:143], v1, s[8:9] offset:512
	global_load_dwordx2 v[144:145], v1, s[8:9] offset:1024
	global_load_dwordx2 v[146:147], v1, s[8:9] offset:1536
	s_add_u32 s6, s6, s20
	s_addc_u32 s7, s7, 0
	s_add_u32 s8, s8, s20
	s_addc_u32 s9, s9, 0
	s_waitcnt vmcnt(24)
	v_lshlrev_b32_e32 v36, 16, v84
	v_and_b32_e32 v37, s34, v84
	v_lshlrev_b32_e32 v38, 16, v85
	v_and_b32_e32 v39, s34, v85
	v_lshlrev_b32_e32 v40, 16, v86
	v_and_b32_e32 v41, s34, v86
	v_lshlrev_b32_e32 v42, 16, v87
	v_and_b32_e32 v43, s34, v87
	v_lshlrev_b32_e32 v44, 16, v88
	v_and_b32_e32 v45, s34, v88
	v_lshlrev_b32_e32 v46, 16, v89
	v_and_b32_e32 v47, s34, v89
	v_lshlrev_b32_e32 v48, 16, v90
	v_and_b32_e32 v49, s34, v90
	v_lshlrev_b32_e32 v50, 16, v91
	v_and_b32_e32 v51, s34, v91
	v_pk_mul_f32 v[70:71], v[36:37], v[36:37]
	v_pk_mul_f32 v[72:73], v[38:39], v[38:39]
	v_pk_fma_f32 v[70:71], v[40:41], v[40:41], v[70:71]
	v_pk_fma_f32 v[72:73], v[42:43], v[42:43], v[72:73]
	v_pk_fma_f32 v[70:71], v[44:45], v[44:45], v[70:71]
	v_pk_fma_f32 v[72:73], v[46:47], v[46:47], v[72:73]
	v_pk_fma_f32 v[70:71], v[48:49], v[48:49], v[70:71]
	v_pk_fma_f32 v[72:73], v[50:51], v[50:51], v[72:73]
	v_pk_add_f32 v[70:71], v[70:71], v[72:73]
	s_nop 0
	v_add_f32_e32 v70, v70, v71
	s_nop 1
	v_add_f32_dpp v70, v70, v70 quad_perm:[1,0,3,2] row_mask:0xf bank_mask:0xf bound_ctrl:1
	s_nop 1
	v_add_f32_dpp v70, v70, v70 quad_perm:[2,3,0,1] row_mask:0xf bank_mask:0xf bound_ctrl:1
	s_nop 1
	v_add_f32_dpp v70, v70, v70 row_half_mirror row_mask:0xf bank_mask:0xf bound_ctrl:1
	s_nop 1
	v_add_f32_dpp v70, v70, v70 row_mirror row_mask:0xf bank_mask:0xf bound_ctrl:1
	v_mov_b32_e32 v71, v70
	s_nop 1
	v_permlane16_swap_b32_e32 v70, v71
	v_add_f32_e32 v70, v70, v71
	v_mov_b32_e32 v71, v70
	s_nop 1
	v_permlane32_swap_b32_e32 v70, v71
	v_add_f32_e32 v70, v70, v71
	v_fmamk_f32 v70, v70, 0x3a800000, v69
	v_mul_f32_e32 v71, 0x4f800000, v70
	v_cmp_gt_f32_e32 vcc, s35, v70
	s_nop 1
	v_cndmask_b32_e32 v70, v70, v71, vcc
	v_sqrt_f32_e32 v71, v70
	s_nop 1
	v_add_u32_e32 v72, -1, v71
	v_add_u32_e32 v73, 1, v71
	v_fma_f32 v74, -v72, v71, v70
	v_fma_f32 v75, -v73, v71, v70
	v_cmp_ge_f32_e64 s[0:1], 0, v74
	s_nop 1
	v_cndmask_b32_e64 v71, v71, v72, s[0:1]
	v_cmp_lt_f32_e64 s[0:1], 0, v75
	s_nop 1
	v_cndmask_b32_e64 v71, v71, v73, s[0:1]
	v_mul_f32_e32 v72, 0x37800000, v71
	s_nop 0
	v_cndmask_b32_e32 v71, v71, v72, vcc
	v_cmp_class_f32_e32 vcc, v70, v80
	s_nop 1
	v_cndmask_b32_e32 v70, v71, v70, vcc
	v_div_scale_f32 v71, s[0:1], v70, v70, 1.0
	v_rcp_f32_e32 v72, v71
	v_div_scale_f32 v73, vcc, 1.0, v70, 1.0
	v_fma_f32 v74, -v71, v72, 1.0
	v_fmac_f32_e32 v72, v74, v72
	v_mul_f32_e32 v74, v73, v72
	v_fma_f32 v75, -v71, v74, v73
	v_fmac_f32_e32 v74, v75, v72
	v_fma_f32 v71, -v71, v74, v73
	v_div_fmas_f32 v71, v71, v72, v74
	v_div_fixup_f32 v76, v71, v70, 1.0
	v_pk_mul_f32 v[36:37], v[36:37], v[76:77] op_sel_hi:[1,0]
	v_pk_mul_f32 v[38:39], v[38:39], v[76:77] op_sel_hi:[1,0]
	v_pk_mul_f32 v[40:41], v[40:41], v[76:77] op_sel_hi:[1,0]
	v_pk_mul_f32 v[42:43], v[42:43], v[76:77] op_sel_hi:[1,0]
	v_pk_mul_f32 v[44:45], v[44:45], v[76:77] op_sel_hi:[1,0]
	v_pk_mul_f32 v[46:47], v[46:47], v[76:77] op_sel_hi:[1,0]
	v_pk_mul_f32 v[48:49], v[48:49], v[76:77] op_sel_hi:[1,0]
	v_pk_mul_f32 v[50:51], v[50:51], v[76:77] op_sel_hi:[1,0]
	v_lshlrev_b32_e32 v52, 16, v92
	v_and_b32_e32 v53, s34, v92
	v_lshlrev_b32_e32 v54, 16, v93
	v_and_b32_e32 v55, s34, v93
	v_lshlrev_b32_e32 v56, 16, v94
	v_and_b32_e32 v57, s34, v94
	v_lshlrev_b32_e32 v58, 16, v95
	v_and_b32_e32 v59, s34, v95
	v_lshlrev_b32_e32 v60, 16, v96
	v_and_b32_e32 v61, s34, v96
	v_lshlrev_b32_e32 v62, 16, v97
	v_and_b32_e32 v63, s34, v97
	v_lshlrev_b32_e32 v64, 16, v98
	v_and_b32_e32 v65, s34, v98
	v_lshlrev_b32_e32 v66, 16, v99
	v_and_b32_e32 v67, s34, v99
	v_pk_fma_f32 v[52:53], v[36:37], v[2:3], v[52:53]
	v_pk_fma_f32 v[54:55], v[38:39], v[4:5], v[54:55]
	v_pk_fma_f32 v[56:57], v[40:41], v[6:7], v[56:57]
	v_pk_fma_f32 v[58:59], v[42:43], v[8:9], v[58:59]
	v_pk_fma_f32 v[60:61], v[44:45], v[10:11], v[60:61]
	v_pk_fma_f32 v[62:63], v[46:47], v[12:13], v[62:63]
	v_pk_fma_f32 v[64:65], v[48:49], v[14:15], v[64:65]
	v_pk_fma_f32 v[66:67], v[50:51], v[16:17], v[66:67]
	v_cvt_pk_bf16_f32 v148, v52, v53
	v_cvt_pk_bf16_f32 v149, v54, v55
	v_cvt_pk_bf16_f32 v150, v56, v57
	v_cvt_pk_bf16_f32 v151, v58, v59
	v_cvt_pk_bf16_f32 v152, v60, v61
	v_cvt_pk_bf16_f32 v153, v62, v63
	v_cvt_pk_bf16_f32 v154, v64, v65
	v_cvt_pk_bf16_f32 v155, v66, v67
	global_store_dwordx2 v1, v[148:149], s[10:11] offset:0
	global_store_dwordx2 v1, v[150:151], s[10:11] offset:512
	global_store_dwordx2 v1, v[152:153], s[10:11] offset:1024
	global_store_dwordx2 v1, v[154:155], s[10:11] offset:1536
	v_lshlrev_b32_e32 v52, 16, v148
	v_and_b32_e32 v53, s34, v148
	v_lshlrev_b32_e32 v54, 16, v149
	v_and_b32_e32 v55, s34, v149
	v_lshlrev_b32_e32 v56, 16, v150
	v_and_b32_e32 v57, s34, v150
	v_lshlrev_b32_e32 v58, 16, v151
	v_and_b32_e32 v59, s34, v151
	v_lshlrev_b32_e32 v60, 16, v152
	v_and_b32_e32 v61, s34, v152
	v_lshlrev_b32_e32 v62, 16, v153
	v_and_b32_e32 v63, s34, v153
	v_lshlrev_b32_e32 v64, 16, v154
	v_and_b32_e32 v65, s34, v154
	v_lshlrev_b32_e32 v66, 16, v155
	v_and_b32_e32 v67, s34, v155
	v_pk_mul_f32 v[70:71], v[52:53], v[52:53]
	v_pk_mul_f32 v[72:73], v[54:55], v[54:55]
	v_pk_fma_f32 v[70:71], v[56:57], v[56:57], v[70:71]
	v_pk_fma_f32 v[72:73], v[58:59], v[58:59], v[72:73]
	v_pk_fma_f32 v[70:71], v[60:61], v[60:61], v[70:71]
	v_pk_fma_f32 v[72:73], v[62:63], v[62:63], v[72:73]
	v_pk_fma_f32 v[70:71], v[64:65], v[64:65], v[70:71]
	v_pk_fma_f32 v[72:73], v[66:67], v[66:67], v[72:73]
	v_pk_add_f32 v[70:71], v[70:71], v[72:73]
	s_nop 0
	v_add_f32_e32 v70, v70, v71
	s_nop 1
	v_add_f32_dpp v70, v70, v70 quad_perm:[1,0,3,2] row_mask:0xf bank_mask:0xf bound_ctrl:1
	s_nop 1
	v_add_f32_dpp v70, v70, v70 quad_perm:[2,3,0,1] row_mask:0xf bank_mask:0xf bound_ctrl:1
	s_nop 1
	v_add_f32_dpp v70, v70, v70 row_half_mirror row_mask:0xf bank_mask:0xf bound_ctrl:1
	s_nop 1
	v_add_f32_dpp v70, v70, v70 row_mirror row_mask:0xf bank_mask:0xf bound_ctrl:1
	v_mov_b32_e32 v71, v70
	s_nop 1
	v_permlane16_swap_b32_e32 v70, v71
	v_add_f32_e32 v70, v70, v71
	v_mov_b32_e32 v71, v70
	s_nop 1
	v_permlane32_swap_b32_e32 v70, v71
	v_add_f32_e32 v70, v70, v71
	v_fmamk_f32 v70, v70, 0x3a800000, v69
	v_mul_f32_e32 v71, 0x4f800000, v70
	v_cmp_gt_f32_e32 vcc, s35, v70
	s_nop 1
	v_cndmask_b32_e32 v70, v70, v71, vcc
	v_sqrt_f32_e32 v71, v70
	s_nop 1
	v_add_u32_e32 v72, -1, v71
	v_add_u32_e32 v73, 1, v71
	v_fma_f32 v74, -v72, v71, v70
	v_fma_f32 v75, -v73, v71, v70
	v_cmp_ge_f32_e64 s[0:1], 0, v74
	s_nop 1
	v_cndmask_b32_e64 v71, v71, v72, s[0:1]
	v_cmp_lt_f32_e64 s[0:1], 0, v75
	s_nop 1
	v_cndmask_b32_e64 v71, v71, v73, s[0:1]
	v_mul_f32_e32 v72, 0x37800000, v71
	s_nop 0
	v_cndmask_b32_e32 v71, v71, v72, vcc
	v_cmp_class_f32_e32 vcc, v70, v80
	s_nop 1
	v_cndmask_b32_e32 v70, v71, v70, vcc
	v_div_scale_f32 v71, s[0:1], v70, v70, 1.0
	v_rcp_f32_e32 v72, v71
	v_div_scale_f32 v73, vcc, 1.0, v70, 1.0
	v_fma_f32 v74, -v71, v72, 1.0
	v_fmac_f32_e32 v72, v74, v72
	v_mul_f32_e32 v74, v73, v72
	v_fma_f32 v75, -v71, v74, v73
	v_fmac_f32_e32 v74, v75, v72
	v_fma_f32 v71, -v71, v74, v73
	v_div_fmas_f32 v71, v71, v72, v74
	v_div_fixup_f32 v76, v71, v70, 1.0
	v_pk_mul_f32 v[52:53], v[52:53], v[76:77] op_sel_hi:[1,0]
	v_pk_mul_f32 v[54:55], v[54:55], v[76:77] op_sel_hi:[1,0]
	v_pk_mul_f32 v[56:57], v[56:57], v[76:77] op_sel_hi:[1,0]
	v_pk_mul_f32 v[58:59], v[58:59], v[76:77] op_sel_hi:[1,0]
	v_pk_mul_f32 v[60:61], v[60:61], v[76:77] op_sel_hi:[1,0]
	v_pk_mul_f32 v[62:63], v[62:63], v[76:77] op_sel_hi:[1,0]
	v_pk_mul_f32 v[64:65], v[64:65], v[76:77] op_sel_hi:[1,0]
	v_pk_mul_f32 v[66:67], v[66:67], v[76:77] op_sel_hi:[1,0]
	v_pk_mul_f32 v[52:53], v[52:53], v[20:21]
	v_pk_mul_f32 v[54:55], v[54:55], v[22:23]
	v_pk_mul_f32 v[56:57], v[56:57], v[24:25]
	v_pk_mul_f32 v[58:59], v[58:59], v[26:27]
	v_pk_mul_f32 v[60:61], v[60:61], v[28:29]
	v_pk_mul_f32 v[62:63], v[62:63], v[30:31]
	v_pk_mul_f32 v[64:65], v[64:65], v[32:33]
	v_pk_mul_f32 v[66:67], v[66:67], v[34:35]
	v_cvt_pk_bf16_f32 v148, v52, v53
	v_cvt_pk_bf16_f32 v149, v54, v55
	v_cvt_pk_bf16_f32 v150, v56, v57
	v_cvt_pk_bf16_f32 v151, v58, v59
	v_cvt_pk_bf16_f32 v152, v60, v61
	v_cvt_pk_bf16_f32 v153, v62, v63
	v_cvt_pk_bf16_f32 v154, v64, v65
	v_cvt_pk_bf16_f32 v155, v66, v67
	global_store_dwordx2 v1, v[148:149], s[12:13] offset:0
	global_store_dwordx2 v1, v[150:151], s[12:13] offset:512
	global_store_dwordx2 v1, v[152:153], s[12:13] offset:1024
	global_store_dwordx2 v1, v[154:155], s[12:13] offset:1536
	s_add_u32 s10, s10, s20
	s_addc_u32 s11, s11, 0
	s_add_u32 s12, s12, s20
	s_addc_u32 s13, s13, 0
	s_waitcnt vmcnt(24)
	v_lshlrev_b32_e32 v36, 16, v100
	v_and_b32_e32 v37, s34, v100
	v_lshlrev_b32_e32 v38, 16, v101
	v_and_b32_e32 v39, s34, v101
	v_lshlrev_b32_e32 v40, 16, v102
	v_and_b32_e32 v41, s34, v102
	v_lshlrev_b32_e32 v42, 16, v103
	v_and_b32_e32 v43, s34, v103
	v_lshlrev_b32_e32 v44, 16, v104
	v_and_b32_e32 v45, s34, v104
	v_lshlrev_b32_e32 v46, 16, v105
	v_and_b32_e32 v47, s34, v105
	v_lshlrev_b32_e32 v48, 16, v106
	v_and_b32_e32 v49, s34, v106
	v_lshlrev_b32_e32 v50, 16, v107
	v_and_b32_e32 v51, s34, v107
	v_pk_mul_f32 v[70:71], v[36:37], v[36:37]
	v_pk_mul_f32 v[72:73], v[38:39], v[38:39]
	v_pk_fma_f32 v[70:71], v[40:41], v[40:41], v[70:71]
	v_pk_fma_f32 v[72:73], v[42:43], v[42:43], v[72:73]
	v_pk_fma_f32 v[70:71], v[44:45], v[44:45], v[70:71]
	v_pk_fma_f32 v[72:73], v[46:47], v[46:47], v[72:73]
	v_pk_fma_f32 v[70:71], v[48:49], v[48:49], v[70:71]
	v_pk_fma_f32 v[72:73], v[50:51], v[50:51], v[72:73]
	v_pk_add_f32 v[70:71], v[70:71], v[72:73]
	s_nop 0
	v_add_f32_e32 v70, v70, v71
	s_nop 1
	v_add_f32_dpp v70, v70, v70 quad_perm:[1,0,3,2] row_mask:0xf bank_mask:0xf bound_ctrl:1
	s_nop 1
	v_add_f32_dpp v70, v70, v70 quad_perm:[2,3,0,1] row_mask:0xf bank_mask:0xf bound_ctrl:1
	s_nop 1
	v_add_f32_dpp v70, v70, v70 row_half_mirror row_mask:0xf bank_mask:0xf bound_ctrl:1
	s_nop 1
	v_add_f32_dpp v70, v70, v70 row_mirror row_mask:0xf bank_mask:0xf bound_ctrl:1
	v_mov_b32_e32 v71, v70
	s_nop 1
	v_permlane16_swap_b32_e32 v70, v71
	v_add_f32_e32 v70, v70, v71
	v_mov_b32_e32 v71, v70
	s_nop 1
	v_permlane32_swap_b32_e32 v70, v71
	v_add_f32_e32 v70, v70, v71
	v_fmamk_f32 v70, v70, 0x3a800000, v69
	v_mul_f32_e32 v71, 0x4f800000, v70
	v_cmp_gt_f32_e32 vcc, s35, v70
	s_nop 1
	v_cndmask_b32_e32 v70, v70, v71, vcc
	v_sqrt_f32_e32 v71, v70
	s_nop 1
	v_add_u32_e32 v72, -1, v71
	v_add_u32_e32 v73, 1, v71
	v_fma_f32 v74, -v72, v71, v70
	v_fma_f32 v75, -v73, v71, v70
	v_cmp_ge_f32_e64 s[0:1], 0, v74
	s_nop 1
	v_cndmask_b32_e64 v71, v71, v72, s[0:1]
	v_cmp_lt_f32_e64 s[0:1], 0, v75
	s_nop 1
	v_cndmask_b32_e64 v71, v71, v73, s[0:1]
	v_mul_f32_e32 v72, 0x37800000, v71
	s_nop 0
	v_cndmask_b32_e32 v71, v71, v72, vcc
	v_cmp_class_f32_e32 vcc, v70, v80
	s_nop 1
	v_cndmask_b32_e32 v70, v71, v70, vcc
	v_div_scale_f32 v71, s[0:1], v70, v70, 1.0
	v_rcp_f32_e32 v72, v71
	v_div_scale_f32 v73, vcc, 1.0, v70, 1.0
	v_fma_f32 v74, -v71, v72, 1.0
	v_fmac_f32_e32 v72, v74, v72
	v_mul_f32_e32 v74, v73, v72
	v_fma_f32 v75, -v71, v74, v73
	v_fmac_f32_e32 v74, v75, v72
	v_fma_f32 v71, -v71, v74, v73
	v_div_fmas_f32 v71, v71, v72, v74
	v_div_fixup_f32 v76, v71, v70, 1.0
	v_pk_mul_f32 v[36:37], v[36:37], v[76:77] op_sel_hi:[1,0]
	v_pk_mul_f32 v[38:39], v[38:39], v[76:77] op_sel_hi:[1,0]
	v_pk_mul_f32 v[40:41], v[40:41], v[76:77] op_sel_hi:[1,0]
	v_pk_mul_f32 v[42:43], v[42:43], v[76:77] op_sel_hi:[1,0]
	v_pk_mul_f32 v[44:45], v[44:45], v[76:77] op_sel_hi:[1,0]
	v_pk_mul_f32 v[46:47], v[46:47], v[76:77] op_sel_hi:[1,0]
	v_pk_mul_f32 v[48:49], v[48:49], v[76:77] op_sel_hi:[1,0]
	v_pk_mul_f32 v[50:51], v[50:51], v[76:77] op_sel_hi:[1,0]
	v_lshlrev_b32_e32 v52, 16, v108
	v_and_b32_e32 v53, s34, v108
	v_lshlrev_b32_e32 v54, 16, v109
	v_and_b32_e32 v55, s34, v109
	v_lshlrev_b32_e32 v56, 16, v110
	v_and_b32_e32 v57, s34, v110
	v_lshlrev_b32_e32 v58, 16, v111
	v_and_b32_e32 v59, s34, v111
	v_lshlrev_b32_e32 v60, 16, v112
	v_and_b32_e32 v61, s34, v112
	v_lshlrev_b32_e32 v62, 16, v113
	v_and_b32_e32 v63, s34, v113
	v_lshlrev_b32_e32 v64, 16, v114
	v_and_b32_e32 v65, s34, v114
	v_lshlrev_b32_e32 v66, 16, v115
	v_and_b32_e32 v67, s34, v115
	v_pk_fma_f32 v[52:53], v[36:37], v[2:3], v[52:53]
	v_pk_fma_f32 v[54:55], v[38:39], v[4:5], v[54:55]
	v_pk_fma_f32 v[56:57], v[40:41], v[6:7], v[56:57]
	v_pk_fma_f32 v[58:59], v[42:43], v[8:9], v[58:59]
	v_pk_fma_f32 v[60:61], v[44:45], v[10:11], v[60:61]
	v_pk_fma_f32 v[62:63], v[46:47], v[12:13], v[62:63]
	v_pk_fma_f32 v[64:65], v[48:49], v[14:15], v[64:65]
	v_pk_fma_f32 v[66:67], v[50:51], v[16:17], v[66:67]
	v_cvt_pk_bf16_f32 v148, v52, v53
	v_cvt_pk_bf16_f32 v149, v54, v55
	v_cvt_pk_bf16_f32 v150, v56, v57
	v_cvt_pk_bf16_f32 v151, v58, v59
	v_cvt_pk_bf16_f32 v152, v60, v61
	v_cvt_pk_bf16_f32 v153, v62, v63
	v_cvt_pk_bf16_f32 v154, v64, v65
	v_cvt_pk_bf16_f32 v155, v66, v67
	global_store_dwordx2 v1, v[148:149], s[10:11] offset:0
	global_store_dwordx2 v1, v[150:151], s[10:11] offset:512
	global_store_dwordx2 v1, v[152:153], s[10:11] offset:1024
	global_store_dwordx2 v1, v[154:155], s[10:11] offset:1536
	v_lshlrev_b32_e32 v52, 16, v148
	v_and_b32_e32 v53, s34, v148
	v_lshlrev_b32_e32 v54, 16, v149
	v_and_b32_e32 v55, s34, v149
	v_lshlrev_b32_e32 v56, 16, v150
	v_and_b32_e32 v57, s34, v150
	v_lshlrev_b32_e32 v58, 16, v151
	v_and_b32_e32 v59, s34, v151
	v_lshlrev_b32_e32 v60, 16, v152
	v_and_b32_e32 v61, s34, v152
	v_lshlrev_b32_e32 v62, 16, v153
	v_and_b32_e32 v63, s34, v153
	v_lshlrev_b32_e32 v64, 16, v154
	v_and_b32_e32 v65, s34, v154
	v_lshlrev_b32_e32 v66, 16, v155
	v_and_b32_e32 v67, s34, v155
	v_pk_mul_f32 v[70:71], v[52:53], v[52:53]
	v_pk_mul_f32 v[72:73], v[54:55], v[54:55]
	v_pk_fma_f32 v[70:71], v[56:57], v[56:57], v[70:71]
	v_pk_fma_f32 v[72:73], v[58:59], v[58:59], v[72:73]
	v_pk_fma_f32 v[70:71], v[60:61], v[60:61], v[70:71]
	v_pk_fma_f32 v[72:73], v[62:63], v[62:63], v[72:73]
	v_pk_fma_f32 v[70:71], v[64:65], v[64:65], v[70:71]
	v_pk_fma_f32 v[72:73], v[66:67], v[66:67], v[72:73]
	v_pk_add_f32 v[70:71], v[70:71], v[72:73]
	s_nop 0
	v_add_f32_e32 v70, v70, v71
	s_nop 1
	v_add_f32_dpp v70, v70, v70 quad_perm:[1,0,3,2] row_mask:0xf bank_mask:0xf bound_ctrl:1
	s_nop 1
	v_add_f32_dpp v70, v70, v70 quad_perm:[2,3,0,1] row_mask:0xf bank_mask:0xf bound_ctrl:1
	s_nop 1
	v_add_f32_dpp v70, v70, v70 row_half_mirror row_mask:0xf bank_mask:0xf bound_ctrl:1
	s_nop 1
	v_add_f32_dpp v70, v70, v70 row_mirror row_mask:0xf bank_mask:0xf bound_ctrl:1
	v_mov_b32_e32 v71, v70
	s_nop 1
	v_permlane16_swap_b32_e32 v70, v71
	v_add_f32_e32 v70, v70, v71
	v_mov_b32_e32 v71, v70
	s_nop 1
	v_permlane32_swap_b32_e32 v70, v71
	v_add_f32_e32 v70, v70, v71
	v_fmamk_f32 v70, v70, 0x3a800000, v69
	v_mul_f32_e32 v71, 0x4f800000, v70
	v_cmp_gt_f32_e32 vcc, s35, v70
	s_nop 1
	v_cndmask_b32_e32 v70, v70, v71, vcc
	v_sqrt_f32_e32 v71, v70
	s_nop 1
	v_add_u32_e32 v72, -1, v71
	v_add_u32_e32 v73, 1, v71
	v_fma_f32 v74, -v72, v71, v70
	v_fma_f32 v75, -v73, v71, v70
	v_cmp_ge_f32_e64 s[0:1], 0, v74
	s_nop 1
	v_cndmask_b32_e64 v71, v71, v72, s[0:1]
	v_cmp_lt_f32_e64 s[0:1], 0, v75
	s_nop 1
	v_cndmask_b32_e64 v71, v71, v73, s[0:1]
	v_mul_f32_e32 v72, 0x37800000, v71
	s_nop 0
	v_cndmask_b32_e32 v71, v71, v72, vcc
	v_cmp_class_f32_e32 vcc, v70, v80
	s_nop 1
	v_cndmask_b32_e32 v70, v71, v70, vcc
	v_div_scale_f32 v71, s[0:1], v70, v70, 1.0
	v_rcp_f32_e32 v72, v71
	v_div_scale_f32 v73, vcc, 1.0, v70, 1.0
	v_fma_f32 v74, -v71, v72, 1.0
	v_fmac_f32_e32 v72, v74, v72
	v_mul_f32_e32 v74, v73, v72
	v_fma_f32 v75, -v71, v74, v73
	v_fmac_f32_e32 v74, v75, v72
	v_fma_f32 v71, -v71, v74, v73
	v_div_fmas_f32 v71, v71, v72, v74
	v_div_fixup_f32 v76, v71, v70, 1.0
	v_pk_mul_f32 v[52:53], v[52:53], v[76:77] op_sel_hi:[1,0]
	v_pk_mul_f32 v[54:55], v[54:55], v[76:77] op_sel_hi:[1,0]
	v_pk_mul_f32 v[56:57], v[56:57], v[76:77] op_sel_hi:[1,0]
	v_pk_mul_f32 v[58:59], v[58:59], v[76:77] op_sel_hi:[1,0]
	v_pk_mul_f32 v[60:61], v[60:61], v[76:77] op_sel_hi:[1,0]
	v_pk_mul_f32 v[62:63], v[62:63], v[76:77] op_sel_hi:[1,0]
	v_pk_mul_f32 v[64:65], v[64:65], v[76:77] op_sel_hi:[1,0]
	v_pk_mul_f32 v[66:67], v[66:67], v[76:77] op_sel_hi:[1,0]
	v_pk_mul_f32 v[52:53], v[52:53], v[20:21]
	v_pk_mul_f32 v[54:55], v[54:55], v[22:23]
	v_pk_mul_f32 v[56:57], v[56:57], v[24:25]
	v_pk_mul_f32 v[58:59], v[58:59], v[26:27]
	v_pk_mul_f32 v[60:61], v[60:61], v[28:29]
	v_pk_mul_f32 v[62:63], v[62:63], v[30:31]
	v_pk_mul_f32 v[64:65], v[64:65], v[32:33]
	v_pk_mul_f32 v[66:67], v[66:67], v[34:35]
	v_cvt_pk_bf16_f32 v148, v52, v53
	v_cvt_pk_bf16_f32 v149, v54, v55
	v_cvt_pk_bf16_f32 v150, v56, v57
	v_cvt_pk_bf16_f32 v151, v58, v59
	v_cvt_pk_bf16_f32 v152, v60, v61
	v_cvt_pk_bf16_f32 v153, v62, v63
	v_cvt_pk_bf16_f32 v154, v64, v65
	v_cvt_pk_bf16_f32 v155, v66, v67
	global_store_dwordx2 v1, v[148:149], s[12:13] offset:0
	global_store_dwordx2 v1, v[150:151], s[12:13] offset:512
	global_store_dwordx2 v1, v[152:153], s[12:13] offset:1024
	global_store_dwordx2 v1, v[154:155], s[12:13] offset:1536
	s_add_u32 s10, s10, s20
	s_addc_u32 s11, s11, 0
	s_add_u32 s12, s12, s20
	s_addc_u32 s13, s13, 0
	s_waitcnt vmcnt(24)
	v_lshlrev_b32_e32 v36, 16, v116
	v_and_b32_e32 v37, s34, v116
	v_lshlrev_b32_e32 v38, 16, v117
	v_and_b32_e32 v39, s34, v117
	v_lshlrev_b32_e32 v40, 16, v118
	v_and_b32_e32 v41, s34, v118
	v_lshlrev_b32_e32 v42, 16, v119
	v_and_b32_e32 v43, s34, v119
	v_lshlrev_b32_e32 v44, 16, v120
	v_and_b32_e32 v45, s34, v120
	v_lshlrev_b32_e32 v46, 16, v121
	v_and_b32_e32 v47, s34, v121
	v_lshlrev_b32_e32 v48, 16, v122
	v_and_b32_e32 v49, s34, v122
	v_lshlrev_b32_e32 v50, 16, v123
	v_and_b32_e32 v51, s34, v123
	v_pk_mul_f32 v[70:71], v[36:37], v[36:37]
	v_pk_mul_f32 v[72:73], v[38:39], v[38:39]
	v_pk_fma_f32 v[70:71], v[40:41], v[40:41], v[70:71]
	v_pk_fma_f32 v[72:73], v[42:43], v[42:43], v[72:73]
	v_pk_fma_f32 v[70:71], v[44:45], v[44:45], v[70:71]
	v_pk_fma_f32 v[72:73], v[46:47], v[46:47], v[72:73]
	v_pk_fma_f32 v[70:71], v[48:49], v[48:49], v[70:71]
	v_pk_fma_f32 v[72:73], v[50:51], v[50:51], v[72:73]
	v_pk_add_f32 v[70:71], v[70:71], v[72:73]
	s_nop 0
	v_add_f32_e32 v70, v70, v71
	s_nop 1
	v_add_f32_dpp v70, v70, v70 quad_perm:[1,0,3,2] row_mask:0xf bank_mask:0xf bound_ctrl:1
	s_nop 1
	v_add_f32_dpp v70, v70, v70 quad_perm:[2,3,0,1] row_mask:0xf bank_mask:0xf bound_ctrl:1
	s_nop 1
	v_add_f32_dpp v70, v70, v70 row_half_mirror row_mask:0xf bank_mask:0xf bound_ctrl:1
	s_nop 1
	v_add_f32_dpp v70, v70, v70 row_mirror row_mask:0xf bank_mask:0xf bound_ctrl:1
	v_mov_b32_e32 v71, v70
	s_nop 1
	v_permlane16_swap_b32_e32 v70, v71
	v_add_f32_e32 v70, v70, v71
	v_mov_b32_e32 v71, v70
	s_nop 1
	v_permlane32_swap_b32_e32 v70, v71
	v_add_f32_e32 v70, v70, v71
	v_fmamk_f32 v70, v70, 0x3a800000, v69
	v_mul_f32_e32 v71, 0x4f800000, v70
	v_cmp_gt_f32_e32 vcc, s35, v70
	s_nop 1
	v_cndmask_b32_e32 v70, v70, v71, vcc
	v_sqrt_f32_e32 v71, v70
	s_nop 1
	v_add_u32_e32 v72, -1, v71
	v_add_u32_e32 v73, 1, v71
	v_fma_f32 v74, -v72, v71, v70
	v_fma_f32 v75, -v73, v71, v70
	v_cmp_ge_f32_e64 s[0:1], 0, v74
	s_nop 1
	v_cndmask_b32_e64 v71, v71, v72, s[0:1]
	v_cmp_lt_f32_e64 s[0:1], 0, v75
	s_nop 1
	v_cndmask_b32_e64 v71, v71, v73, s[0:1]
	v_mul_f32_e32 v72, 0x37800000, v71
	s_nop 0
	v_cndmask_b32_e32 v71, v71, v72, vcc
	v_cmp_class_f32_e32 vcc, v70, v80
	s_nop 1
	v_cndmask_b32_e32 v70, v71, v70, vcc
	v_div_scale_f32 v71, s[0:1], v70, v70, 1.0
	v_rcp_f32_e32 v72, v71
	v_div_scale_f32 v73, vcc, 1.0, v70, 1.0
	v_fma_f32 v74, -v71, v72, 1.0
	v_fmac_f32_e32 v72, v74, v72
	v_mul_f32_e32 v74, v73, v72
	v_fma_f32 v75, -v71, v74, v73
	v_fmac_f32_e32 v74, v75, v72
	v_fma_f32 v71, -v71, v74, v73
	v_div_fmas_f32 v71, v71, v72, v74
	v_div_fixup_f32 v76, v71, v70, 1.0
	v_pk_mul_f32 v[36:37], v[36:37], v[76:77] op_sel_hi:[1,0]
	v_pk_mul_f32 v[38:39], v[38:39], v[76:77] op_sel_hi:[1,0]
	v_pk_mul_f32 v[40:41], v[40:41], v[76:77] op_sel_hi:[1,0]
	v_pk_mul_f32 v[42:43], v[42:43], v[76:77] op_sel_hi:[1,0]
	v_pk_mul_f32 v[44:45], v[44:45], v[76:77] op_sel_hi:[1,0]
	v_pk_mul_f32 v[46:47], v[46:47], v[76:77] op_sel_hi:[1,0]
	v_pk_mul_f32 v[48:49], v[48:49], v[76:77] op_sel_hi:[1,0]
	v_pk_mul_f32 v[50:51], v[50:51], v[76:77] op_sel_hi:[1,0]
	v_lshlrev_b32_e32 v52, 16, v124
	v_and_b32_e32 v53, s34, v124
	v_lshlrev_b32_e32 v54, 16, v125
	v_and_b32_e32 v55, s34, v125
	v_lshlrev_b32_e32 v56, 16, v126
	v_and_b32_e32 v57, s34, v126
	v_lshlrev_b32_e32 v58, 16, v127
	v_and_b32_e32 v59, s34, v127
	v_lshlrev_b32_e32 v60, 16, v128
	v_and_b32_e32 v61, s34, v128
	v_lshlrev_b32_e32 v62, 16, v129
	v_and_b32_e32 v63, s34, v129
	v_lshlrev_b32_e32 v64, 16, v130
	v_and_b32_e32 v65, s34, v130
	v_lshlrev_b32_e32 v66, 16, v131
	v_and_b32_e32 v67, s34, v131
	v_pk_fma_f32 v[52:53], v[36:37], v[2:3], v[52:53]
	v_pk_fma_f32 v[54:55], v[38:39], v[4:5], v[54:55]
	v_pk_fma_f32 v[56:57], v[40:41], v[6:7], v[56:57]
	v_pk_fma_f32 v[58:59], v[42:43], v[8:9], v[58:59]
	v_pk_fma_f32 v[60:61], v[44:45], v[10:11], v[60:61]
	v_pk_fma_f32 v[62:63], v[46:47], v[12:13], v[62:63]
	v_pk_fma_f32 v[64:65], v[48:49], v[14:15], v[64:65]
	v_pk_fma_f32 v[66:67], v[50:51], v[16:17], v[66:67]
	v_cvt_pk_bf16_f32 v148, v52, v53
	v_cvt_pk_bf16_f32 v149, v54, v55
	v_cvt_pk_bf16_f32 v150, v56, v57
	v_cvt_pk_bf16_f32 v151, v58, v59
	v_cvt_pk_bf16_f32 v152, v60, v61
	v_cvt_pk_bf16_f32 v153, v62, v63
	v_cvt_pk_bf16_f32 v154, v64, v65
	v_cvt_pk_bf16_f32 v155, v66, v67
	global_store_dwordx2 v1, v[148:149], s[10:11] offset:0
	global_store_dwordx2 v1, v[150:151], s[10:11] offset:512
	global_store_dwordx2 v1, v[152:153], s[10:11] offset:1024
	global_store_dwordx2 v1, v[154:155], s[10:11] offset:1536
	v_lshlrev_b32_e32 v52, 16, v148
	v_and_b32_e32 v53, s34, v148
	v_lshlrev_b32_e32 v54, 16, v149
	v_and_b32_e32 v55, s34, v149
	v_lshlrev_b32_e32 v56, 16, v150
	v_and_b32_e32 v57, s34, v150
	v_lshlrev_b32_e32 v58, 16, v151
	v_and_b32_e32 v59, s34, v151
	v_lshlrev_b32_e32 v60, 16, v152
	v_and_b32_e32 v61, s34, v152
	v_lshlrev_b32_e32 v62, 16, v153
	v_and_b32_e32 v63, s34, v153
	v_lshlrev_b32_e32 v64, 16, v154
	v_and_b32_e32 v65, s34, v154
	v_lshlrev_b32_e32 v66, 16, v155
	v_and_b32_e32 v67, s34, v155
	v_pk_mul_f32 v[70:71], v[52:53], v[52:53]
	v_pk_mul_f32 v[72:73], v[54:55], v[54:55]
	v_pk_fma_f32 v[70:71], v[56:57], v[56:57], v[70:71]
	v_pk_fma_f32 v[72:73], v[58:59], v[58:59], v[72:73]
	v_pk_fma_f32 v[70:71], v[60:61], v[60:61], v[70:71]
	v_pk_fma_f32 v[72:73], v[62:63], v[62:63], v[72:73]
	v_pk_fma_f32 v[70:71], v[64:65], v[64:65], v[70:71]
	v_pk_fma_f32 v[72:73], v[66:67], v[66:67], v[72:73]
	v_pk_add_f32 v[70:71], v[70:71], v[72:73]
	s_nop 0
	v_add_f32_e32 v70, v70, v71
	s_nop 1
	v_add_f32_dpp v70, v70, v70 quad_perm:[1,0,3,2] row_mask:0xf bank_mask:0xf bound_ctrl:1
	s_nop 1
	v_add_f32_dpp v70, v70, v70 quad_perm:[2,3,0,1] row_mask:0xf bank_mask:0xf bound_ctrl:1
	s_nop 1
	v_add_f32_dpp v70, v70, v70 row_half_mirror row_mask:0xf bank_mask:0xf bound_ctrl:1
	s_nop 1
	v_add_f32_dpp v70, v70, v70 row_mirror row_mask:0xf bank_mask:0xf bound_ctrl:1
	v_mov_b32_e32 v71, v70
	s_nop 1
	v_permlane16_swap_b32_e32 v70, v71
	v_add_f32_e32 v70, v70, v71
	v_mov_b32_e32 v71, v70
	s_nop 1
	v_permlane32_swap_b32_e32 v70, v71
	v_add_f32_e32 v70, v70, v71
	v_fmamk_f32 v70, v70, 0x3a800000, v69
	v_mul_f32_e32 v71, 0x4f800000, v70
	v_cmp_gt_f32_e32 vcc, s35, v70
	s_nop 1
	v_cndmask_b32_e32 v70, v70, v71, vcc
	v_sqrt_f32_e32 v71, v70
	s_nop 1
	v_add_u32_e32 v72, -1, v71
	v_add_u32_e32 v73, 1, v71
	v_fma_f32 v74, -v72, v71, v70
	v_fma_f32 v75, -v73, v71, v70
	v_cmp_ge_f32_e64 s[0:1], 0, v74
	s_nop 1
	v_cndmask_b32_e64 v71, v71, v72, s[0:1]
	v_cmp_lt_f32_e64 s[0:1], 0, v75
	s_nop 1
	v_cndmask_b32_e64 v71, v71, v73, s[0:1]
	v_mul_f32_e32 v72, 0x37800000, v71
	s_nop 0
	v_cndmask_b32_e32 v71, v71, v72, vcc
	v_cmp_class_f32_e32 vcc, v70, v80
	s_nop 1
	v_cndmask_b32_e32 v70, v71, v70, vcc
	v_div_scale_f32 v71, s[0:1], v70, v70, 1.0
	v_rcp_f32_e32 v72, v71
	v_div_scale_f32 v73, vcc, 1.0, v70, 1.0
	v_fma_f32 v74, -v71, v72, 1.0
	v_fmac_f32_e32 v72, v74, v72
	v_mul_f32_e32 v74, v73, v72
	v_fma_f32 v75, -v71, v74, v73
	v_fmac_f32_e32 v74, v75, v72
	v_fma_f32 v71, -v71, v74, v73
	v_div_fmas_f32 v71, v71, v72, v74
	v_div_fixup_f32 v76, v71, v70, 1.0
	v_pk_mul_f32 v[52:53], v[52:53], v[76:77] op_sel_hi:[1,0]
	v_pk_mul_f32 v[54:55], v[54:55], v[76:77] op_sel_hi:[1,0]
	v_pk_mul_f32 v[56:57], v[56:57], v[76:77] op_sel_hi:[1,0]
	v_pk_mul_f32 v[58:59], v[58:59], v[76:77] op_sel_hi:[1,0]
	v_pk_mul_f32 v[60:61], v[60:61], v[76:77] op_sel_hi:[1,0]
	v_pk_mul_f32 v[62:63], v[62:63], v[76:77] op_sel_hi:[1,0]
	v_pk_mul_f32 v[64:65], v[64:65], v[76:77] op_sel_hi:[1,0]
	v_pk_mul_f32 v[66:67], v[66:67], v[76:77] op_sel_hi:[1,0]
	v_pk_mul_f32 v[52:53], v[52:53], v[20:21]
	v_pk_mul_f32 v[54:55], v[54:55], v[22:23]
	v_pk_mul_f32 v[56:57], v[56:57], v[24:25]
	v_pk_mul_f32 v[58:59], v[58:59], v[26:27]
	v_pk_mul_f32 v[60:61], v[60:61], v[28:29]
	v_pk_mul_f32 v[62:63], v[62:63], v[30:31]
	v_pk_mul_f32 v[64:65], v[64:65], v[32:33]
	v_pk_mul_f32 v[66:67], v[66:67], v[34:35]
	v_cvt_pk_bf16_f32 v148, v52, v53
	v_cvt_pk_bf16_f32 v149, v54, v55
	v_cvt_pk_bf16_f32 v150, v56, v57
	v_cvt_pk_bf16_f32 v151, v58, v59
	v_cvt_pk_bf16_f32 v152, v60, v61
	v_cvt_pk_bf16_f32 v153, v62, v63
	v_cvt_pk_bf16_f32 v154, v64, v65
	v_cvt_pk_bf16_f32 v155, v66, v67
	global_store_dwordx2 v1, v[148:149], s[12:13] offset:0
	global_store_dwordx2 v1, v[150:151], s[12:13] offset:512
	global_store_dwordx2 v1, v[152:153], s[12:13] offset:1024
	global_store_dwordx2 v1, v[154:155], s[12:13] offset:1536
	s_add_u32 s10, s10, s20
	s_addc_u32 s11, s11, 0
	s_add_u32 s12, s12, s20
	s_addc_u32 s13, s13, 0
	s_waitcnt vmcnt(24)
	v_lshlrev_b32_e32 v36, 16, v132
	v_and_b32_e32 v37, s34, v132
	v_lshlrev_b32_e32 v38, 16, v133
	v_and_b32_e32 v39, s34, v133
	v_lshlrev_b32_e32 v40, 16, v134
	v_and_b32_e32 v41, s34, v134
	v_lshlrev_b32_e32 v42, 16, v135
	v_and_b32_e32 v43, s34, v135
	v_lshlrev_b32_e32 v44, 16, v136
	v_and_b32_e32 v45, s34, v136
	v_lshlrev_b32_e32 v46, 16, v137
	v_and_b32_e32 v47, s34, v137
	v_lshlrev_b32_e32 v48, 16, v138
	v_and_b32_e32 v49, s34, v138
	v_lshlrev_b32_e32 v50, 16, v139
	v_and_b32_e32 v51, s34, v139
	v_pk_mul_f32 v[70:71], v[36:37], v[36:37]
	v_pk_mul_f32 v[72:73], v[38:39], v[38:39]
	v_pk_fma_f32 v[70:71], v[40:41], v[40:41], v[70:71]
	v_pk_fma_f32 v[72:73], v[42:43], v[42:43], v[72:73]
	v_pk_fma_f32 v[70:71], v[44:45], v[44:45], v[70:71]
	v_pk_fma_f32 v[72:73], v[46:47], v[46:47], v[72:73]
	v_pk_fma_f32 v[70:71], v[48:49], v[48:49], v[70:71]
	v_pk_fma_f32 v[72:73], v[50:51], v[50:51], v[72:73]
	v_pk_add_f32 v[70:71], v[70:71], v[72:73]
	s_nop 0
	v_add_f32_e32 v70, v70, v71
	s_nop 1
	v_add_f32_dpp v70, v70, v70 quad_perm:[1,0,3,2] row_mask:0xf bank_mask:0xf bound_ctrl:1
	s_nop 1
	v_add_f32_dpp v70, v70, v70 quad_perm:[2,3,0,1] row_mask:0xf bank_mask:0xf bound_ctrl:1
	s_nop 1
	v_add_f32_dpp v70, v70, v70 row_half_mirror row_mask:0xf bank_mask:0xf bound_ctrl:1
	s_nop 1
	v_add_f32_dpp v70, v70, v70 row_mirror row_mask:0xf bank_mask:0xf bound_ctrl:1
	v_mov_b32_e32 v71, v70
	s_nop 1
	v_permlane16_swap_b32_e32 v70, v71
	v_add_f32_e32 v70, v70, v71
	v_mov_b32_e32 v71, v70
	s_nop 1
	v_permlane32_swap_b32_e32 v70, v71
	v_add_f32_e32 v70, v70, v71
	v_fmamk_f32 v70, v70, 0x3a800000, v69
	v_mul_f32_e32 v71, 0x4f800000, v70
	v_cmp_gt_f32_e32 vcc, s35, v70
	s_nop 1
	v_cndmask_b32_e32 v70, v70, v71, vcc
	v_sqrt_f32_e32 v71, v70
	s_nop 1
	v_add_u32_e32 v72, -1, v71
	v_add_u32_e32 v73, 1, v71
	v_fma_f32 v74, -v72, v71, v70
	v_fma_f32 v75, -v73, v71, v70
	v_cmp_ge_f32_e64 s[0:1], 0, v74
	s_nop 1
	v_cndmask_b32_e64 v71, v71, v72, s[0:1]
	v_cmp_lt_f32_e64 s[0:1], 0, v75
	s_nop 1
	v_cndmask_b32_e64 v71, v71, v73, s[0:1]
	v_mul_f32_e32 v72, 0x37800000, v71
	s_nop 0
	v_cndmask_b32_e32 v71, v71, v72, vcc
	v_cmp_class_f32_e32 vcc, v70, v80
	s_nop 1
	v_cndmask_b32_e32 v70, v71, v70, vcc
	v_div_scale_f32 v71, s[0:1], v70, v70, 1.0
	v_rcp_f32_e32 v72, v71
	v_div_scale_f32 v73, vcc, 1.0, v70, 1.0
	v_fma_f32 v74, -v71, v72, 1.0
	v_fmac_f32_e32 v72, v74, v72
	v_mul_f32_e32 v74, v73, v72
	v_fma_f32 v75, -v71, v74, v73
	v_fmac_f32_e32 v74, v75, v72
	v_fma_f32 v71, -v71, v74, v73
	v_div_fmas_f32 v71, v71, v72, v74
	v_div_fixup_f32 v76, v71, v70, 1.0
	v_pk_mul_f32 v[36:37], v[36:37], v[76:77] op_sel_hi:[1,0]
	v_pk_mul_f32 v[38:39], v[38:39], v[76:77] op_sel_hi:[1,0]
	v_pk_mul_f32 v[40:41], v[40:41], v[76:77] op_sel_hi:[1,0]
	v_pk_mul_f32 v[42:43], v[42:43], v[76:77] op_sel_hi:[1,0]
	v_pk_mul_f32 v[44:45], v[44:45], v[76:77] op_sel_hi:[1,0]
	v_pk_mul_f32 v[46:47], v[46:47], v[76:77] op_sel_hi:[1,0]
	v_pk_mul_f32 v[48:49], v[48:49], v[76:77] op_sel_hi:[1,0]
	v_pk_mul_f32 v[50:51], v[50:51], v[76:77] op_sel_hi:[1,0]
	v_lshlrev_b32_e32 v52, 16, v140
	v_and_b32_e32 v53, s34, v140
	v_lshlrev_b32_e32 v54, 16, v141
	v_and_b32_e32 v55, s34, v141
	v_lshlrev_b32_e32 v56, 16, v142
	v_and_b32_e32 v57, s34, v142
	v_lshlrev_b32_e32 v58, 16, v143
	v_and_b32_e32 v59, s34, v143
	v_lshlrev_b32_e32 v60, 16, v144
	v_and_b32_e32 v61, s34, v144
	v_lshlrev_b32_e32 v62, 16, v145
	v_and_b32_e32 v63, s34, v145
	v_lshlrev_b32_e32 v64, 16, v146
	v_and_b32_e32 v65, s34, v146
	v_lshlrev_b32_e32 v66, 16, v147
	v_and_b32_e32 v67, s34, v147
	v_pk_fma_f32 v[52:53], v[36:37], v[2:3], v[52:53]
	v_pk_fma_f32 v[54:55], v[38:39], v[4:5], v[54:55]
	v_pk_fma_f32 v[56:57], v[40:41], v[6:7], v[56:57]
	v_pk_fma_f32 v[58:59], v[42:43], v[8:9], v[58:59]
	v_pk_fma_f32 v[60:61], v[44:45], v[10:11], v[60:61]
	v_pk_fma_f32 v[62:63], v[46:47], v[12:13], v[62:63]
	v_pk_fma_f32 v[64:65], v[48:49], v[14:15], v[64:65]
	v_pk_fma_f32 v[66:67], v[50:51], v[16:17], v[66:67]
	v_cvt_pk_bf16_f32 v148, v52, v53
	v_cvt_pk_bf16_f32 v149, v54, v55
	v_cvt_pk_bf16_f32 v150, v56, v57
	v_cvt_pk_bf16_f32 v151, v58, v59
	v_cvt_pk_bf16_f32 v152, v60, v61
	v_cvt_pk_bf16_f32 v153, v62, v63
	v_cvt_pk_bf16_f32 v154, v64, v65
	v_cvt_pk_bf16_f32 v155, v66, v67
	global_store_dwordx2 v1, v[148:149], s[10:11] offset:0
	global_store_dwordx2 v1, v[150:151], s[10:11] offset:512
	global_store_dwordx2 v1, v[152:153], s[10:11] offset:1024
	global_store_dwordx2 v1, v[154:155], s[10:11] offset:1536
	v_lshlrev_b32_e32 v52, 16, v148
	v_and_b32_e32 v53, s34, v148
	v_lshlrev_b32_e32 v54, 16, v149
	v_and_b32_e32 v55, s34, v149
	v_lshlrev_b32_e32 v56, 16, v150
	v_and_b32_e32 v57, s34, v150
	v_lshlrev_b32_e32 v58, 16, v151
	v_and_b32_e32 v59, s34, v151
	v_lshlrev_b32_e32 v60, 16, v152
	v_and_b32_e32 v61, s34, v152
	v_lshlrev_b32_e32 v62, 16, v153
	v_and_b32_e32 v63, s34, v153
	v_lshlrev_b32_e32 v64, 16, v154
	v_and_b32_e32 v65, s34, v154
	v_lshlrev_b32_e32 v66, 16, v155
	v_and_b32_e32 v67, s34, v155
	v_pk_mul_f32 v[70:71], v[52:53], v[52:53]
	v_pk_mul_f32 v[72:73], v[54:55], v[54:55]
	v_pk_fma_f32 v[70:71], v[56:57], v[56:57], v[70:71]
	v_pk_fma_f32 v[72:73], v[58:59], v[58:59], v[72:73]
	v_pk_fma_f32 v[70:71], v[60:61], v[60:61], v[70:71]
	v_pk_fma_f32 v[72:73], v[62:63], v[62:63], v[72:73]
	v_pk_fma_f32 v[70:71], v[64:65], v[64:65], v[70:71]
	v_pk_fma_f32 v[72:73], v[66:67], v[66:67], v[72:73]
	v_pk_add_f32 v[70:71], v[70:71], v[72:73]
	s_nop 0
	v_add_f32_e32 v70, v70, v71
	s_nop 1
	v_add_f32_dpp v70, v70, v70 quad_perm:[1,0,3,2] row_mask:0xf bank_mask:0xf bound_ctrl:1
	s_nop 1
	v_add_f32_dpp v70, v70, v70 quad_perm:[2,3,0,1] row_mask:0xf bank_mask:0xf bound_ctrl:1
	s_nop 1
	v_add_f32_dpp v70, v70, v70 row_half_mirror row_mask:0xf bank_mask:0xf bound_ctrl:1
	s_nop 1
	v_add_f32_dpp v70, v70, v70 row_mirror row_mask:0xf bank_mask:0xf bound_ctrl:1
	v_mov_b32_e32 v71, v70
	s_nop 1
	v_permlane16_swap_b32_e32 v70, v71
	v_add_f32_e32 v70, v70, v71
	v_mov_b32_e32 v71, v70
	s_nop 1
	v_permlane32_swap_b32_e32 v70, v71
	v_add_f32_e32 v70, v70, v71
	v_fmamk_f32 v70, v70, 0x3a800000, v69
	v_mul_f32_e32 v71, 0x4f800000, v70
	v_cmp_gt_f32_e32 vcc, s35, v70
	s_nop 1
	v_cndmask_b32_e32 v70, v70, v71, vcc
	v_sqrt_f32_e32 v71, v70
	s_nop 1
	v_add_u32_e32 v72, -1, v71
	v_add_u32_e32 v73, 1, v71
	v_fma_f32 v74, -v72, v71, v70
	v_fma_f32 v75, -v73, v71, v70
	v_cmp_ge_f32_e64 s[0:1], 0, v74
	s_nop 1
	v_cndmask_b32_e64 v71, v71, v72, s[0:1]
	v_cmp_lt_f32_e64 s[0:1], 0, v75
	s_nop 1
	v_cndmask_b32_e64 v71, v71, v73, s[0:1]
	v_mul_f32_e32 v72, 0x37800000, v71
	s_nop 0
	v_cndmask_b32_e32 v71, v71, v72, vcc
	v_cmp_class_f32_e32 vcc, v70, v80
	s_nop 1
	v_cndmask_b32_e32 v70, v71, v70, vcc
	v_div_scale_f32 v71, s[0:1], v70, v70, 1.0
	v_rcp_f32_e32 v72, v71
	v_div_scale_f32 v73, vcc, 1.0, v70, 1.0
	v_fma_f32 v74, -v71, v72, 1.0
	v_fmac_f32_e32 v72, v74, v72
	v_mul_f32_e32 v74, v73, v72
	v_fma_f32 v75, -v71, v74, v73
	v_fmac_f32_e32 v74, v75, v72
	v_fma_f32 v71, -v71, v74, v73
	v_div_fmas_f32 v71, v71, v72, v74
	v_div_fixup_f32 v76, v71, v70, 1.0
	v_pk_mul_f32 v[52:53], v[52:53], v[76:77] op_sel_hi:[1,0]
	v_pk_mul_f32 v[54:55], v[54:55], v[76:77] op_sel_hi:[1,0]
	v_pk_mul_f32 v[56:57], v[56:57], v[76:77] op_sel_hi:[1,0]
	v_pk_mul_f32 v[58:59], v[58:59], v[76:77] op_sel_hi:[1,0]
	v_pk_mul_f32 v[60:61], v[60:61], v[76:77] op_sel_hi:[1,0]
	v_pk_mul_f32 v[62:63], v[62:63], v[76:77] op_sel_hi:[1,0]
	v_pk_mul_f32 v[64:65], v[64:65], v[76:77] op_sel_hi:[1,0]
	v_pk_mul_f32 v[66:67], v[66:67], v[76:77] op_sel_hi:[1,0]
	v_pk_mul_f32 v[52:53], v[52:53], v[20:21]
	v_pk_mul_f32 v[54:55], v[54:55], v[22:23]
	v_pk_mul_f32 v[56:57], v[56:57], v[24:25]
	v_pk_mul_f32 v[58:59], v[58:59], v[26:27]
	v_pk_mul_f32 v[60:61], v[60:61], v[28:29]
	v_pk_mul_f32 v[62:63], v[62:63], v[30:31]
	v_pk_mul_f32 v[64:65], v[64:65], v[32:33]
	v_pk_mul_f32 v[66:67], v[66:67], v[34:35]
	v_cvt_pk_bf16_f32 v148, v52, v53
	v_cvt_pk_bf16_f32 v149, v54, v55
	v_cvt_pk_bf16_f32 v150, v56, v57
	v_cvt_pk_bf16_f32 v151, v58, v59
	v_cvt_pk_bf16_f32 v152, v60, v61
	v_cvt_pk_bf16_f32 v153, v62, v63
	v_cvt_pk_bf16_f32 v154, v64, v65
	v_cvt_pk_bf16_f32 v155, v66, v67
	global_store_dwordx2 v1, v[148:149], s[12:13] offset:0
	global_store_dwordx2 v1, v[150:151], s[12:13] offset:512
	global_store_dwordx2 v1, v[152:153], s[12:13] offset:1024
	global_store_dwordx2 v1, v[154:155], s[12:13] offset:1536
	s_add_u32 s10, s10, s20
	s_addc_u32 s11, s11, 0
	s_add_u32 s12, s12, s20
	s_addc_u32 s13, s13, 0
	s_lshl_b32 s36, s23, 2
	s_add_i32 s5, s5, s36
	s_branch .Lrw9_batch
.Lrw9_single:
	s_cmpk_lt_i32 s5, 0x4200
	s_cbranch_scc0 .Lrw9_done
	s_cmpk_lt_i32 s5, 0x4000
	s_cbranch_scc0 .Lrw9_sample
	global_load_dwordx2 v[84:85], v1, s[6:7] offset:0
	global_load_dwordx2 v[86:87], v1, s[6:7] offset:512
	global_load_dwordx2 v[88:89], v1, s[6:7] offset:1024
	global_load_dwordx2 v[90:91], v1, s[6:7] offset:1536
	global_load_dwordx2 v[92:93], v1, s[8:9] offset:0
	global_load_dwordx2 v[94:95], v1, s[8:9] offset:512
	global_load_dwordx2 v[96:97], v1, s[8:9] offset:1024
	global_load_dwordx2 v[98:99], v1, s[8:9] offset:1536
	s_waitcnt vmcnt(0)
	v_lshlrev_b32_e32 v36, 16, v84
	v_and_b32_e32 v37, s34, v84
	v_lshlrev_b32_e32 v38, 16, v85
	v_and_b32_e32 v39, s34, v85
	v_lshlrev_b32_e32 v40, 16, v86
	v_and_b32_e32 v41, s34, v86
	v_lshlrev_b32_e32 v42, 16, v87
	v_and_b32_e32 v43, s34, v87
	v_lshlrev_b32_e32 v44, 16, v88
	v_and_b32_e32 v45, s34, v88
	v_lshlrev_b32_e32 v46, 16, v89
	v_and_b32_e32 v47, s34, v89
	v_lshlrev_b32_e32 v48, 16, v90
	v_and_b32_e32 v49, s34, v90
	v_lshlrev_b32_e32 v50, 16, v91
	v_and_b32_e32 v51, s34, v91
	v_pk_mul_f32 v[70:71], v[36:37], v[36:37]
	v_pk_mul_f32 v[72:73], v[38:39], v[38:39]
	v_pk_fma_f32 v[70:71], v[40:41], v[40:41], v[70:71]
	v_pk_fma_f32 v[72:73], v[42:43], v[42:43], v[72:73]
	v_pk_fma_f32 v[70:71], v[44:45], v[44:45], v[70:71]
	v_pk_fma_f32 v[72:73], v[46:47], v[46:47], v[72:73]
	v_pk_fma_f32 v[70:71], v[48:49], v[48:49], v[70:71]
	v_pk_fma_f32 v[72:73], v[50:51], v[50:51], v[72:73]
	v_pk_add_f32 v[70:71], v[70:71], v[72:73]
	s_nop 0
	v_add_f32_e32 v70, v70, v71
	s_nop 1
	v_add_f32_dpp v70, v70, v70 quad_perm:[1,0,3,2] row_mask:0xf bank_mask:0xf bound_ctrl:1
	s_nop 1
	v_add_f32_dpp v70, v70, v70 quad_perm:[2,3,0,1] row_mask:0xf bank_mask:0xf bound_ctrl:1
	s_nop 1
	v_add_f32_dpp v70, v70, v70 row_half_mirror row_mask:0xf bank_mask:0xf bound_ctrl:1
	s_nop 1
	v_add_f32_dpp v70, v70, v70 row_mirror row_mask:0xf bank_mask:0xf bound_ctrl:1
	v_mov_b32_e32 v71, v70
	s_nop 1
	v_permlane16_swap_b32_e32 v70, v71
	v_add_f32_e32 v70, v70, v71
	v_mov_b32_e32 v71, v70
	s_nop 1
	v_permlane32_swap_b32_e32 v70, v71
	v_add_f32_e32 v70, v70, v71
	v_fmamk_f32 v70, v70, 0x3a800000, v69
	v_mul_f32_e32 v71, 0x4f800000, v70
	v_cmp_gt_f32_e32 vcc, s35, v70
	s_nop 1
	v_cndmask_b32_e32 v70, v70, v71, vcc
	v_sqrt_f32_e32 v71, v70
	s_nop 1
	v_add_u32_e32 v72, -1, v71
	v_add_u32_e32 v73, 1, v71
	v_fma_f32 v74, -v72, v71, v70
	v_fma_f32 v75, -v73, v71, v70
	v_cmp_ge_f32_e64 s[0:1], 0, v74
	s_nop 1
	v_cndmask_b32_e64 v71, v71, v72, s[0:1]
	v_cmp_lt_f32_e64 s[0:1], 0, v75
	s_nop 1
	v_cndmask_b32_e64 v71, v71, v73, s[0:1]
	v_mul_f32_e32 v72, 0x37800000, v71
	s_nop 0
	v_cndmask_b32_e32 v71, v71, v72, vcc
	v_cmp_class_f32_e32 vcc, v70, v80
	s_nop 1
	v_cndmask_b32_e32 v70, v71, v70, vcc
	v_div_scale_f32 v71, s[0:1], v70, v70, 1.0
	v_rcp_f32_e32 v72, v71
	v_div_scale_f32 v73, vcc, 1.0, v70, 1.0
	v_fma_f32 v74, -v71, v72, 1.0
	v_fmac_f32_e32 v72, v74, v72
	v_mul_f32_e32 v74, v73, v72
	v_fma_f32 v75, -v71, v74, v73
	v_fmac_f32_e32 v74, v75, v72
	v_fma_f32 v71, -v71, v74, v73
	v_div_fmas_f32 v71, v71, v72, v74
	v_div_fixup_f32 v76, v71, v70, 1.0
	v_pk_mul_f32 v[36:37], v[36:37], v[76:77] op_sel_hi:[1,0]
	v_pk_mul_f32 v[38:39], v[38:39], v[76:77] op_sel_hi:[1,0]
	v_pk_mul_f32 v[40:41], v[40:41], v[76:77] op_sel_hi:[1,0]
	v_pk_mul_f32 v[42:43], v[42:43], v[76:77] op_sel_hi:[1,0]
	v_pk_mul_f32 v[44:45], v[44:45], v[76:77] op_sel_hi:[1,0]
	v_pk_mul_f32 v[46:47], v[46:47], v[76:77] op_sel_hi:[1,0]
	v_pk_mul_f32 v[48:49], v[48:49], v[76:77] op_sel_hi:[1,0]
	v_pk_mul_f32 v[50:51], v[50:51], v[76:77] op_sel_hi:[1,0]
	v_lshlrev_b32_e32 v52, 16, v92
	v_and_b32_e32 v53, s34, v92
	v_lshlrev_b32_e32 v54, 16, v93
	v_and_b32_e32 v55, s34, v93
	v_lshlrev_b32_e32 v56, 16, v94
	v_and_b32_e32 v57, s34, v94
	v_lshlrev_b32_e32 v58, 16, v95
	v_and_b32_e32 v59, s34, v95
	v_lshlrev_b32_e32 v60, 16, v96
	v_and_b32_e32 v61, s34, v96
	v_lshlrev_b32_e32 v62, 16, v97
	v_and_b32_e32 v63, s34, v97
	v_lshlrev_b32_e32 v64, 16, v98
	v_and_b32_e32 v65, s34, v98
	v_lshlrev_b32_e32 v66, 16, v99
	v_and_b32_e32 v67, s34, v99
	v_pk_fma_f32 v[52:53], v[36:37], v[2:3], v[52:53]
	v_pk_fma_f32 v[54:55], v[38:39], v[4:5], v[54:55]
	v_pk_fma_f32 v[56:57], v[40:41], v[6:7], v[56:57]
	v_pk_fma_f32 v[58:59], v[42:43], v[8:9], v[58:59]
	v_pk_fma_f32 v[60:61], v[44:45], v[10:11], v[60:61]
	v_pk_fma_f32 v[62:63], v[46:47], v[12:13], v[62:63]
	v_pk_fma_f32 v[64:65], v[48:49], v[14:15], v[64:65]
	v_pk_fma_f32 v[66:67], v[50:51], v[16:17], v[66:67]
	v_cvt_pk_bf16_f32 v148, v52, v53
	v_cvt_pk_bf16_f32 v149, v54, v55
	v_cvt_pk_bf16_f32 v150, v56, v57
	v_cvt_pk_bf16_f32 v151, v58, v59
	v_cvt_pk_bf16_f32 v152, v60, v61
	v_cvt_pk_bf16_f32 v153, v62, v63
	v_cvt_pk_bf16_f32 v154, v64, v65
	v_cvt_pk_bf16_f32 v155, v66, v67
	global_store_dwordx2 v1, v[148:149], s[10:11] offset:0
	global_store_dwordx2 v1, v[150:151], s[10:11] offset:512
	global_store_dwordx2 v1, v[152:153], s[10:11] offset:1024
	global_store_dwordx2 v1, v[154:155], s[10:11] offset:1536
	v_lshlrev_b32_e32 v52, 16, v148
	v_and_b32_e32 v53, s34, v148
	v_lshlrev_b32_e32 v54, 16, v149
	v_and_b32_e32 v55, s34, v149
	v_lshlrev_b32_e32 v56, 16, v150
	v_and_b32_e32 v57, s34, v150
	v_lshlrev_b32_e32 v58, 16, v151
	v_and_b32_e32 v59, s34, v151
	v_lshlrev_b32_e32 v60, 16, v152
	v_and_b32_e32 v61, s34, v152
	v_lshlrev_b32_e32 v62, 16, v153
	v_and_b32_e32 v63, s34, v153
	v_lshlrev_b32_e32 v64, 16, v154
	v_and_b32_e32 v65, s34, v154
	v_lshlrev_b32_e32 v66, 16, v155
	v_and_b32_e32 v67, s34, v155
	v_pk_mul_f32 v[70:71], v[52:53], v[52:53]
	v_pk_mul_f32 v[72:73], v[54:55], v[54:55]
	v_pk_fma_f32 v[70:71], v[56:57], v[56:57], v[70:71]
	v_pk_fma_f32 v[72:73], v[58:59], v[58:59], v[72:73]
	v_pk_fma_f32 v[70:71], v[60:61], v[60:61], v[70:71]
	v_pk_fma_f32 v[72:73], v[62:63], v[62:63], v[72:73]
	v_pk_fma_f32 v[70:71], v[64:65], v[64:65], v[70:71]
	v_pk_fma_f32 v[72:73], v[66:67], v[66:67], v[72:73]
	v_pk_add_f32 v[70:71], v[70:71], v[72:73]
	s_nop 0
	v_add_f32_e32 v70, v70, v71
	s_nop 1
	v_add_f32_dpp v70, v70, v70 quad_perm:[1,0,3,2] row_mask:0xf bank_mask:0xf bound_ctrl:1
	s_nop 1
	v_add_f32_dpp v70, v70, v70 quad_perm:[2,3,0,1] row_mask:0xf bank_mask:0xf bound_ctrl:1
	s_nop 1
	v_add_f32_dpp v70, v70, v70 row_half_mirror row_mask:0xf bank_mask:0xf bound_ctrl:1
	s_nop 1
	v_add_f32_dpp v70, v70, v70 row_mirror row_mask:0xf bank_mask:0xf bound_ctrl:1
	v_mov_b32_e32 v71, v70
	s_nop 1
	v_permlane16_swap_b32_e32 v70, v71
	v_add_f32_e32 v70, v70, v71
	v_mov_b32_e32 v71, v70
	s_nop 1
	v_permlane32_swap_b32_e32 v70, v71
	v_add_f32_e32 v70, v70, v71
	v_fmamk_f32 v70, v70, 0x3a800000, v69
	v_mul_f32_e32 v71, 0x4f800000, v70
	v_cmp_gt_f32_e32 vcc, s35, v70
	s_nop 1
	v_cndmask_b32_e32 v70, v70, v71, vcc
	v_sqrt_f32_e32 v71, v70
	s_nop 1
	v_add_u32_e32 v72, -1, v71
	v_add_u32_e32 v73, 1, v71
	v_fma_f32 v74, -v72, v71, v70
	v_fma_f32 v75, -v73, v71, v70
	v_cmp_ge_f32_e64 s[0:1], 0, v74
	s_nop 1
	v_cndmask_b32_e64 v71, v71, v72, s[0:1]
	v_cmp_lt_f32_e64 s[0:1], 0, v75
	s_nop 1
	v_cndmask_b32_e64 v71, v71, v73, s[0:1]
	v_mul_f32_e32 v72, 0x37800000, v71
	s_nop 0
	v_cndmask_b32_e32 v71, v71, v72, vcc
	v_cmp_class_f32_e32 vcc, v70, v80
	s_nop 1
	v_cndmask_b32_e32 v70, v71, v70, vcc
	v_div_scale_f32 v71, s[0:1], v70, v70, 1.0
	v_rcp_f32_e32 v72, v71
	v_div_scale_f32 v73, vcc, 1.0, v70, 1.0
	v_fma_f32 v74, -v71, v72, 1.0
	v_fmac_f32_e32 v72, v74, v72
	v_mul_f32_e32 v74, v73, v72
	v_fma_f32 v75, -v71, v74, v73
	v_fmac_f32_e32 v74, v75, v72
	v_fma_f32 v71, -v71, v74, v73
	v_div_fmas_f32 v71, v71, v72, v74
	v_div_fixup_f32 v76, v71, v70, 1.0
	v_pk_mul_f32 v[52:53], v[52:53], v[76:77] op_sel_hi:[1,0]
	v_pk_mul_f32 v[54:55], v[54:55], v[76:77] op_sel_hi:[1,0]
	v_pk_mul_f32 v[56:57], v[56:57], v[76:77] op_sel_hi:[1,0]
	v_pk_mul_f32 v[58:59], v[58:59], v[76:77] op_sel_hi:[1,0]
	v_pk_mul_f32 v[60:61], v[60:61], v[76:77] op_sel_hi:[1,0]
	v_pk_mul_f32 v[62:63], v[62:63], v[76:77] op_sel_hi:[1,0]
	v_pk_mul_f32 v[64:65], v[64:65], v[76:77] op_sel_hi:[1,0]
	v_pk_mul_f32 v[66:67], v[66:67], v[76:77] op_sel_hi:[1,0]
	v_pk_mul_f32 v[52:53], v[52:53], v[20:21]
	v_pk_mul_f32 v[54:55], v[54:55], v[22:23]
	v_pk_mul_f32 v[56:57], v[56:57], v[24:25]
	v_pk_mul_f32 v[58:59], v[58:59], v[26:27]
	v_pk_mul_f32 v[60:61], v[60:61], v[28:29]
	v_pk_mul_f32 v[62:63], v[62:63], v[30:31]
	v_pk_mul_f32 v[64:65], v[64:65], v[32:33]
	v_pk_mul_f32 v[66:67], v[66:67], v[34:35]
	v_cvt_pk_bf16_f32 v148, v52, v53
	v_cvt_pk_bf16_f32 v149, v54, v55
	v_cvt_pk_bf16_f32 v150, v56, v57
	v_cvt_pk_bf16_f32 v151, v58, v59
	v_cvt_pk_bf16_f32 v152, v60, v61
	v_cvt_pk_bf16_f32 v153, v62, v63
	v_cvt_pk_bf16_f32 v154, v64, v65
	v_cvt_pk_bf16_f32 v155, v66, v67
	global_store_dwordx2 v1, v[148:149], s[12:13] offset:0
	global_store_dwordx2 v1, v[150:151], s[12:13] offset:512
	global_store_dwordx2 v1, v[152:153], s[12:13] offset:1024
	global_store_dwordx2 v1, v[154:155], s[12:13] offset:1536
	s_branch .Lrw9_next
.Lrw9_sample:
	s_sub_i32 s36, s5, 0x4000
	s_lshl_b32 s36, s36, 12
	s_add_u32 s14, s26, 0x32200000
	s_addc_u32 s15, s27, 0
	s_add_u32 s14, s14, s36
	s_addc_u32 s15, s15, 0
	global_load_dwordx2 v[148:149], v1, s[8:9] offset:0
	global_load_dwordx2 v[150:151], v1, s[8:9] offset:512
	global_load_dwordx2 v[152:153], v1, s[8:9] offset:1024
	global_load_dwordx2 v[154:155], v1, s[8:9] offset:1536
	v_mov_b32_e32 v36, 0
	v_mov_b32_e32 v37, 0
	v_mov_b32_e32 v38, 0
	v_mov_b32_e32 v39, 0
	v_mov_b32_e32 v40, 0
	v_mov_b32_e32 v41, 0
	v_mov_b32_e32 v42, 0
	v_mov_b32_e32 v43, 0
	v_mov_b32_e32 v44, 0
	v_mov_b32_e32 v45, 0
	v_mov_b32_e32 v46, 0
	v_mov_b32_e32 v47, 0
	v_mov_b32_e32 v48, 0
	v_mov_b32_e32 v49, 0
	v_mov_b32_e32 v50, 0
	v_mov_b32_e32 v51, 0
	global_load_dwordx4 v[84:87], v19, s[14:15] offset:0
	global_load_dwordx4 v[88:91], v19, s[14:15] offset:1024
	global_load_dwordx4 v[92:95], v19, s[14:15] offset:2048
	global_load_dwordx4 v[96:99], v19, s[14:15] offset:3072
	s_add_u32 s14, s14, 0x200000
	s_addc_u32 s15, s15, 0
	global_load_dwordx4 v[100:103], v19, s[14:15] offset:0
	global_load_dwordx4 v[104:107], v19, s[14:15] offset:1024
	global_load_dwordx4 v[108:111], v19, s[14:15] offset:2048
	global_load_dwordx4 v[112:115], v19, s[14:15] offset:3072
	s_add_u32 s14, s14, 0x200000
	s_addc_u32 s15, s15, 0
	global_load_dwordx4 v[116:119], v19, s[14:15] offset:0
	global_load_dwordx4 v[120:123], v19, s[14:15] offset:1024
	global_load_dwordx4 v[124:127], v19, s[14:15] offset:2048
	global_load_dwordx4 v[128:131], v19, s[14:15] offset:3072
	s_add_u32 s14, s14, 0x200000
	s_addc_u32 s15, s15, 0
	global_load_dwordx4 v[132:135], v19, s[14:15] offset:0
	global_load_dwordx4 v[136:139], v19, s[14:15] offset:1024
	global_load_dwordx4 v[140:143], v19, s[14:15] offset:2048
	global_load_dwordx4 v[144:147], v19, s[14:15] offset:3072
	s_add_u32 s14, s14, 0x200000
	s_addc_u32 s15, s15, 0
	s_waitcnt vmcnt(12)
	v_pk_add_f32 v[36:37], v[36:37], v[84:85]
	v_pk_add_f32 v[38:39], v[38:39], v[86:87]
	v_pk_add_f32 v[40:41], v[40:41], v[88:89]
	v_pk_add_f32 v[42:43], v[42:43], v[90:91]
	v_pk_add_f32 v[44:45], v[44:45], v[92:93]
	v_pk_add_f32 v[46:47], v[46:47], v[94:95]
	v_pk_add_f32 v[48:49], v[48:49], v[96:97]
	v_pk_add_f32 v[50:51], v[50:51], v[98:99]
	s_waitcnt vmcnt(8)
	v_pk_add_f32 v[36:37], v[36:37], v[100:101]
	v_pk_add_f32 v[38:39], v[38:39], v[102:103]
	v_pk_add_f32 v[40:41], v[40:41], v[104:105]
	v_pk_add_f32 v[42:43], v[42:43], v[106:107]
	v_pk_add_f32 v[44:45], v[44:45], v[108:109]
	v_pk_add_f32 v[46:47], v[46:47], v[110:111]
	v_pk_add_f32 v[48:49], v[48:49], v[112:113]
	v_pk_add_f32 v[50:51], v[50:51], v[114:115]
	s_waitcnt vmcnt(4)
	v_pk_add_f32 v[36:37], v[36:37], v[116:117]
	v_pk_add_f32 v[38:39], v[38:39], v[118:119]
	v_pk_add_f32 v[40:41], v[40:41], v[120:121]
	v_pk_add_f32 v[42:43], v[42:43], v[122:123]
	v_pk_add_f32 v[44:45], v[44:45], v[124:125]
	v_pk_add_f32 v[46:47], v[46:47], v[126:127]
	v_pk_add_f32 v[48:49], v[48:49], v[128:129]
	v_pk_add_f32 v[50:51], v[50:51], v[130:131]
	s_waitcnt vmcnt(0)
	v_pk_add_f32 v[36:37], v[36:37], v[132:133]
	v_pk_add_f32 v[38:39], v[38:39], v[134:135]
	v_pk_add_f32 v[40:41], v[40:41], v[136:137]
	v_pk_add_f32 v[42:43], v[42:43], v[138:139]
	v_pk_add_f32 v[44:45], v[44:45], v[140:141]
	v_pk_add_f32 v[46:47], v[46:47], v[142:143]
	v_pk_add_f32 v[48:49], v[48:49], v[144:145]
	v_pk_add_f32 v[50:51], v[50:51], v[146:147]
	v_pk_mul_f32 v[70:71], v[36:37], v[36:37]
	v_pk_mul_f32 v[72:73], v[38:39], v[38:39]
	v_pk_fma_f32 v[70:71], v[40:41], v[40:41], v[70:71]
	v_pk_fma_f32 v[72:73], v[42:43], v[42:43], v[72:73]
	v_pk_fma_f32 v[70:71], v[44:45], v[44:45], v[70:71]
	v_pk_fma_f32 v[72:73], v[46:47], v[46:47], v[72:73]
	v_pk_fma_f32 v[70:71], v[48:49], v[48:49], v[70:71]
	v_pk_fma_f32 v[72:73], v[50:51], v[50:51], v[72:73]
	v_pk_add_f32 v[70:71], v[70:71], v[72:73]
	s_nop 0
	v_add_f32_e32 v70, v70, v71
	s_nop 1
	v_add_f32_dpp v70, v70, v70 quad_perm:[1,0,3,2] row_mask:0xf bank_mask:0xf bound_ctrl:1
	s_nop 1
	v_add_f32_dpp v70, v70, v70 quad_perm:[2,3,0,1] row_mask:0xf bank_mask:0xf bound_ctrl:1
	s_nop 1
	v_add_f32_dpp v70, v70, v70 row_half_mirror row_mask:0xf bank_mask:0xf bound_ctrl:1
	s_nop 1
	v_add_f32_dpp v70, v70, v70 row_mirror row_mask:0xf bank_mask:0xf bound_ctrl:1
	v_mov_b32_e32 v71, v70
	s_nop 1
	v_permlane16_swap_b32_e32 v70, v71
	v_add_f32_e32 v70, v70, v71
	v_mov_b32_e32 v71, v70
	s_nop 1
	v_permlane32_swap_b32_e32 v70, v71
	v_add_f32_e32 v70, v70, v71
	v_fmamk_f32 v70, v70, 0x3a800000, v69
	v_mul_f32_e32 v71, 0x4f800000, v70
	v_cmp_gt_f32_e32 vcc, s35, v70
	s_nop 1
	v_cndmask_b32_e32 v70, v70, v71, vcc
	v_sqrt_f32_e32 v71, v70
	s_nop 1
	v_add_u32_e32 v72, -1, v71
	v_add_u32_e32 v73, 1, v71
	v_fma_f32 v74, -v72, v71, v70
	v_fma_f32 v75, -v73, v71, v70
	v_cmp_ge_f32_e64 s[0:1], 0, v74
	s_nop 1
	v_cndmask_b32_e64 v71, v71, v72, s[0:1]
	v_cmp_lt_f32_e64 s[0:1], 0, v75
	s_nop 1
	v_cndmask_b32_e64 v71, v71, v73, s[0:1]
	v_mul_f32_e32 v72, 0x37800000, v71
	s_nop 0
	v_cndmask_b32_e32 v71, v71, v72, vcc
	v_cmp_class_f32_e32 vcc, v70, v80
	s_nop 1
	v_cndmask_b32_e32 v70, v71, v70, vcc
	v_div_scale_f32 v71, s[0:1], v70, v70, 1.0
	v_rcp_f32_e32 v72, v71
	v_div_scale_f32 v73, vcc, 1.0, v70, 1.0
	v_fma_f32 v74, -v71, v72, 1.0
	v_fmac_f32_e32 v72, v74, v72
	v_mul_f32_e32 v74, v73, v72
	v_fma_f32 v75, -v71, v74, v73
	v_fmac_f32_e32 v74, v75, v72
	v_fma_f32 v71, -v71, v74, v73
	v_div_fmas_f32 v71, v71, v72, v74
	v_div_fixup_f32 v76, v71, v70, 1.0
	v_pk_mul_f32 v[36:37], v[36:37], v[76:77] op_sel_hi:[1,0]
	v_pk_mul_f32 v[38:39], v[38:39], v[76:77] op_sel_hi:[1,0]
	v_pk_mul_f32 v[40:41], v[40:41], v[76:77] op_sel_hi:[1,0]
	v_pk_mul_f32 v[42:43], v[42:43], v[76:77] op_sel_hi:[1,0]
	v_pk_mul_f32 v[44:45], v[44:45], v[76:77] op_sel_hi:[1,0]
	v_pk_mul_f32 v[46:47], v[46:47], v[76:77] op_sel_hi:[1,0]
	v_pk_mul_f32 v[48:49], v[48:49], v[76:77] op_sel_hi:[1,0]
	v_pk_mul_f32 v[50:51], v[50:51], v[76:77] op_sel_hi:[1,0]
	v_lshlrev_b32_e32 v52, 16, v148
	v_and_b32_e32 v53, s34, v148
	v_lshlrev_b32_e32 v54, 16, v149
	v_and_b32_e32 v55, s34, v149
	v_lshlrev_b32_e32 v56, 16, v150
	v_and_b32_e32 v57, s34, v150
	v_lshlrev_b32_e32 v58, 16, v151
	v_and_b32_e32 v59, s34, v151
	v_lshlrev_b32_e32 v60, 16, v152
	v_and_b32_e32 v61, s34, v152
	v_lshlrev_b32_e32 v62, 16, v153
	v_and_b32_e32 v63, s34, v153
	v_lshlrev_b32_e32 v64, 16, v154
	v_and_b32_e32 v65, s34, v154
	v_lshlrev_b32_e32 v66, 16, v155
	v_and_b32_e32 v67, s34, v155
	v_pk_fma_f32 v[52:53], v[36:37], v[2:3], v[52:53]
	v_pk_fma_f32 v[54:55], v[38:39], v[4:5], v[54:55]
	v_pk_fma_f32 v[56:57], v[40:41], v[6:7], v[56:57]
	v_pk_fma_f32 v[58:59], v[42:43], v[8:9], v[58:59]
	v_pk_fma_f32 v[60:61], v[44:45], v[10:11], v[60:61]
	v_pk_fma_f32 v[62:63], v[46:47], v[12:13], v[62:63]
	v_pk_fma_f32 v[64:65], v[48:49], v[14:15], v[64:65]
	v_pk_fma_f32 v[66:67], v[50:51], v[16:17], v[66:67]
	v_cvt_pk_bf16_f32 v148, v52, v53
	v_cvt_pk_bf16_f32 v149, v54, v55
	v_cvt_pk_bf16_f32 v150, v56, v57
	v_cvt_pk_bf16_f32 v151, v58, v59
	v_cvt_pk_bf16_f32 v152, v60, v61
	v_cvt_pk_bf16_f32 v153, v62, v63
	v_cvt_pk_bf16_f32 v154, v64, v65
	v_cvt_pk_bf16_f32 v155, v66, v67
	global_store_dwordx2 v1, v[148:149], s[10:11] offset:0
	global_store_dwordx2 v1, v[150:151], s[10:11] offset:512
	global_store_dwordx2 v1, v[152:153], s[10:11] offset:1024
	global_store_dwordx2 v1, v[154:155], s[10:11] offset:1536
	v_lshlrev_b32_e32 v52, 16, v148
	v_and_b32_e32 v53, s34, v148
	v_lshlrev_b32_e32 v54, 16, v149
	v_and_b32_e32 v55, s34, v149
	v_lshlrev_b32_e32 v56, 16, v150
	v_and_b32_e32 v57, s34, v150
	v_lshlrev_b32_e32 v58, 16, v151
	v_and_b32_e32 v59, s34, v151
	v_lshlrev_b32_e32 v60, 16, v152
	v_and_b32_e32 v61, s34, v152
	v_lshlrev_b32_e32 v62, 16, v153
	v_and_b32_e32 v63, s34, v153
	v_lshlrev_b32_e32 v64, 16, v154
	v_and_b32_e32 v65, s34, v154
	v_lshlrev_b32_e32 v66, 16, v155
	v_and_b32_e32 v67, s34, v155
	v_pk_mul_f32 v[70:71], v[52:53], v[52:53]
	v_pk_mul_f32 v[72:73], v[54:55], v[54:55]
	v_pk_fma_f32 v[70:71], v[56:57], v[56:57], v[70:71]
	v_pk_fma_f32 v[72:73], v[58:59], v[58:59], v[72:73]
	v_pk_fma_f32 v[70:71], v[60:61], v[60:61], v[70:71]
	v_pk_fma_f32 v[72:73], v[62:63], v[62:63], v[72:73]
	v_pk_fma_f32 v[70:71], v[64:65], v[64:65], v[70:71]
	v_pk_fma_f32 v[72:73], v[66:67], v[66:67], v[72:73]
	v_pk_add_f32 v[70:71], v[70:71], v[72:73]
	s_nop 0
	v_add_f32_e32 v70, v70, v71
	s_nop 1
	v_add_f32_dpp v70, v70, v70 quad_perm:[1,0,3,2] row_mask:0xf bank_mask:0xf bound_ctrl:1
	s_nop 1
	v_add_f32_dpp v70, v70, v70 quad_perm:[2,3,0,1] row_mask:0xf bank_mask:0xf bound_ctrl:1
	s_nop 1
	v_add_f32_dpp v70, v70, v70 row_half_mirror row_mask:0xf bank_mask:0xf bound_ctrl:1
	s_nop 1
	v_add_f32_dpp v70, v70, v70 row_mirror row_mask:0xf bank_mask:0xf bound_ctrl:1
	v_mov_b32_e32 v71, v70
	s_nop 1
	v_permlane16_swap_b32_e32 v70, v71
	v_add_f32_e32 v70, v70, v71
	v_mov_b32_e32 v71, v70
	s_nop 1
	v_permlane32_swap_b32_e32 v70, v71
	v_add_f32_e32 v70, v70, v71
	v_fmamk_f32 v70, v70, 0x3a800000, v69
	v_mul_f32_e32 v71, 0x4f800000, v70
	v_cmp_gt_f32_e32 vcc, s35, v70
	s_nop 1
	v_cndmask_b32_e32 v70, v70, v71, vcc
	v_sqrt_f32_e32 v71, v70
	s_nop 1
	v_add_u32_e32 v72, -1, v71
	v_add_u32_e32 v73, 1, v71
	v_fma_f32 v74, -v72, v71, v70
	v_fma_f32 v75, -v73, v71, v70
	v_cmp_ge_f32_e64 s[0:1], 0, v74
	s_nop 1
	v_cndmask_b32_e64 v71, v71, v72, s[0:1]
	v_cmp_lt_f32_e64 s[0:1], 0, v75
	s_nop 1
	v_cndmask_b32_e64 v71, v71, v73, s[0:1]
	v_mul_f32_e32 v72, 0x37800000, v71
	s_nop 0
	v_cndmask_b32_e32 v71, v71, v72, vcc
	v_cmp_class_f32_e32 vcc, v70, v80
	s_nop 1
	v_cndmask_b32_e32 v70, v71, v70, vcc
	v_div_scale_f32 v71, s[0:1], v70, v70, 1.0
	v_rcp_f32_e32 v72, v71
	v_div_scale_f32 v73, vcc, 1.0, v70, 1.0
	v_fma_f32 v74, -v71, v72, 1.0
	v_fmac_f32_e32 v72, v74, v72
	v_mul_f32_e32 v74, v73, v72
	v_fma_f32 v75, -v71, v74, v73
	v_fmac_f32_e32 v74, v75, v72
	v_fma_f32 v71, -v71, v74, v73
	v_div_fmas_f32 v71, v71, v72, v74
	v_div_fixup_f32 v76, v71, v70, 1.0
	v_pk_mul_f32 v[52:53], v[52:53], v[76:77] op_sel_hi:[1,0]
	v_pk_mul_f32 v[54:55], v[54:55], v[76:77] op_sel_hi:[1,0]
	v_pk_mul_f32 v[56:57], v[56:57], v[76:77] op_sel_hi:[1,0]
	v_pk_mul_f32 v[58:59], v[58:59], v[76:77] op_sel_hi:[1,0]
	v_pk_mul_f32 v[60:61], v[60:61], v[76:77] op_sel_hi:[1,0]
	v_pk_mul_f32 v[62:63], v[62:63], v[76:77] op_sel_hi:[1,0]
	v_pk_mul_f32 v[64:65], v[64:65], v[76:77] op_sel_hi:[1,0]
	v_pk_mul_f32 v[66:67], v[66:67], v[76:77] op_sel_hi:[1,0]
	v_pk_mul_f32 v[52:53], v[52:53], v[20:21]
	v_pk_mul_f32 v[54:55], v[54:55], v[22:23]
	v_pk_mul_f32 v[56:57], v[56:57], v[24:25]
	v_pk_mul_f32 v[58:59], v[58:59], v[26:27]
	v_pk_mul_f32 v[60:61], v[60:61], v[28:29]
	v_pk_mul_f32 v[62:63], v[62:63], v[30:31]
	v_pk_mul_f32 v[64:65], v[64:65], v[32:33]
	v_pk_mul_f32 v[66:67], v[66:67], v[34:35]
	v_cvt_pk_bf16_f32 v148, v52, v53
	v_cvt_pk_bf16_f32 v149, v54, v55
	v_cvt_pk_bf16_f32 v150, v56, v57
	v_cvt_pk_bf16_f32 v151, v58, v59
	v_cvt_pk_bf16_f32 v152, v60, v61
	v_cvt_pk_bf16_f32 v153, v62, v63
	v_cvt_pk_bf16_f32 v154, v64, v65
	v_cvt_pk_bf16_f32 v155, v66, v67
	global_store_dwordx2 v1, v[148:149], s[12:13] offset:0
	global_store_dwordx2 v1, v[150:151], s[12:13] offset:512
	global_store_dwordx2 v1, v[152:153], s[12:13] offset:1024
	global_store_dwordx2 v1, v[154:155], s[12:13] offset:1536
.Lrw9_next:
	s_add_u32 s6, s6, s20
	s_addc_u32 s7, s7, 0
	s_add_u32 s8, s8, s20
	s_addc_u32 s9, s9, 0
	s_add_u32 s10, s10, s20
	s_addc_u32 s11, s11, 0
	s_add_u32 s12, s12, s20
	s_addc_u32 s13, s13, 0
	s_add_i32 s5, s5, s23
	s_branch .Lrw9_single
.Lrw9_done:
.LBB0_1631:
	s_cmp_lt_i32 s91, 11
	s_cbranch_scc1 .LBB0_1685
	s_waitcnt vmcnt(0)
	s_waitcnt lgkmcnt(0)
	s_barrier
	s_mov_b64 s[0:1], exec
	v_readlane_b32 s2, v255, 5
	v_readlane_b32 s3, v255, 6
	s_and_b64 s[2:3], s[0:1], s[2:3]
	s_mov_b64 exec, s[2:3]
	s_cbranch_execz .LBB0_1684
	s_add_u32 s2, s26, 0x4200
	s_addc_u32 s3, s27, 0
	s_add_i32 s4, 0, 0x24160
	v_mov_b32_e32 v1, s4
	s_waitcnt vmcnt(0) expcnt(0) lgkmcnt(0)
	ds_read_b32 v3, v1
	s_add_i32 s4, 0, 0x24164
	v_mov_b32_e32 v1, s4
	ds_read_b32 v1, v1
	s_waitcnt lgkmcnt(1)
	v_cmp_ne_u32_e32 vcc, 0, v3
	s_cbranch_vccnz .LBB0_1648
	s_add_u32 s4, s26, 0x4400
	s_addc_u32 s5, s27, 0
	s_add_u32 s6, s26, 0x4500
	s_addc_u32 s7, s27, 0
	s_add_u32 s8, s26, 0x4600
	s_addc_u32 s9, s27, 0
	s_add_u32 s10, s26, 0x4700
	s_addc_u32 s11, s27, 0
	s_add_u32 s12, s26, 0x4800
	s_addc_u32 s13, s27, 0
	s_add_u32 s14, s26, 0x4900
	s_addc_u32 s15, s27, 0
	s_add_u32 s16, s26, 0x4a00
	s_addc_u32 s17, s27, 0
	s_add_u32 s18, s26, 0x4b00
	s_addc_u32 s19, s27, 0
	s_add_u32 s20, s26, 0x4c00
	s_addc_u32 s21, s27, 0
	s_add_u32 s22, s26, 0x4d00
	s_addc_u32 s23, s27, 0
	s_add_u32 s30, s26, 0x4e00
	s_addc_u32 s31, s27, 0
	s_add_u32 s34, s26, 0x4f00
	s_addc_u32 s35, s27, 0
	v_readlane_b32 s40, v255, 0
	s_add_u32 s36, s26, 0x5000
	v_readlane_b32 s41, v255, 1
	s_addc_u32 s37, s27, 0
	s_load_dwordx2 s[28:29], s[40:41], 0x4
	s_add_u32 s38, s26, 0x5100
	s_addc_u32 s39, s27, 0
	s_add_u32 s40, s26, 0x5200
	s_addc_u32 s41, s27, 0
	s_add_u32 s42, s26, 0x5300
	s_waitcnt lgkmcnt(0)
	s_mul_i32 s25, s28, s33
	s_addc_u32 s43, s27, 0
	s_mul_i32 s25, s25, s29
	s_mov_b32 s28, 1
	v_mov_b32_e32 v17, 0
	s_branch .LBB0_1636

.LBB0_1856:
	s_cmp_lt_i32 s90, 13
	s_cselect_b64 s[0:1], -1, 0
	s_cmp_gt_i32 s91, 12
	s_cselect_b64 s[2:3], -1, 0
	s_and_b64 s[0:1], s[0:1], s[2:3]
	s_andn2_b64 vcc, exec, s[0:1]
	s_cbranch_vccnz .LBB0_1891
	s_lshl_b32 s0, s82, 3
	s_add_i32 s0, s0, s83
	s_cmpk_gt_i32 s0, 0x41ff
	s_waitcnt vmcnt(0)
	v_mbcnt_lo_u32_b32 v68, -1, 0
	v_mbcnt_hi_u32_b32 v68, -1, v68
	s_cbranch_scc1 .LBB0_1891
	s_waitcnt lgkmcnt(0)
	s_mov_b32 s4, s0
	v_mbcnt_lo_u32_b32 v1, -1, 0
	v_mbcnt_hi_u32_b32 v1, -1, v1
	v_lshlrev_b32_e32 v19, 4, v1
	v_lshlrev_b32_e32 v1, 3, v1
	s_add_u32 s14, s66, 0x5000
	s_addc_u32 s15, s67, 0
	global_load_dwordx4 v[2:5], v19, s[14:15] offset:0
	global_load_dwordx4 v[6:9], v19, s[14:15] offset:1024
	global_load_dwordx4 v[10:13], v19, s[14:15] offset:2048
	global_load_dwordx4 v[14:17], v19, s[14:15] offset:3072
	s_mov_b32 s34, 0xffff0000
	s_mov_b32 s35, 0xf800000
	v_mov_b32_e32 v69, 0x358637bd
	v_mov_b32_e32 v80, 0x260
	s_lshl_b32 s23, s33, 3
	s_lshl_b32 s20, s33, 14
	s_lshl_b32 s21, s33, 15
	s_mul_i32 s22, s23, 3
	s_sub_i32 s22, 0x4000, s22
	v_readlane_b32 s2, v255, 37
	v_readlane_b32 s3, v255, 38
	s_mov_b32 s5, s4
	s_lshl_b32 s36, s4, 11
	s_lshl_b32 s37, s4, 12
	s_add_u32 s6, s26, 0xae00000
	s_addc_u32 s7, s27, 0
	s_add_u32 s6, s6, s36
	s_addc_u32 s7, s7, 0
	s_add_u32 s8, s26, 0xf000000
	s_addc_u32 s9, s27, 0
	s_add_u32 s8, s8, s36
	s_addc_u32 s9, s9, 0
	s_add_u32 s10, s2, s37
	s_addc_u32 s11, s3, 0
.Lrw12_batch:
	s_cmp_lt_i32 s5, s22
	s_cbranch_scc0 .Lrw12_single
	global_load_dwordx2 v[84:85], v1, s[6:7] offset:0
	global_load_dwordx2 v[86:87], v1, s[6:7] offset:512
	global_load_dwordx2 v[88:89], v1, s[6:7] offset:1024
	global_load_dwordx2 v[90:91], v1, s[6:7] offset:1536
	global_load_dwordx2 v[92:93], v1, s[8:9] offset:0
	global_load_dwordx2 v[94:95], v1, s[8:9] offset:512
	global_load_dwordx2 v[96:97], v1, s[8:9] offset:1024
	global_load_dwordx2 v[98:99], v1, s[8:9] offset:1536
	s_add_u32 s6, s6, s20
	s_addc_u32 s7, s7, 0
	s_add_u32 s8, s8, s20
	s_addc_u32 s9, s9, 0
	global_load_dwordx2 v[100:101], v1, s[6:7] offset:0
	global_load_dwordx2 v[102:103], v1, s[6:7] offset:512
	global_load_dwordx2 v[104:105], v1, s[6:7] offset:1024
	global_load_dwordx2 v[106:107], v1, s[6:7] offset:1536
	global_load_dwordx2 v[108:109], v1, s[8:9] offset:0
	global_load_dwordx2 v[110:111], v1, s[8:9] offset:512
	global_load_dwordx2 v[112:113], v1, s[8:9] offset:1024
	global_load_dwordx2 v[114:115], v1, s[8:9] offset:1536
	s_add_u32 s6, s6, s20
	s_addc_u32 s7, s7, 0
	s_add_u32 s8, s8, s20
	s_addc_u32 s9, s9, 0
	global_load_dwordx2 v[116:117], v1, s[6:7] offset:0
	global_load_dwordx2 v[118:119], v1, s[6:7] offset:512
	global_load_dwordx2 v[120:121], v1, s[6:7] offset:1024
	global_load_dwordx2 v[122:123], v1, s[6:7] offset:1536
	global_load_dwordx2 v[124:125], v1, s[8:9] offset:0
	global_load_dwordx2 v[126:127], v1, s[8:9] offset:512
	global_load_dwordx2 v[128:129], v1, s[8:9] offset:1024
	global_load_dwordx2 v[130:131], v1, s[8:9] offset:1536
	s_add_u32 s6, s6, s20
	s_addc_u32 s7, s7, 0
	s_add_u32 s8, s8, s20
	s_addc_u32 s9, s9, 0
	global_load_dwordx2 v[132:133], v1, s[6:7] offset:0
	global_load_dwordx2 v[134:135], v1, s[6:7] offset:512
	global_load_dwordx2 v[136:137], v1, s[6:7] offset:1024
	global_load_dwordx2 v[138:139], v1, s[6:7] offset:1536
	global_load_dwordx2 v[140:141], v1, s[8:9] offset:0
	global_load_dwordx2 v[142:143], v1, s[8:9] offset:512
	global_load_dwordx2 v[144:145], v1, s[8:9] offset:1024
	global_load_dwordx2 v[146:147], v1, s[8:9] offset:1536
	s_add_u32 s6, s6, s20
	s_addc_u32 s7, s7, 0
	s_add_u32 s8, s8, s20
	s_addc_u32 s9, s9, 0
	s_waitcnt vmcnt(24)
	v_lshlrev_b32_e32 v36, 16, v84
	v_and_b32_e32 v37, s34, v84
	v_lshlrev_b32_e32 v38, 16, v85
	v_and_b32_e32 v39, s34, v85
	v_lshlrev_b32_e32 v40, 16, v86
	v_and_b32_e32 v41, s34, v86
	v_lshlrev_b32_e32 v42, 16, v87
	v_and_b32_e32 v43, s34, v87
	v_lshlrev_b32_e32 v44, 16, v88
	v_and_b32_e32 v45, s34, v88
	v_lshlrev_b32_e32 v46, 16, v89
	v_and_b32_e32 v47, s34, v89
	v_lshlrev_b32_e32 v48, 16, v90
	v_and_b32_e32 v49, s34, v90
	v_lshlrev_b32_e32 v50, 16, v91
	v_and_b32_e32 v51, s34, v91
	v_pk_mul_f32 v[70:71], v[36:37], v[36:37]
	v_pk_mul_f32 v[72:73], v[38:39], v[38:39]
	v_pk_fma_f32 v[70:71], v[40:41], v[40:41], v[70:71]
	v_pk_fma_f32 v[72:73], v[42:43], v[42:43], v[72:73]
	v_pk_fma_f32 v[70:71], v[44:45], v[44:45], v[70:71]
	v_pk_fma_f32 v[72:73], v[46:47], v[46:47], v[72:73]
	v_pk_fma_f32 v[70:71], v[48:49], v[48:49], v[70:71]
	v_pk_fma_f32 v[72:73], v[50:51], v[50:51], v[72:73]
	v_pk_add_f32 v[70:71], v[70:71], v[72:73]
	s_nop 0
	v_add_f32_e32 v70, v70, v71
	s_nop 1
	v_add_f32_dpp v70, v70, v70 quad_perm:[1,0,3,2] row_mask:0xf bank_mask:0xf bound_ctrl:1
	s_nop 1
	v_add_f32_dpp v70, v70, v70 quad_perm:[2,3,0,1] row_mask:0xf bank_mask:0xf bound_ctrl:1
	s_nop 1
	v_add_f32_dpp v70, v70, v70 row_half_mirror row_mask:0xf bank_mask:0xf bound_ctrl:1
	s_nop 1
	v_add_f32_dpp v70, v70, v70 row_mirror row_mask:0xf bank_mask:0xf bound_ctrl:1
	v_mov_b32_e32 v71, v70
	s_nop 1
	v_permlane16_swap_b32_e32 v70, v71
	v_add_f32_e32 v70, v70, v71
	v_mov_b32_e32 v71, v70
	s_nop 1
	v_permlane32_swap_b32_e32 v70, v71
	v_add_f32_e32 v70, v70, v71
	v_fmamk_f32 v70, v70, 0x3a800000, v69
	v_mul_f32_e32 v71, 0x4f800000, v70
	v_cmp_gt_f32_e32 vcc, s35, v70
	s_nop 1
	v_cndmask_b32_e32 v70, v70, v71, vcc
	v_sqrt_f32_e32 v71, v70
	s_nop 1
	v_add_u32_e32 v72, -1, v71
	v_add_u32_e32 v73, 1, v71
	v_fma_f32 v74, -v72, v71, v70
	v_fma_f32 v75, -v73, v71, v70
	v_cmp_ge_f32_e64 s[0:1], 0, v74
	s_nop 1
	v_cndmask_b32_e64 v71, v71, v72, s[0:1]
	v_cmp_lt_f32_e64 s[0:1], 0, v75
	s_nop 1
	v_cndmask_b32_e64 v71, v71, v73, s[0:1]
	v_mul_f32_e32 v72, 0x37800000, v71
	s_nop 0
	v_cndmask_b32_e32 v71, v71, v72, vcc
	v_cmp_class_f32_e32 vcc, v70, v80
	s_nop 1
	v_cndmask_b32_e32 v70, v71, v70, vcc
	v_div_scale_f32 v71, s[0:1], v70, v70, 0.5
	v_rcp_f32_e32 v72, v71
	v_div_scale_f32 v73, vcc, 0.5, v70, 0.5
	v_fma_f32 v74, -v71, v72, 1.0
	v_fmac_f32_e32 v72, v74, v72
	v_mul_f32_e32 v74, v73, v72
	v_fma_f32 v75, -v71, v74, v73
	v_fmac_f32_e32 v74, v75, v72
	v_fma_f32 v71, -v71, v74, v73
	v_div_fmas_f32 v71, v71, v72, v74
	v_div_fixup_f32 v76, v71, v70, 0.5
	v_pk_mul_f32 v[36:37], v[36:37], v[76:77] op_sel_hi:[1,0]
	v_pk_mul_f32 v[38:39], v[38:39], v[76:77] op_sel_hi:[1,0]
	v_pk_mul_f32 v[40:41], v[40:41], v[76:77] op_sel_hi:[1,0]
	v_pk_mul_f32 v[42:43], v[42:43], v[76:77] op_sel_hi:[1,0]
	v_pk_mul_f32 v[44:45], v[44:45], v[76:77] op_sel_hi:[1,0]
	v_pk_mul_f32 v[46:47], v[46:47], v[76:77] op_sel_hi:[1,0]
	v_pk_mul_f32 v[48:49], v[48:49], v[76:77] op_sel_hi:[1,0]
	v_pk_mul_f32 v[50:51], v[50:51], v[76:77] op_sel_hi:[1,0]
	v_lshlrev_b32_e32 v52, 16, v92
	v_and_b32_e32 v53, s34, v92
	v_lshlrev_b32_e32 v54, 16, v93
	v_and_b32_e32 v55, s34, v93
	v_lshlrev_b32_e32 v56, 16, v94
	v_and_b32_e32 v57, s34, v94
	v_lshlrev_b32_e32 v58, 16, v95
	v_and_b32_e32 v59, s34, v95
	v_lshlrev_b32_e32 v60, 16, v96
	v_and_b32_e32 v61, s34, v96
	v_lshlrev_b32_e32 v62, 16, v97
	v_and_b32_e32 v63, s34, v97
	v_lshlrev_b32_e32 v64, 16, v98
	v_and_b32_e32 v65, s34, v98
	v_lshlrev_b32_e32 v66, 16, v99
	v_and_b32_e32 v67, s34, v99
	v_pk_fma_f32 v[52:53], v[36:37], v[2:3], v[52:53]
	v_pk_fma_f32 v[54:55], v[38:39], v[4:5], v[54:55]
	v_pk_fma_f32 v[56:57], v[40:41], v[6:7], v[56:57]
	v_pk_fma_f32 v[58:59], v[42:43], v[8:9], v[58:59]
	v_pk_fma_f32 v[60:61], v[44:45], v[10:11], v[60:61]
	v_pk_fma_f32 v[62:63], v[46:47], v[12:13], v[62:63]
	v_pk_fma_f32 v[64:65], v[48:49], v[14:15], v[64:65]
	v_pk_fma_f32 v[66:67], v[50:51], v[16:17], v[66:67]
	global_store_dwordx4 v19, v[52:55], s[10:11] offset:0 nt
	global_store_dwordx4 v19, v[56:59], s[10:11] offset:1024 nt
	global_store_dwordx4 v19, v[60:63], s[10:11] offset:2048 nt
	global_store_dwordx4 v19, v[64:67], s[10:11] offset:3072 nt
	s_add_u32 s10, s10, s21
	s_addc_u32 s11, s11, 0
	s_waitcnt vmcnt(20)
	v_lshlrev_b32_e32 v36, 16, v100
	v_and_b32_e32 v37, s34, v100
	v_lshlrev_b32_e32 v38, 16, v101
	v_and_b32_e32 v39, s34, v101
	v_lshlrev_b32_e32 v40, 16, v102
	v_and_b32_e32 v41, s34, v102
	v_lshlrev_b32_e32 v42, 16, v103
	v_and_b32_e32 v43, s34, v103
	v_lshlrev_b32_e32 v44, 16, v104
	v_and_b32_e32 v45, s34, v104
	v_lshlrev_b32_e32 v46, 16, v105
	v_and_b32_e32 v47, s34, v105
	v_lshlrev_b32_e32 v48, 16, v106
	v_and_b32_e32 v49, s34, v106
	v_lshlrev_b32_e32 v50, 16, v107
	v_and_b32_e32 v51, s34, v107
	v_pk_mul_f32 v[70:71], v[36:37], v[36:37]
	v_pk_mul_f32 v[72:73], v[38:39], v[38:39]
	v_pk_fma_f32 v[70:71], v[40:41], v[40:41], v[70:71]
	v_pk_fma_f32 v[72:73], v[42:43], v[42:43], v[72:73]
	v_pk_fma_f32 v[70:71], v[44:45], v[44:45], v[70:71]
	v_pk_fma_f32 v[72:73], v[46:47], v[46:47], v[72:73]
	v_pk_fma_f32 v[70:71], v[48:49], v[48:49], v[70:71]
	v_pk_fma_f32 v[72:73], v[50:51], v[50:51], v[72:73]
	v_pk_add_f32 v[70:71], v[70:71], v[72:73]
	s_nop 0
	v_add_f32_e32 v70, v70, v71
	s_nop 1
	v_add_f32_dpp v70, v70, v70 quad_perm:[1,0,3,2] row_mask:0xf bank_mask:0xf bound_ctrl:1
	s_nop 1
	v_add_f32_dpp v70, v70, v70 quad_perm:[2,3,0,1] row_mask:0xf bank_mask:0xf bound_ctrl:1
	s_nop 1
	v_add_f32_dpp v70, v70, v70 row_half_mirror row_mask:0xf bank_mask:0xf bound_ctrl:1
	s_nop 1
	v_add_f32_dpp v70, v70, v70 row_mirror row_mask:0xf bank_mask:0xf bound_ctrl:1
	v_mov_b32_e32 v71, v70
	s_nop 1
	v_permlane16_swap_b32_e32 v70, v71
	v_add_f32_e32 v70, v70, v71
	v_mov_b32_e32 v71, v70
	s_nop 1
	v_permlane32_swap_b32_e32 v70, v71
	v_add_f32_e32 v70, v70, v71
	v_fmamk_f32 v70, v70, 0x3a800000, v69
	v_mul_f32_e32 v71, 0x4f800000, v70
	v_cmp_gt_f32_e32 vcc, s35, v70
	s_nop 1
	v_cndmask_b32_e32 v70, v70, v71, vcc
	v_sqrt_f32_e32 v71, v70
	s_nop 1
	v_add_u32_e32 v72, -1, v71
	v_add_u32_e32 v73, 1, v71
	v_fma_f32 v74, -v72, v71, v70
	v_fma_f32 v75, -v73, v71, v70
	v_cmp_ge_f32_e64 s[0:1], 0, v74
	s_nop 1
	v_cndmask_b32_e64 v71, v71, v72, s[0:1]
	v_cmp_lt_f32_e64 s[0:1], 0, v75
	s_nop 1
	v_cndmask_b32_e64 v71, v71, v73, s[0:1]
	v_mul_f32_e32 v72, 0x37800000, v71
	s_nop 0
	v_cndmask_b32_e32 v71, v71, v72, vcc
	v_cmp_class_f32_e32 vcc, v70, v80
	s_nop 1
	v_cndmask_b32_e32 v70, v71, v70, vcc
	v_div_scale_f32 v71, s[0:1], v70, v70, 0.5
	v_rcp_f32_e32 v72, v71
	v_div_scale_f32 v73, vcc, 0.5, v70, 0.5
	v_fma_f32 v74, -v71, v72, 1.0
	v_fmac_f32_e32 v72, v74, v72
	v_mul_f32_e32 v74, v73, v72
	v_fma_f32 v75, -v71, v74, v73
	v_fmac_f32_e32 v74, v75, v72
	v_fma_f32 v71, -v71, v74, v73
	v_div_fmas_f32 v71, v71, v72, v74
	v_div_fixup_f32 v76, v71, v70, 0.5
	v_pk_mul_f32 v[36:37], v[36:37], v[76:77] op_sel_hi:[1,0]
	v_pk_mul_f32 v[38:39], v[38:39], v[76:77] op_sel_hi:[1,0]
	v_pk_mul_f32 v[40:41], v[40:41], v[76:77] op_sel_hi:[1,0]
	v_pk_mul_f32 v[42:43], v[42:43], v[76:77] op_sel_hi:[1,0]
	v_pk_mul_f32 v[44:45], v[44:45], v[76:77] op_sel_hi:[1,0]
	v_pk_mul_f32 v[46:47], v[46:47], v[76:77] op_sel_hi:[1,0]
	v_pk_mul_f32 v[48:49], v[48:49], v[76:77] op_sel_hi:[1,0]
	v_pk_mul_f32 v[50:51], v[50:51], v[76:77] op_sel_hi:[1,0]
	v_lshlrev_b32_e32 v52, 16, v108
	v_and_b32_e32 v53, s34, v108
	v_lshlrev_b32_e32 v54, 16, v109
	v_and_b32_e32 v55, s34, v109
	v_lshlrev_b32_e32 v56, 16, v110
	v_and_b32_e32 v57, s34, v110
	v_lshlrev_b32_e32 v58, 16, v111
	v_and_b32_e32 v59, s34, v111
	v_lshlrev_b32_e32 v60, 16, v112
	v_and_b32_e32 v61, s34, v112
	v_lshlrev_b32_e32 v62, 16, v113
	v_and_b32_e32 v63, s34, v113
	v_lshlrev_b32_e32 v64, 16, v114
	v_and_b32_e32 v65, s34, v114
	v_lshlrev_b32_e32 v66, 16, v115
	v_and_b32_e32 v67, s34, v115
	v_pk_fma_f32 v[52:53], v[36:37], v[2:3], v[52:53]
	v_pk_fma_f32 v[54:55], v[38:39], v[4:5], v[54:55]
	v_pk_fma_f32 v[56:57], v[40:41], v[6:7], v[56:57]
	v_pk_fma_f32 v[58:59], v[42:43], v[8:9], v[58:59]
	v_pk_fma_f32 v[60:61], v[44:45], v[10:11], v[60:61]
	v_pk_fma_f32 v[62:63], v[46:47], v[12:13], v[62:63]
	v_pk_fma_f32 v[64:65], v[48:49], v[14:15], v[64:65]
	v_pk_fma_f32 v[66:67], v[50:51], v[16:17], v[66:67]
	global_store_dwordx4 v19, v[52:55], s[10:11] offset:0 nt
	global_store_dwordx4 v19, v[56:59], s[10:11] offset:1024 nt
	global_store_dwordx4 v19, v[60:63], s[10:11] offset:2048 nt
	global_store_dwordx4 v19, v[64:67], s[10:11] offset:3072 nt
	s_add_u32 s10, s10, s21
	s_addc_u32 s11, s11, 0
	s_waitcnt vmcnt(16)
	v_lshlrev_b32_e32 v36, 16, v116
	v_and_b32_e32 v37, s34, v116
	v_lshlrev_b32_e32 v38, 16, v117
	v_and_b32_e32 v39, s34, v117
	v_lshlrev_b32_e32 v40, 16, v118
	v_and_b32_e32 v41, s34, v118
	v_lshlrev_b32_e32 v42, 16, v119
	v_and_b32_e32 v43, s34, v119
	v_lshlrev_b32_e32 v44, 16, v120
	v_and_b32_e32 v45, s34, v120
	v_lshlrev_b32_e32 v46, 16, v121
	v_and_b32_e32 v47, s34, v121
	v_lshlrev_b32_e32 v48, 16, v122
	v_and_b32_e32 v49, s34, v122
	v_lshlrev_b32_e32 v50, 16, v123
	v_and_b32_e32 v51, s34, v123
	v_pk_mul_f32 v[70:71], v[36:37], v[36:37]
	v_pk_mul_f32 v[72:73], v[38:39], v[38:39]
	v_pk_fma_f32 v[70:71], v[40:41], v[40:41], v[70:71]
	v_pk_fma_f32 v[72:73], v[42:43], v[42:43], v[72:73]
	v_pk_fma_f32 v[70:71], v[44:45], v[44:45], v[70:71]
	v_pk_fma_f32 v[72:73], v[46:47], v[46:47], v[72:73]
	v_pk_fma_f32 v[70:71], v[48:49], v[48:49], v[70:71]
	v_pk_fma_f32 v[72:73], v[50:51], v[50:51], v[72:73]
	v_pk_add_f32 v[70:71], v[70:71], v[72:73]
	s_nop 0
	v_add_f32_e32 v70, v70, v71
	s_nop 1
	v_add_f32_dpp v70, v70, v70 quad_perm:[1,0,3,2] row_mask:0xf bank_mask:0xf bound_ctrl:1
	s_nop 1
	v_add_f32_dpp v70, v70, v70 quad_perm:[2,3,0,1] row_mask:0xf bank_mask:0xf bound_ctrl:1
	s_nop 1
	v_add_f32_dpp v70, v70, v70 row_half_mirror row_mask:0xf bank_mask:0xf bound_ctrl:1
	s_nop 1
	v_add_f32_dpp v70, v70, v70 row_mirror row_mask:0xf bank_mask:0xf bound_ctrl:1
	v_mov_b32_e32 v71, v70
	s_nop 1
	v_permlane16_swap_b32_e32 v70, v71
	v_add_f32_e32 v70, v70, v71
	v_mov_b32_e32 v71, v70
	s_nop 1
	v_permlane32_swap_b32_e32 v70, v71
	v_add_f32_e32 v70, v70, v71
	v_fmamk_f32 v70, v70, 0x3a800000, v69
	v_mul_f32_e32 v71, 0x4f800000, v70
	v_cmp_gt_f32_e32 vcc, s35, v70
	s_nop 1
	v_cndmask_b32_e32 v70, v70, v71, vcc
	v_sqrt_f32_e32 v71, v70
	s_nop 1
	v_add_u32_e32 v72, -1, v71
	v_add_u32_e32 v73, 1, v71
	v_fma_f32 v74, -v72, v71, v70
	v_fma_f32 v75, -v73, v71, v70
	v_cmp_ge_f32_e64 s[0:1], 0, v74
	s_nop 1
	v_cndmask_b32_e64 v71, v71, v72, s[0:1]
	v_cmp_lt_f32_e64 s[0:1], 0, v75
	s_nop 1
	v_cndmask_b32_e64 v71, v71, v73, s[0:1]
	v_mul_f32_e32 v72, 0x37800000, v71
	s_nop 0
	v_cndmask_b32_e32 v71, v71, v72, vcc
	v_cmp_class_f32_e32 vcc, v70, v80
	s_nop 1
	v_cndmask_b32_e32 v70, v71, v70, vcc
	v_div_scale_f32 v71, s[0:1], v70, v70, 0.5
	v_rcp_f32_e32 v72, v71
	v_div_scale_f32 v73, vcc, 0.5, v70, 0.5
	v_fma_f32 v74, -v71, v72, 1.0
	v_fmac_f32_e32 v72, v74, v72
	v_mul_f32_e32 v74, v73, v72
	v_fma_f32 v75, -v71, v74, v73
	v_fmac_f32_e32 v74, v75, v72
	v_fma_f32 v71, -v71, v74, v73
	v_div_fmas_f32 v71, v71, v72, v74
	v_div_fixup_f32 v76, v71, v70, 0.5
	v_pk_mul_f32 v[36:37], v[36:37], v[76:77] op_sel_hi:[1,0]
	v_pk_mul_f32 v[38:39], v[38:39], v[76:77] op_sel_hi:[1,0]
	v_pk_mul_f32 v[40:41], v[40:41], v[76:77] op_sel_hi:[1,0]
	v_pk_mul_f32 v[42:43], v[42:43], v[76:77] op_sel_hi:[1,0]
	v_pk_mul_f32 v[44:45], v[44:45], v[76:77] op_sel_hi:[1,0]
	v_pk_mul_f32 v[46:47], v[46:47], v[76:77] op_sel_hi:[1,0]
	v_pk_mul_f32 v[48:49], v[48:49], v[76:77] op_sel_hi:[1,0]
	v_pk_mul_f32 v[50:51], v[50:51], v[76:77] op_sel_hi:[1,0]
	v_lshlrev_b32_e32 v52, 16, v124
	v_and_b32_e32 v53, s34, v124
	v_lshlrev_b32_e32 v54, 16, v125
	v_and_b32_e32 v55, s34, v125
	v_lshlrev_b32_e32 v56, 16, v126
	v_and_b32_e32 v57, s34, v126
	v_lshlrev_b32_e32 v58, 16, v127
	v_and_b32_e32 v59, s34, v127
	v_lshlrev_b32_e32 v60, 16, v128
	v_and_b32_e32 v61, s34, v128
	v_lshlrev_b32_e32 v62, 16, v129
	v_and_b32_e32 v63, s34, v129
	v_lshlrev_b32_e32 v64, 16, v130
	v_and_b32_e32 v65, s34, v130
	v_lshlrev_b32_e32 v66, 16, v131
	v_and_b32_e32 v67, s34, v131
	v_pk_fma_f32 v[52:53], v[36:37], v[2:3], v[52:53]
	v_pk_fma_f32 v[54:55], v[38:39], v[4:5], v[54:55]
	v_pk_fma_f32 v[56:57], v[40:41], v[6:7], v[56:57]
	v_pk_fma_f32 v[58:59], v[42:43], v[8:9], v[58:59]
	v_pk_fma_f32 v[60:61], v[44:45], v[10:11], v[60:61]
	v_pk_fma_f32 v[62:63], v[46:47], v[12:13], v[62:63]
	v_pk_fma_f32 v[64:65], v[48:49], v[14:15], v[64:65]
	v_pk_fma_f32 v[66:67], v[50:51], v[16:17], v[66:67]
	global_store_dwordx4 v19, v[52:55], s[10:11] offset:0 nt
	global_store_dwordx4 v19, v[56:59], s[10:11] offset:1024 nt
	global_store_dwordx4 v19, v[60:63], s[10:11] offset:2048 nt
	global_store_dwordx4 v19, v[64:67], s[10:11] offset:3072 nt
	s_add_u32 s10, s10, s21
	s_addc_u32 s11, s11, 0
	s_waitcnt vmcnt(12)
	v_lshlrev_b32_e32 v36, 16, v132
	v_and_b32_e32 v37, s34, v132
	v_lshlrev_b32_e32 v38, 16, v133
	v_and_b32_e32 v39, s34, v133
	v_lshlrev_b32_e32 v40, 16, v134
	v_and_b32_e32 v41, s34, v134
	v_lshlrev_b32_e32 v42, 16, v135
	v_and_b32_e32 v43, s34, v135
	v_lshlrev_b32_e32 v44, 16, v136
	v_and_b32_e32 v45, s34, v136
	v_lshlrev_b32_e32 v46, 16, v137
	v_and_b32_e32 v47, s34, v137
	v_lshlrev_b32_e32 v48, 16, v138
	v_and_b32_e32 v49, s34, v138
	v_lshlrev_b32_e32 v50, 16, v139
	v_and_b32_e32 v51, s34, v139
	v_pk_mul_f32 v[70:71], v[36:37], v[36:37]
	v_pk_mul_f32 v[72:73], v[38:39], v[38:39]
	v_pk_fma_f32 v[70:71], v[40:41], v[40:41], v[70:71]
	v_pk_fma_f32 v[72:73], v[42:43], v[42:43], v[72:73]
	v_pk_fma_f32 v[70:71], v[44:45], v[44:45], v[70:71]
	v_pk_fma_f32 v[72:73], v[46:47], v[46:47], v[72:73]
	v_pk_fma_f32 v[70:71], v[48:49], v[48:49], v[70:71]
	v_pk_fma_f32 v[72:73], v[50:51], v[50:51], v[72:73]
	v_pk_add_f32 v[70:71], v[70:71], v[72:73]
	s_nop 0
	v_add_f32_e32 v70, v70, v71
	s_nop 1
	v_add_f32_dpp v70, v70, v70 quad_perm:[1,0,3,2] row_mask:0xf bank_mask:0xf bound_ctrl:1
	s_nop 1
	v_add_f32_dpp v70, v70, v70 quad_perm:[2,3,0,1] row_mask:0xf bank_mask:0xf bound_ctrl:1
	s_nop 1
	v_add_f32_dpp v70, v70, v70 row_half_mirror row_mask:0xf bank_mask:0xf bound_ctrl:1
	s_nop 1
	v_add_f32_dpp v70, v70, v70 row_mirror row_mask:0xf bank_mask:0xf bound_ctrl:1
	v_mov_b32_e32 v71, v70
	s_nop 1
	v_permlane16_swap_b32_e32 v70, v71
	v_add_f32_e32 v70, v70, v71
	v_mov_b32_e32 v71, v70
	s_nop 1
	v_permlane32_swap_b32_e32 v70, v71
	v_add_f32_e32 v70, v70, v71
	v_fmamk_f32 v70, v70, 0x3a800000, v69
	v_mul_f32_e32 v71, 0x4f800000, v70
	v_cmp_gt_f32_e32 vcc, s35, v70
	s_nop 1
	v_cndmask_b32_e32 v70, v70, v71, vcc
	v_sqrt_f32_e32 v71, v70
	s_nop 1
	v_add_u32_e32 v72, -1, v71
	v_add_u32_e32 v73, 1, v71
	v_fma_f32 v74, -v72, v71, v70
	v_fma_f32 v75, -v73, v71, v70
	v_cmp_ge_f32_e64 s[0:1], 0, v74
	s_nop 1
	v_cndmask_b32_e64 v71, v71, v72, s[0:1]
	v_cmp_lt_f32_e64 s[0:1], 0, v75
	s_nop 1
	v_cndmask_b32_e64 v71, v71, v73, s[0:1]
	v_mul_f32_e32 v72, 0x37800000, v71
	s_nop 0
	v_cndmask_b32_e32 v71, v71, v72, vcc
	v_cmp_class_f32_e32 vcc, v70, v80
	s_nop 1
	v_cndmask_b32_e32 v70, v71, v70, vcc
	v_div_scale_f32 v71, s[0:1], v70, v70, 0.5
	v_rcp_f32_e32 v72, v71
	v_div_scale_f32 v73, vcc, 0.5, v70, 0.5
	v_fma_f32 v74, -v71, v72, 1.0
	v_fmac_f32_e32 v72, v74, v72
	v_mul_f32_e32 v74, v73, v72
	v_fma_f32 v75, -v71, v74, v73
	v_fmac_f32_e32 v74, v75, v72
	v_fma_f32 v71, -v71, v74, v73
	v_div_fmas_f32 v71, v71, v72, v74
	v_div_fixup_f32 v76, v71, v70, 0.5
	v_pk_mul_f32 v[36:37], v[36:37], v[76:77] op_sel_hi:[1,0]
	v_pk_mul_f32 v[38:39], v[38:39], v[76:77] op_sel_hi:[1,0]
	v_pk_mul_f32 v[40:41], v[40:41], v[76:77] op_sel_hi:[1,0]
	v_pk_mul_f32 v[42:43], v[42:43], v[76:77] op_sel_hi:[1,0]
	v_pk_mul_f32 v[44:45], v[44:45], v[76:77] op_sel_hi:[1,0]
	v_pk_mul_f32 v[46:47], v[46:47], v[76:77] op_sel_hi:[1,0]
	v_pk_mul_f32 v[48:49], v[48:49], v[76:77] op_sel_hi:[1,0]
	v_pk_mul_f32 v[50:51], v[50:51], v[76:77] op_sel_hi:[1,0]
	v_lshlrev_b32_e32 v52, 16, v140
	v_and_b32_e32 v53, s34, v140
	v_lshlrev_b32_e32 v54, 16, v141
	v_and_b32_e32 v55, s34, v141
	v_lshlrev_b32_e32 v56, 16, v142
	v_and_b32_e32 v57, s34, v142
	v_lshlrev_b32_e32 v58, 16, v143
	v_and_b32_e32 v59, s34, v143
	v_lshlrev_b32_e32 v60, 16, v144
	v_and_b32_e32 v61, s34, v144
	v_lshlrev_b32_e32 v62, 16, v145
	v_and_b32_e32 v63, s34, v145
	v_lshlrev_b32_e32 v64, 16, v146
	v_and_b32_e32 v65, s34, v146
	v_lshlrev_b32_e32 v66, 16, v147
	v_and_b32_e32 v67, s34, v147
	v_pk_fma_f32 v[52:53], v[36:37], v[2:3], v[52:53]
	v_pk_fma_f32 v[54:55], v[38:39], v[4:5], v[54:55]
	v_pk_fma_f32 v[56:57], v[40:41], v[6:7], v[56:57]
	v_pk_fma_f32 v[58:59], v[42:43], v[8:9], v[58:59]
	v_pk_fma_f32 v[60:61], v[44:45], v[10:11], v[60:61]
	v_pk_fma_f32 v[62:63], v[46:47], v[12:13], v[62:63]
	v_pk_fma_f32 v[64:65], v[48:49], v[14:15], v[64:65]
	v_pk_fma_f32 v[66:67], v[50:51], v[16:17], v[66:67]
	global_store_dwordx4 v19, v[52:55], s[10:11] offset:0 nt
	global_store_dwordx4 v19, v[56:59], s[10:11] offset:1024 nt
	global_store_dwordx4 v19, v[60:63], s[10:11] offset:2048 nt
	global_store_dwordx4 v19, v[64:67], s[10:11] offset:3072 nt
	s_add_u32 s10, s10, s21
	s_addc_u32 s11, s11, 0
	s_lshl_b32 s36, s23, 2
	s_add_i32 s5, s5, s36
	s_branch .Lrw12_batch
.Lrw12_single:
	s_cmpk_lt_i32 s5, 0x4200
	s_cbranch_scc0 .Lrw12_done
	s_cmpk_lt_i32 s5, 0x4000
	s_cbranch_scc0 .Lrw12_sample
	global_load_dwordx2 v[84:85], v1, s[6:7] offset:0
	global_load_dwordx2 v[86:87], v1, s[6:7] offset:512
	global_load_dwordx2 v[88:89], v1, s[6:7] offset:1024
	global_load_dwordx2 v[90:91], v1, s[6:7] offset:1536
	global_load_dwordx2 v[92:93], v1, s[8:9] offset:0
	global_load_dwordx2 v[94:95], v1, s[8:9] offset:512
	global_load_dwordx2 v[96:97], v1, s[8:9] offset:1024
	global_load_dwordx2 v[98:99], v1, s[8:9] offset:1536
	s_waitcnt vmcnt(0)
	v_lshlrev_b32_e32 v36, 16, v84
	v_and_b32_e32 v37, s34, v84
	v_lshlrev_b32_e32 v38, 16, v85
	v_and_b32_e32 v39, s34, v85
	v_lshlrev_b32_e32 v40, 16, v86
	v_and_b32_e32 v41, s34, v86
	v_lshlrev_b32_e32 v42, 16, v87
	v_and_b32_e32 v43, s34, v87
	v_lshlrev_b32_e32 v44, 16, v88
	v_and_b32_e32 v45, s34, v88
	v_lshlrev_b32_e32 v46, 16, v89
	v_and_b32_e32 v47, s34, v89
	v_lshlrev_b32_e32 v48, 16, v90
	v_and_b32_e32 v49, s34, v90
	v_lshlrev_b32_e32 v50, 16, v91
	v_and_b32_e32 v51, s34, v91
	v_pk_mul_f32 v[70:71], v[36:37], v[36:37]
	v_pk_mul_f32 v[72:73], v[38:39], v[38:39]
	v_pk_fma_f32 v[70:71], v[40:41], v[40:41], v[70:71]
	v_pk_fma_f32 v[72:73], v[42:43], v[42:43], v[72:73]
	v_pk_fma_f32 v[70:71], v[44:45], v[44:45], v[70:71]
	v_pk_fma_f32 v[72:73], v[46:47], v[46:47], v[72:73]
	v_pk_fma_f32 v[70:71], v[48:49], v[48:49], v[70:71]
	v_pk_fma_f32 v[72:73], v[50:51], v[50:51], v[72:73]
	v_pk_add_f32 v[70:71], v[70:71], v[72:73]
	s_nop 0
	v_add_f32_e32 v70, v70, v71
	s_nop 1
	v_add_f32_dpp v70, v70, v70 quad_perm:[1,0,3,2] row_mask:0xf bank_mask:0xf bound_ctrl:1
	s_nop 1
	v_add_f32_dpp v70, v70, v70 quad_perm:[2,3,0,1] row_mask:0xf bank_mask:0xf bound_ctrl:1
	s_nop 1
	v_add_f32_dpp v70, v70, v70 row_half_mirror row_mask:0xf bank_mask:0xf bound_ctrl:1
	s_nop 1
	v_add_f32_dpp v70, v70, v70 row_mirror row_mask:0xf bank_mask:0xf bound_ctrl:1
	v_mov_b32_e32 v71, v70
	s_nop 1
	v_permlane16_swap_b32_e32 v70, v71
	v_add_f32_e32 v70, v70, v71
	v_mov_b32_e32 v71, v70
	s_nop 1
	v_permlane32_swap_b32_e32 v70, v71
	v_add_f32_e32 v70, v70, v71
	v_fmamk_f32 v70, v70, 0x3a800000, v69
	v_mul_f32_e32 v71, 0x4f800000, v70
	v_cmp_gt_f32_e32 vcc, s35, v70
	s_nop 1
	v_cndmask_b32_e32 v70, v70, v71, vcc
	v_sqrt_f32_e32 v71, v70
	s_nop 1
	v_add_u32_e32 v72, -1, v71
	v_add_u32_e32 v73, 1, v71
	v_fma_f32 v74, -v72, v71, v70
	v_fma_f32 v75, -v73, v71, v70
	v_cmp_ge_f32_e64 s[0:1], 0, v74
	s_nop 1
	v_cndmask_b32_e64 v71, v71, v72, s[0:1]
	v_cmp_lt_f32_e64 s[0:1], 0, v75
	s_nop 1
	v_cndmask_b32_e64 v71, v71, v73, s[0:1]
	v_mul_f32_e32 v72, 0x37800000, v71
	s_nop 0
	v_cndmask_b32_e32 v71, v71, v72, vcc
	v_cmp_class_f32_e32 vcc, v70, v80
	s_nop 1
	v_cndmask_b32_e32 v70, v71, v70, vcc
	v_div_scale_f32 v71, s[0:1], v70, v70, 0.5
	v_rcp_f32_e32 v72, v71
	v_div_scale_f32 v73, vcc, 0.5, v70, 0.5
	v_fma_f32 v74, -v71, v72, 1.0
	v_fmac_f32_e32 v72, v74, v72
	v_mul_f32_e32 v74, v73, v72
	v_fma_f32 v75, -v71, v74, v73
	v_fmac_f32_e32 v74, v75, v72
	v_fma_f32 v71, -v71, v74, v73
	v_div_fmas_f32 v71, v71, v72, v74
	v_div_fixup_f32 v76, v71, v70, 0.5
	v_pk_mul_f32 v[36:37], v[36:37], v[76:77] op_sel_hi:[1,0]
	v_pk_mul_f32 v[38:39], v[38:39], v[76:77] op_sel_hi:[1,0]
	v_pk_mul_f32 v[40:41], v[40:41], v[76:77] op_sel_hi:[1,0]
	v_pk_mul_f32 v[42:43], v[42:43], v[76:77] op_sel_hi:[1,0]
	v_pk_mul_f32 v[44:45], v[44:45], v[76:77] op_sel_hi:[1,0]
	v_pk_mul_f32 v[46:47], v[46:47], v[76:77] op_sel_hi:[1,0]
	v_pk_mul_f32 v[48:49], v[48:49], v[76:77] op_sel_hi:[1,0]
	v_pk_mul_f32 v[50:51], v[50:51], v[76:77] op_sel_hi:[1,0]
	v_lshlrev_b32_e32 v52, 16, v92
	v_and_b32_e32 v53, s34, v92
	v_lshlrev_b32_e32 v54, 16, v93
	v_and_b32_e32 v55, s34, v93
	v_lshlrev_b32_e32 v56, 16, v94
	v_and_b32_e32 v57, s34, v94
	v_lshlrev_b32_e32 v58, 16, v95
	v_and_b32_e32 v59, s34, v95
	v_lshlrev_b32_e32 v60, 16, v96
	v_and_b32_e32 v61, s34, v96
	v_lshlrev_b32_e32 v62, 16, v97
	v_and_b32_e32 v63, s34, v97
	v_lshlrev_b32_e32 v64, 16, v98
	v_and_b32_e32 v65, s34, v98
	v_lshlrev_b32_e32 v66, 16, v99
	v_and_b32_e32 v67, s34, v99
	v_pk_fma_f32 v[52:53], v[36:37], v[2:3], v[52:53]
	v_pk_fma_f32 v[54:55], v[38:39], v[4:5], v[54:55]
	v_pk_fma_f32 v[56:57], v[40:41], v[6:7], v[56:57]
	v_pk_fma_f32 v[58:59], v[42:43], v[8:9], v[58:59]
	v_pk_fma_f32 v[60:61], v[44:45], v[10:11], v[60:61]
	v_pk_fma_f32 v[62:63], v[46:47], v[12:13], v[62:63]
	v_pk_fma_f32 v[64:65], v[48:49], v[14:15], v[64:65]
	v_pk_fma_f32 v[66:67], v[50:51], v[16:17], v[66:67]
	global_store_dwordx4 v19, v[52:55], s[10:11] offset:0 nt
	global_store_dwordx4 v19, v[56:59], s[10:11] offset:1024 nt
	global_store_dwordx4 v19, v[60:63], s[10:11] offset:2048 nt
	global_store_dwordx4 v19, v[64:67], s[10:11] offset:3072 nt
	s_branch .Lrw12_next
.Lrw12_sample:
	s_sub_i32 s36, s5, 0x4000
	s_lshl_b32 s36, s36, 12
	s_add_u32 s14, s26, 0x32200000
	s_addc_u32 s15, s27, 0
	s_add_u32 s14, s14, s36
	s_addc_u32 s15, s15, 0
	global_load_dwordx2 v[148:149], v1, s[8:9] offset:0
	global_load_dwordx2 v[150:151], v1, s[8:9] offset:512
	global_load_dwordx2 v[152:153], v1, s[8:9] offset:1024
	global_load_dwordx2 v[154:155], v1, s[8:9] offset:1536
	v_mov_b32_e32 v36, 0
	v_mov_b32_e32 v37, 0
	v_mov_b32_e32 v38, 0
	v_mov_b32_e32 v39, 0
	v_mov_b32_e32 v40, 0
	v_mov_b32_e32 v41, 0
	v_mov_b32_e32 v42, 0
	v_mov_b32_e32 v43, 0
	v_mov_b32_e32 v44, 0
	v_mov_b32_e32 v45, 0
	v_mov_b32_e32 v46, 0
	v_mov_b32_e32 v47, 0
	v_mov_b32_e32 v48, 0
	v_mov_b32_e32 v49, 0
	v_mov_b32_e32 v50, 0
	v_mov_b32_e32 v51, 0
	global_load_dwordx4 v[84:87], v19, s[14:15] offset:0
	global_load_dwordx4 v[88:91], v19, s[14:15] offset:1024
	global_load_dwordx4 v[92:95], v19, s[14:15] offset:2048
	global_load_dwordx4 v[96:99], v19, s[14:15] offset:3072
	s_add_u32 s14, s14, 0x200000
	s_addc_u32 s15, s15, 0
	global_load_dwordx4 v[100:103], v19, s[14:15] offset:0
	global_load_dwordx4 v[104:107], v19, s[14:15] offset:1024
	global_load_dwordx4 v[108:111], v19, s[14:15] offset:2048
	global_load_dwordx4 v[112:115], v19, s[14:15] offset:3072
	s_add_u32 s14, s14, 0x200000
	s_addc_u32 s15, s15, 0
	global_load_dwordx4 v[116:119], v19, s[14:15] offset:0
	global_load_dwordx4 v[120:123], v19, s[14:15] offset:1024
	global_load_dwordx4 v[124:127], v19, s[14:15] offset:2048
	global_load_dwordx4 v[128:131], v19, s[14:15] offset:3072
	s_add_u32 s14, s14, 0x200000
	s_addc_u32 s15, s15, 0
	global_load_dwordx4 v[132:135], v19, s[14:15] offset:0
	global_load_dwordx4 v[136:139], v19, s[14:15] offset:1024
	global_load_dwordx4 v[140:143], v19, s[14:15] offset:2048
	global_load_dwordx4 v[144:147], v19, s[14:15] offset:3072
	s_add_u32 s14, s14, 0x200000
	s_addc_u32 s15, s15, 0
	s_waitcnt vmcnt(12)
	v_pk_add_f32 v[36:37], v[36:37], v[84:85]
	v_pk_add_f32 v[38:39], v[38:39], v[86:87]
	v_pk_add_f32 v[40:41], v[40:41], v[88:89]
	v_pk_add_f32 v[42:43], v[42:43], v[90:91]
	v_pk_add_f32 v[44:45], v[44:45], v[92:93]
	v_pk_add_f32 v[46:47], v[46:47], v[94:95]
	v_pk_add_f32 v[48:49], v[48:49], v[96:97]
	v_pk_add_f32 v[50:51], v[50:51], v[98:99]
	s_waitcnt vmcnt(8)
	v_pk_add_f32 v[36:37], v[36:37], v[100:101]
	v_pk_add_f32 v[38:39], v[38:39], v[102:103]
	v_pk_add_f32 v[40:41], v[40:41], v[104:105]
	v_pk_add_f32 v[42:43], v[42:43], v[106:107]
	v_pk_add_f32 v[44:45], v[44:45], v[108:109]
	v_pk_add_f32 v[46:47], v[46:47], v[110:111]
	v_pk_add_f32 v[48:49], v[48:49], v[112:113]
	v_pk_add_f32 v[50:51], v[50:51], v[114:115]
	s_waitcnt vmcnt(4)
	v_pk_add_f32 v[36:37], v[36:37], v[116:117]
	v_pk_add_f32 v[38:39], v[38:39], v[118:119]
	v_pk_add_f32 v[40:41], v[40:41], v[120:121]
	v_pk_add_f32 v[42:43], v[42:43], v[122:123]
	v_pk_add_f32 v[44:45], v[44:45], v[124:125]
	v_pk_add_f32 v[46:47], v[46:47], v[126:127]
	v_pk_add_f32 v[48:49], v[48:49], v[128:129]
	v_pk_add_f32 v[50:51], v[50:51], v[130:131]
	s_waitcnt vmcnt(0)
	v_pk_add_f32 v[36:37], v[36:37], v[132:133]
	v_pk_add_f32 v[38:39], v[38:39], v[134:135]
	v_pk_add_f32 v[40:41], v[40:41], v[136:137]
	v_pk_add_f32 v[42:43], v[42:43], v[138:139]
	v_pk_add_f32 v[44:45], v[44:45], v[140:141]
	v_pk_add_f32 v[46:47], v[46:47], v[142:143]
	v_pk_add_f32 v[48:49], v[48:49], v[144:145]
	v_pk_add_f32 v[50:51], v[50:51], v[146:147]
	global_load_dwordx4 v[84:87], v19, s[14:15] offset:0
	global_load_dwordx4 v[88:91], v19, s[14:15] offset:1024
	global_load_dwordx4 v[92:95], v19, s[14:15] offset:2048
	global_load_dwordx4 v[96:99], v19, s[14:15] offset:3072
	s_add_u32 s14, s14, 0x200000
	s_addc_u32 s15, s15, 0
	global_load_dwordx4 v[100:103], v19, s[14:15] offset:0
	global_load_dwordx4 v[104:107], v19, s[14:15] offset:1024
	global_load_dwordx4 v[108:111], v19, s[14:15] offset:2048
	global_load_dwordx4 v[112:115], v19, s[14:15] offset:3072
	s_add_u32 s14, s14, 0x200000
	s_addc_u32 s15, s15, 0
	global_load_dwordx4 v[116:119], v19, s[14:15] offset:0
	global_load_dwordx4 v[120:123], v19, s[14:15] offset:1024
	global_load_dwordx4 v[124:127], v19, s[14:15] offset:2048
	global_load_dwordx4 v[128:131], v19, s[14:15] offset:3072
	s_add_u32 s14, s14, 0x200000
	s_addc_u32 s15, s15, 0
	global_load_dwordx4 v[132:135], v19, s[14:15] offset:0
	global_load_dwordx4 v[136:139], v19, s[14:15] offset:1024
	global_load_dwordx4 v[140:143], v19, s[14:15] offset:2048
	global_load_dwordx4 v[144:147], v19, s[14:15] offset:3072
	s_add_u32 s14, s14, 0x200000
	s_addc_u32 s15, s15, 0
	s_waitcnt vmcnt(12)
	v_pk_add_f32 v[36:37], v[36:37], v[84:85]
	v_pk_add_f32 v[38:39], v[38:39], v[86:87]
	v_pk_add_f32 v[40:41], v[40:41], v[88:89]
	v_pk_add_f32 v[42:43], v[42:43], v[90:91]
	v_pk_add_f32 v[44:45], v[44:45], v[92:93]
	v_pk_add_f32 v[46:47], v[46:47], v[94:95]
	v_pk_add_f32 v[48:49], v[48:49], v[96:97]
	v_pk_add_f32 v[50:51], v[50:51], v[98:99]
	s_waitcnt vmcnt(8)
	v_pk_add_f32 v[36:37], v[36:37], v[100:101]
	v_pk_add_f32 v[38:39], v[38:39], v[102:103]
	v_pk_add_f32 v[40:41], v[40:41], v[104:105]
	v_pk_add_f32 v[42:43], v[42:43], v[106:107]
	v_pk_add_f32 v[44:45], v[44:45], v[108:109]
	v_pk_add_f32 v[46:47], v[46:47], v[110:111]
	v_pk_add_f32 v[48:49], v[48:49], v[112:113]
	v_pk_add_f32 v[50:51], v[50:51], v[114:115]
	s_waitcnt vmcnt(4)
	v_pk_add_f32 v[36:37], v[36:37], v[116:117]
	v_pk_add_f32 v[38:39], v[38:39], v[118:119]
	v_pk_add_f32 v[40:41], v[40:41], v[120:121]
	v_pk_add_f32 v[42:43], v[42:43], v[122:123]
	v_pk_add_f32 v[44:45], v[44:45], v[124:125]
	v_pk_add_f32 v[46:47], v[46:47], v[126:127]
	v_pk_add_f32 v[48:49], v[48:49], v[128:129]
	v_pk_add_f32 v[50:51], v[50:51], v[130:131]
	s_waitcnt vmcnt(0)
	v_pk_add_f32 v[36:37], v[36:37], v[132:133]
	v_pk_add_f32 v[38:39], v[38:39], v[134:135]
	v_pk_add_f32 v[40:41], v[40:41], v[136:137]
	v_pk_add_f32 v[42:43], v[42:43], v[138:139]
	v_pk_add_f32 v[44:45], v[44:45], v[140:141]
	v_pk_add_f32 v[46:47], v[46:47], v[142:143]
	v_pk_add_f32 v[48:49], v[48:49], v[144:145]
	v_pk_add_f32 v[50:51], v[50:51], v[146:147]
	global_load_dwordx4 v[84:87], v19, s[14:15] offset:0
	global_load_dwordx4 v[88:91], v19, s[14:15] offset:1024
	global_load_dwordx4 v[92:95], v19, s[14:15] offset:2048
	global_load_dwordx4 v[96:99], v19, s[14:15] offset:3072
	s_add_u32 s14, s14, 0x200000
	s_addc_u32 s15, s15, 0
	global_load_dwordx4 v[100:103], v19, s[14:15] offset:0
	global_load_dwordx4 v[104:107], v19, s[14:15] offset:1024
	global_load_dwordx4 v[108:111], v19, s[14:15] offset:2048
	global_load_dwordx4 v[112:115], v19, s[14:15] offset:3072
	s_add_u32 s14, s14, 0x200000
	s_addc_u32 s15, s15, 0
	global_load_dwordx4 v[116:119], v19, s[14:15] offset:0
	global_load_dwordx4 v[120:123], v19, s[14:15] offset:1024
	global_load_dwordx4 v[124:127], v19, s[14:15] offset:2048
	global_load_dwordx4 v[128:131], v19, s[14:15] offset:3072
	s_add_u32 s14, s14, 0x200000
	s_addc_u32 s15, s15, 0
	s_waitcnt vmcnt(8)
	v_pk_add_f32 v[36:37], v[36:37], v[84:85]
	v_pk_add_f32 v[38:39], v[38:39], v[86:87]
	v_pk_add_f32 v[40:41], v[40:41], v[88:89]
	v_pk_add_f32 v[42:43], v[42:43], v[90:91]
	v_pk_add_f32 v[44:45], v[44:45], v[92:93]
	v_pk_add_f32 v[46:47], v[46:47], v[94:95]
	v_pk_add_f32 v[48:49], v[48:49], v[96:97]
	v_pk_add_f32 v[50:51], v[50:51], v[98:99]
	s_waitcnt vmcnt(4)
	v_pk_add_f32 v[36:37], v[36:37], v[100:101]
	v_pk_add_f32 v[38:39], v[38:39], v[102:103]
	v_pk_add_f32 v[40:41], v[40:41], v[104:105]
	v_pk_add_f32 v[42:43], v[42:43], v[106:107]
	v_pk_add_f32 v[44:45], v[44:45], v[108:109]
	v_pk_add_f32 v[46:47], v[46:47], v[110:111]
	v_pk_add_f32 v[48:49], v[48:49], v[112:113]
	v_pk_add_f32 v[50:51], v[50:51], v[114:115]
	s_waitcnt vmcnt(0)
	v_pk_add_f32 v[36:37], v[36:37], v[116:117]
	v_pk_add_f32 v[38:39], v[38:39], v[118:119]
	v_pk_add_f32 v[40:41], v[40:41], v[120:121]
	v_pk_add_f32 v[42:43], v[42:43], v[122:123]
	v_pk_add_f32 v[44:45], v[44:45], v[124:125]
	v_pk_add_f32 v[46:47], v[46:47], v[126:127]
	v_pk_add_f32 v[48:49], v[48:49], v[128:129]
	v_pk_add_f32 v[50:51], v[50:51], v[130:131]
	v_pk_mul_f32 v[70:71], v[36:37], v[36:37]
	v_pk_mul_f32 v[72:73], v[38:39], v[38:39]
	v_pk_fma_f32 v[70:71], v[40:41], v[40:41], v[70:71]
	v_pk_fma_f32 v[72:73], v[42:43], v[42:43], v[72:73]
	v_pk_fma_f32 v[70:71], v[44:45], v[44:45], v[70:71]
	v_pk_fma_f32 v[72:73], v[46:47], v[46:47], v[72:73]
	v_pk_fma_f32 v[70:71], v[48:49], v[48:49], v[70:71]
	v_pk_fma_f32 v[72:73], v[50:51], v[50:51], v[72:73]
	v_pk_add_f32 v[70:71], v[70:71], v[72:73]
	s_nop 0
	v_add_f32_e32 v70, v70, v71
	s_nop 1
	v_add_f32_dpp v70, v70, v70 quad_perm:[1,0,3,2] row_mask:0xf bank_mask:0xf bound_ctrl:1
	s_nop 1
	v_add_f32_dpp v70, v70, v70 quad_perm:[2,3,0,1] row_mask:0xf bank_mask:0xf bound_ctrl:1
	s_nop 1
	v_add_f32_dpp v70, v70, v70 row_half_mirror row_mask:0xf bank_mask:0xf bound_ctrl:1
	s_nop 1
	v_add_f32_dpp v70, v70, v70 row_mirror row_mask:0xf bank_mask:0xf bound_ctrl:1
	v_mov_b32_e32 v71, v70
	s_nop 1
	v_permlane16_swap_b32_e32 v70, v71
	v_add_f32_e32 v70, v70, v71
	v_mov_b32_e32 v71, v70
	s_nop 1
	v_permlane32_swap_b32_e32 v70, v71
	v_add_f32_e32 v70, v70, v71
	v_fmamk_f32 v70, v70, 0x3a800000, v69
	v_mul_f32_e32 v71, 0x4f800000, v70
	v_cmp_gt_f32_e32 vcc, s35, v70
	s_nop 1
	v_cndmask_b32_e32 v70, v70, v71, vcc
	v_sqrt_f32_e32 v71, v70
	s_nop 1
	v_add_u32_e32 v72, -1, v71
	v_add_u32_e32 v73, 1, v71
	v_fma_f32 v74, -v72, v71, v70
	v_fma_f32 v75, -v73, v71, v70
	v_cmp_ge_f32_e64 s[0:1], 0, v74
	s_nop 1
	v_cndmask_b32_e64 v71, v71, v72, s[0:1]
	v_cmp_lt_f32_e64 s[0:1], 0, v75
	s_nop 1
	v_cndmask_b32_e64 v71, v71, v73, s[0:1]
	v_mul_f32_e32 v72, 0x37800000, v71
	s_nop 0
	v_cndmask_b32_e32 v71, v71, v72, vcc
	v_cmp_class_f32_e32 vcc, v70, v80
	s_nop 1
	v_cndmask_b32_e32 v70, v71, v70, vcc
	v_div_scale_f32 v71, s[0:1], v70, v70, 0.5
	v_rcp_f32_e32 v72, v71
	v_div_scale_f32 v73, vcc, 0.5, v70, 0.5
	v_fma_f32 v74, -v71, v72, 1.0
	v_fmac_f32_e32 v72, v74, v72
	v_mul_f32_e32 v74, v73, v72
	v_fma_f32 v75, -v71, v74, v73
	v_fmac_f32_e32 v74, v75, v72
	v_fma_f32 v71, -v71, v74, v73
	v_div_fmas_f32 v71, v71, v72, v74
	v_div_fixup_f32 v76, v71, v70, 0.5
	v_pk_mul_f32 v[36:37], v[36:37], v[76:77] op_sel_hi:[1,0]
	v_pk_mul_f32 v[38:39], v[38:39], v[76:77] op_sel_hi:[1,0]
	v_pk_mul_f32 v[40:41], v[40:41], v[76:77] op_sel_hi:[1,0]
	v_pk_mul_f32 v[42:43], v[42:43], v[76:77] op_sel_hi:[1,0]
	v_pk_mul_f32 v[44:45], v[44:45], v[76:77] op_sel_hi:[1,0]
	v_pk_mul_f32 v[46:47], v[46:47], v[76:77] op_sel_hi:[1,0]
	v_pk_mul_f32 v[48:49], v[48:49], v[76:77] op_sel_hi:[1,0]
	v_pk_mul_f32 v[50:51], v[50:51], v[76:77] op_sel_hi:[1,0]
	v_lshlrev_b32_e32 v52, 16, v148
	v_and_b32_e32 v53, s34, v148
	v_lshlrev_b32_e32 v54, 16, v149
	v_and_b32_e32 v55, s34, v149
	v_lshlrev_b32_e32 v56, 16, v150
	v_and_b32_e32 v57, s34, v150
	v_lshlrev_b32_e32 v58, 16, v151
	v_and_b32_e32 v59, s34, v151
	v_lshlrev_b32_e32 v60, 16, v152
	v_and_b32_e32 v61, s34, v152
	v_lshlrev_b32_e32 v62, 16, v153
	v_and_b32_e32 v63, s34, v153
	v_lshlrev_b32_e32 v64, 16, v154
	v_and_b32_e32 v65, s34, v154
	v_lshlrev_b32_e32 v66, 16, v155
	v_and_b32_e32 v67, s34, v155
	v_pk_fma_f32 v[52:53], v[36:37], v[2:3], v[52:53]
	v_pk_fma_f32 v[54:55], v[38:39], v[4:5], v[54:55]
	v_pk_fma_f32 v[56:57], v[40:41], v[6:7], v[56:57]
	v_pk_fma_f32 v[58:59], v[42:43], v[8:9], v[58:59]
	v_pk_fma_f32 v[60:61], v[44:45], v[10:11], v[60:61]
	v_pk_fma_f32 v[62:63], v[46:47], v[12:13], v[62:63]
	v_pk_fma_f32 v[64:65], v[48:49], v[14:15], v[64:65]
	v_pk_fma_f32 v[66:67], v[50:51], v[16:17], v[66:67]
	global_store_dwordx4 v19, v[52:55], s[10:11] offset:0 nt
	global_store_dwordx4 v19, v[56:59], s[10:11] offset:1024 nt
	global_store_dwordx4 v19, v[60:63], s[10:11] offset:2048 nt
	global_store_dwordx4 v19, v[64:67], s[10:11] offset:3072 nt
.Lrw12_next:
	s_add_u32 s6, s6, s20
	s_addc_u32 s7, s7, 0
	s_add_u32 s8, s8, s20
	s_addc_u32 s9, s9, 0
	s_add_u32 s10, s10, s21
	s_addc_u32 s11, s11, 0
	s_add_i32 s5, s5, s23
	s_branch .Lrw12_single
.Lrw12_done:
.LBB0_1891:
	s_endpgm
